# v76 + W1/QKV epilogues: first 20 rstd loads issued at unit start (before the K-loop) instead of at epilogue start
# speedup vs baseline: 1.0007x; 1.0007x over previous
.LBB0_440:
	v_add_u32_e32 v226, s33, v160
	v_ashrrev_i32_e32 v227, 31, v226
	v_lshl_add_u64 v[228:229], v[226:227], 2, s[8:9]
	global_load_dword v232, v[228:229], off
	v_add_u32_e32 v226, s33, v160
	v_ashrrev_i32_e32 v227, 31, v226
	v_lshl_add_u64 v[228:229], v[226:227], 2, s[8:9]
	s_mov_b32 s98, 0x40000
	s_mov_b32 s99, 0
	v_lshl_add_u64 v[230:231], v[228:229], 0, s[98:99]
	global_load_dword v233, v[230:231], off
	v_add_u32_e32 v226, s33, v160
	v_ashrrev_i32_e32 v227, 31, v226
	v_lshl_add_u64 v[228:229], v[226:227], 2, s[8:9]
	s_mov_b32 s98, 0x80000
	s_mov_b32 s99, 0
	v_lshl_add_u64 v[230:231], v[228:229], 0, s[98:99]
	global_load_dword v234, v[230:231], off
	v_add_u32_e32 v226, s33, v160
	v_ashrrev_i32_e32 v227, 31, v226
	v_lshl_add_u64 v[228:229], v[226:227], 2, s[8:9]
	s_mov_b32 s98, 0xc0000
	s_mov_b32 s99, 0
	v_lshl_add_u64 v[230:231], v[228:229], 0, s[98:99]
	global_load_dword v235, v[230:231], off
	v_add_u32_e32 v226, s33, v160
	v_ashrrev_i32_e32 v227, 31, v226
	v_lshl_add_u64 v[228:229], v[226:227], 2, s[8:9]
	global_load_dword v236, v[228:229], off offset:64
	v_add_u32_e32 v226, s33, v160
	v_ashrrev_i32_e32 v227, 31, v226
	v_lshl_add_u64 v[228:229], v[226:227], 2, s[8:9]
	s_mov_b32 s98, 0x40000
	s_mov_b32 s99, 0
	v_lshl_add_u64 v[230:231], v[228:229], 0, s[98:99]
	global_load_dword v237, v[230:231], off offset:64
	v_add_u32_e32 v226, s33, v160
	v_ashrrev_i32_e32 v227, 31, v226
	v_lshl_add_u64 v[228:229], v[226:227], 2, s[8:9]
	s_mov_b32 s98, 0x80000
	s_mov_b32 s99, 0
	v_lshl_add_u64 v[230:231], v[228:229], 0, s[98:99]
	global_load_dword v238, v[230:231], off offset:64
	v_add_u32_e32 v226, s33, v160
	v_ashrrev_i32_e32 v227, 31, v226
	v_lshl_add_u64 v[228:229], v[226:227], 2, s[8:9]
	s_mov_b32 s98, 0xc0000
	s_mov_b32 s99, 0
	v_lshl_add_u64 v[230:231], v[228:229], 0, s[98:99]
	global_load_dword v239, v[230:231], off offset:64
	v_add_u32_e32 v226, s33, v160
	v_ashrrev_i32_e32 v227, 31, v226
	v_lshl_add_u64 v[228:229], v[226:227], 2, s[8:9]
	global_load_dword v240, v[228:229], off offset:128
	v_add_u32_e32 v226, s33, v160
	v_ashrrev_i32_e32 v227, 31, v226
	v_lshl_add_u64 v[228:229], v[226:227], 2, s[8:9]
	s_mov_b32 s98, 0x40000
	s_mov_b32 s99, 0
	v_lshl_add_u64 v[230:231], v[228:229], 0, s[98:99]
	global_load_dword v241, v[230:231], off offset:128
	v_add_u32_e32 v226, s33, v160
	v_ashrrev_i32_e32 v227, 31, v226
	v_lshl_add_u64 v[228:229], v[226:227], 2, s[8:9]
	s_mov_b32 s98, 0x80000
	s_mov_b32 s99, 0
	v_lshl_add_u64 v[230:231], v[228:229], 0, s[98:99]
	global_load_dword v242, v[230:231], off offset:128
	v_add_u32_e32 v226, s33, v160
	v_ashrrev_i32_e32 v227, 31, v226
	v_lshl_add_u64 v[228:229], v[226:227], 2, s[8:9]
	s_mov_b32 s98, 0xc0000
	s_mov_b32 s99, 0
	v_lshl_add_u64 v[230:231], v[228:229], 0, s[98:99]
	global_load_dword v243, v[230:231], off offset:128
	v_add_u32_e32 v226, s33, v160
	v_ashrrev_i32_e32 v227, 31, v226
	v_lshl_add_u64 v[228:229], v[226:227], 2, s[8:9]
	global_load_dword v244, v[228:229], off offset:192
	v_add_u32_e32 v226, s33, v160
	v_ashrrev_i32_e32 v227, 31, v226
	v_lshl_add_u64 v[228:229], v[226:227], 2, s[8:9]
	s_mov_b32 s98, 0x40000
	s_mov_b32 s99, 0
	v_lshl_add_u64 v[230:231], v[228:229], 0, s[98:99]
	global_load_dword v245, v[230:231], off offset:192
	v_add_u32_e32 v226, s33, v160
	v_ashrrev_i32_e32 v227, 31, v226
	v_lshl_add_u64 v[228:229], v[226:227], 2, s[8:9]
	s_mov_b32 s98, 0x80000
	s_mov_b32 s99, 0
	v_lshl_add_u64 v[230:231], v[228:229], 0, s[98:99]
	global_load_dword v246, v[230:231], off offset:192
	v_add_u32_e32 v226, s33, v160
	v_ashrrev_i32_e32 v227, 31, v226
	v_lshl_add_u64 v[228:229], v[226:227], 2, s[8:9]
	s_mov_b32 s98, 0xc0000
	s_mov_b32 s99, 0
	v_lshl_add_u64 v[230:231], v[228:229], 0, s[98:99]
	global_load_dword v247, v[230:231], off offset:192
	v_add_u32_e32 v226, s33, v160
	v_ashrrev_i32_e32 v227, 31, v226
	v_lshl_add_u64 v[228:229], v[226:227], 2, s[8:9]
	global_load_dword v248, v[228:229], off offset:512
	v_add_u32_e32 v226, s33, v160
	v_ashrrev_i32_e32 v227, 31, v226
	v_lshl_add_u64 v[228:229], v[226:227], 2, s[8:9]
	s_mov_b32 s98, 0x40000
	s_mov_b32 s99, 0
	v_lshl_add_u64 v[230:231], v[228:229], 0, s[98:99]
	global_load_dword v249, v[230:231], off offset:512
	v_add_u32_e32 v226, s33, v160
	v_ashrrev_i32_e32 v227, 31, v226
	v_lshl_add_u64 v[228:229], v[226:227], 2, s[8:9]
	s_mov_b32 s98, 0x80000
	s_mov_b32 s99, 0
	v_lshl_add_u64 v[230:231], v[228:229], 0, s[98:99]
	global_load_dword v250, v[230:231], off offset:512
	v_add_u32_e32 v226, s33, v160
	v_ashrrev_i32_e32 v227, 31, v226
	v_lshl_add_u64 v[228:229], v[226:227], 2, s[8:9]
	s_mov_b32 s98, 0xc0000
	s_mov_b32 s99, 0
	v_lshl_add_u64 v[230:231], v[228:229], 0, s[98:99]
	global_load_dword v251, v[230:231], off offset:512
	s_add_u32 s42, s42, 0x40080
	s_addc_u32 s43, s43, 0
	s_add_u32 s18, s44, 0x100
	v_mov_b32_e32 v0, 0
	s_addc_u32 s19, s45, 0
	s_mov_b32 s60, -2
	v_mov_b32_e32 v1, v0
	v_mov_b32_e32 v2, v0
	v_mov_b32_e32 v3, v0
	v_mov_b32_e32 v4, v0
	v_mov_b32_e32 v5, v0
	v_mov_b32_e32 v6, v0
	v_mov_b32_e32 v7, v0
	v_mov_b32_e32 v16, v0
	v_mov_b32_e32 v17, v0
	v_mov_b32_e32 v18, v0
	v_mov_b32_e32 v19, v0
	v_mov_b32_e32 v20, v0
	v_mov_b32_e32 v21, v0
	v_mov_b32_e32 v22, v0
	v_mov_b32_e32 v23, v0
	v_mov_b32_e32 v32, v0
	v_mov_b32_e32 v33, v0
	v_mov_b32_e32 v34, v0
	v_mov_b32_e32 v35, v0
	v_mov_b32_e32 v36, v0
	v_mov_b32_e32 v37, v0
	v_mov_b32_e32 v38, v0
	v_mov_b32_e32 v39, v0
	v_mov_b32_e32 v48, v0
	v_mov_b32_e32 v49, v0
	v_mov_b32_e32 v50, v0
	v_mov_b32_e32 v51, v0
	v_mov_b32_e32 v52, v0
	v_mov_b32_e32 v53, v0
	v_mov_b32_e32 v54, v0
	v_mov_b32_e32 v55, v0
	v_mov_b32_e32 v8, v0
	v_mov_b32_e32 v9, v0
	v_mov_b32_e32 v10, v0
	v_mov_b32_e32 v11, v0
	v_mov_b32_e32 v12, v0
	v_mov_b32_e32 v13, v0
	v_mov_b32_e32 v14, v0
	v_mov_b32_e32 v15, v0
	v_mov_b32_e32 v24, v0
	v_mov_b32_e32 v25, v0
	v_mov_b32_e32 v26, v0
	v_mov_b32_e32 v27, v0
	v_mov_b32_e32 v28, v0
	v_mov_b32_e32 v29, v0
	v_mov_b32_e32 v30, v0
	v_mov_b32_e32 v31, v0
	v_mov_b32_e32 v40, v0
	v_mov_b32_e32 v41, v0
	v_mov_b32_e32 v42, v0
	v_mov_b32_e32 v43, v0
	v_mov_b32_e32 v44, v0
	v_mov_b32_e32 v45, v0
	v_mov_b32_e32 v46, v0
	v_mov_b32_e32 v47, v0
	v_mov_b32_e32 v56, v0
	v_mov_b32_e32 v57, v0
	v_mov_b32_e32 v58, v0
	v_mov_b32_e32 v59, v0
	v_mov_b32_e32 v60, v0
	v_mov_b32_e32 v61, v0
	v_mov_b32_e32 v62, v0
	v_mov_b32_e32 v63, v0
	v_mov_b32_e32 v64, v0
	v_mov_b32_e32 v65, v0
	v_mov_b32_e32 v66, v0
	v_mov_b32_e32 v67, v0
	v_mov_b32_e32 v68, v0
	v_mov_b32_e32 v69, v0
	v_mov_b32_e32 v70, v0
	v_mov_b32_e32 v71, v0
	v_mov_b32_e32 v80, v0
	v_mov_b32_e32 v81, v0
	v_mov_b32_e32 v82, v0
	v_mov_b32_e32 v83, v0
	v_mov_b32_e32 v84, v0
	v_mov_b32_e32 v85, v0
	v_mov_b32_e32 v86, v0
	v_mov_b32_e32 v87, v0
	v_mov_b32_e32 v96, v0
	v_mov_b32_e32 v97, v0
	v_mov_b32_e32 v98, v0
	v_mov_b32_e32 v99, v0
	v_mov_b32_e32 v100, v0
	v_mov_b32_e32 v101, v0
	v_mov_b32_e32 v102, v0
	v_mov_b32_e32 v103, v0
	v_mov_b32_e32 v112, v0
	v_mov_b32_e32 v113, v0
	v_mov_b32_e32 v114, v0
	v_mov_b32_e32 v115, v0
	v_mov_b32_e32 v116, v0
	v_mov_b32_e32 v117, v0
	v_mov_b32_e32 v118, v0
	v_mov_b32_e32 v119, v0
	v_mov_b32_e32 v72, v0
	v_mov_b32_e32 v73, v0
	v_mov_b32_e32 v74, v0
	v_mov_b32_e32 v75, v0
	v_mov_b32_e32 v76, v0
	v_mov_b32_e32 v77, v0
	v_mov_b32_e32 v78, v0
	v_mov_b32_e32 v79, v0
	v_mov_b32_e32 v88, v0
	v_mov_b32_e32 v89, v0
	v_mov_b32_e32 v90, v0
	v_mov_b32_e32 v91, v0
	v_mov_b32_e32 v92, v0
	v_mov_b32_e32 v93, v0
	v_mov_b32_e32 v94, v0
	v_mov_b32_e32 v95, v0
	v_mov_b32_e32 v104, v0
	v_mov_b32_e32 v105, v0
	v_mov_b32_e32 v106, v0
	v_mov_b32_e32 v107, v0
	v_mov_b32_e32 v108, v0
	v_mov_b32_e32 v109, v0
	v_mov_b32_e32 v110, v0
	v_mov_b32_e32 v111, v0
	v_mov_b32_e32 v120, v0
	v_mov_b32_e32 v121, v0
	v_mov_b32_e32 v122, v0
	v_mov_b32_e32 v123, v0
	v_mov_b32_e32 v124, v0
	v_mov_b32_e32 v125, v0
	v_mov_b32_e32 v126, v0
	v_mov_b32_e32 v127, v0
.LBB0_441:
	s_add_u32 s22, s42, 0xfffc0080
	s_addc_u32 s23, s43, -1
	s_add_i32 s79, 0, 0x10000
	v_add_u32_e32 v156, s79, v161
	ds_read_b128 v[144:147], v156
	ds_read_b128 v[148:151], v156 offset:1024
	ds_read_b128 v[152:155], v156 offset:2048
	ds_read_b128 v[164:167], v156 offset:3072
	s_cmp_eq_u32 s60, 12
	s_cselect_b32 s47, s5, s23
	s_cselect_b32 s46, s4, s22
	s_cselect_b32 s45, s7, s19
	s_cselect_b32 s44, s6, s18
	v_lshl_add_u64 v[156:157], s[42:43], 0, v[140:141]
	s_add_i32 m0, s52, 0xc000
	ds_read_b128 v[168:171], v163
	ds_read_b128 v[172:175], v163 offset:1024
	ds_read_b128 v[176:179], v163 offset:2048
	ds_read_b128 v[180:183], v163 offset:3072
	ds_read_b128 v[184:187], v163 offset:4096
	ds_read_b128 v[188:191], v163 offset:5120
	ds_read_b128 v[192:195], v163 offset:6144
	ds_read_b128 v[200:203], v163 offset:7168
	global_load_lds_dwordx4 v[156:157], off
	v_lshl_add_u64 v[156:157], s[42:43], 0, v[142:143]
	s_add_i32 m0, s52, 0xe000
	s_nop 0
	global_load_lds_dwordx4 v[156:157], off
	s_waitcnt lgkmcnt(8)
	s_barrier
	s_waitcnt lgkmcnt(0)
	s_setprio 1
	s_waitcnt lgkmcnt(0)
	v_mfma_f32_16x16x32_bf16 v[124:127], v[144:147], v[168:171], v[124:127]
	v_mfma_f32_16x16x32_bf16 v[120:123], v[152:155], v[168:171], v[120:123]
	v_mfma_f32_16x16x32_bf16 v[108:111], v[144:147], v[176:179], v[108:111]
	v_mfma_f32_16x16x32_bf16 v[104:107], v[152:155], v[176:179], v[104:107]
	v_mfma_f32_16x16x32_bf16 v[92:95], v[144:147], v[184:187], v[92:95]
	v_mfma_f32_16x16x32_bf16 v[88:91], v[152:155], v[184:187], v[88:91]
	v_mfma_f32_16x16x32_bf16 v[76:79], v[144:147], v[192:195], v[76:79]
	v_mfma_f32_16x16x32_bf16 v[72:75], v[152:155], v[192:195], v[72:75]
	v_mfma_f32_16x16x32_bf16 v[124:127], v[148:151], v[172:175], v[124:127]
	v_mfma_f32_16x16x32_bf16 v[120:123], v[164:167], v[172:175], v[120:123]
	v_mfma_f32_16x16x32_bf16 v[108:111], v[148:151], v[180:183], v[108:111]
	v_mfma_f32_16x16x32_bf16 v[104:107], v[164:167], v[180:183], v[104:107]
	v_mfma_f32_16x16x32_bf16 v[92:95], v[148:151], v[188:191], v[92:95]
	v_mfma_f32_16x16x32_bf16 v[88:91], v[164:167], v[188:191], v[88:91]
	v_mfma_f32_16x16x32_bf16 v[76:79], v[148:151], v[200:203], v[76:79]
	v_mfma_f32_16x16x32_bf16 v[72:75], v[164:167], v[200:203], v[72:75]
	s_setprio 0
	s_barrier
	s_add_i32 s80, 0, 0x14000
	v_add_u32_e32 v156, s80, v161
	s_add_i32 s22, s79, s51
	ds_read_b128 v[204:207], v156
	ds_read_b128 v[208:211], v156 offset:1024
	ds_read_b128 v[212:215], v156 offset:2048
	ds_read_b128 v[216:219], v156 offset:3072
	v_lshl_add_u64 v[156:157], s[44:45], 0, v[128:129]
	s_mov_b32 m0, s22
	v_lshl_add_u64 v[220:221], s[44:45], 0, v[134:135]
	global_load_lds_dwordx4 v[156:157], off
	s_add_i32 m0, s22, 0x2000
	s_nop 0
	global_load_lds_dwordx4 v[220:221], off
	s_barrier
	s_waitcnt lgkmcnt(0)
	s_setprio 1
	s_waitcnt lgkmcnt(0)
	v_mfma_f32_16x16x32_bf16 v[116:119], v[204:207], v[168:171], v[116:119]
	v_mfma_f32_16x16x32_bf16 v[112:115], v[212:215], v[168:171], v[112:115]
	v_mfma_f32_16x16x32_bf16 v[100:103], v[204:207], v[176:179], v[100:103]
	v_mfma_f32_16x16x32_bf16 v[96:99], v[212:215], v[176:179], v[96:99]
	v_mfma_f32_16x16x32_bf16 v[84:87], v[204:207], v[184:187], v[84:87]
	v_mfma_f32_16x16x32_bf16 v[80:83], v[212:215], v[184:187], v[80:83]
	v_mfma_f32_16x16x32_bf16 v[68:71], v[204:207], v[192:195], v[68:71]
	v_mfma_f32_16x16x32_bf16 v[64:67], v[212:215], v[192:195], v[64:67]
	v_mfma_f32_16x16x32_bf16 v[116:119], v[208:211], v[172:175], v[116:119]
	v_mfma_f32_16x16x32_bf16 v[112:115], v[216:219], v[172:175], v[112:115]
	v_mfma_f32_16x16x32_bf16 v[100:103], v[208:211], v[180:183], v[100:103]
	v_mfma_f32_16x16x32_bf16 v[96:99], v[216:219], v[180:183], v[96:99]
	v_mfma_f32_16x16x32_bf16 v[84:87], v[208:211], v[188:191], v[84:87]
	v_mfma_f32_16x16x32_bf16 v[80:83], v[216:219], v[188:191], v[80:83]
	v_mfma_f32_16x16x32_bf16 v[68:71], v[208:211], v[200:203], v[68:71]
	v_mfma_f32_16x16x32_bf16 v[64:67], v[216:219], v[200:203], v[64:67]
	s_setprio 0
	s_mov_b32 m0, s52
	v_lshl_add_u64 v[222:223], s[46:47], 0, v[138:139]
	s_barrier
	ds_read_b128 v[168:171], v163 offset:16384
	ds_read_b128 v[172:175], v163 offset:17408
	ds_read_b128 v[176:179], v163 offset:18432
	ds_read_b128 v[180:183], v163 offset:19456
	ds_read_b128 v[184:187], v163 offset:20480
	ds_read_b128 v[188:191], v163 offset:21504
	ds_read_b128 v[192:195], v163 offset:22528
	ds_read_b128 v[200:203], v163 offset:23552
	global_load_lds_dwordx4 v[222:223], off
	v_lshl_add_u64 v[224:225], s[46:47], 0, v[136:137]
	s_mov_b32 m0, s53
	s_nop 0
	global_load_lds_dwordx4 v[224:225], off
	s_barrier
	s_waitcnt lgkmcnt(0)
	s_setprio 1
	s_waitcnt lgkmcnt(0)
	v_mfma_f32_16x16x32_bf16 v[60:63], v[144:147], v[168:171], v[60:63]
	v_mfma_f32_16x16x32_bf16 v[56:59], v[152:155], v[168:171], v[56:59]
	v_mfma_f32_16x16x32_bf16 v[44:47], v[144:147], v[176:179], v[44:47]
	v_mfma_f32_16x16x32_bf16 v[40:43], v[152:155], v[176:179], v[40:43]
	v_mfma_f32_16x16x32_bf16 v[28:31], v[144:147], v[184:187], v[28:31]
	v_mfma_f32_16x16x32_bf16 v[24:27], v[152:155], v[184:187], v[24:27]
	v_mfma_f32_16x16x32_bf16 v[12:15], v[144:147], v[192:195], v[12:15]
	v_mfma_f32_16x16x32_bf16 v[8:11], v[152:155], v[192:195], v[8:11]
	v_mfma_f32_16x16x32_bf16 v[60:63], v[148:151], v[172:175], v[60:63]
	v_mfma_f32_16x16x32_bf16 v[56:59], v[164:167], v[172:175], v[56:59]
	v_mfma_f32_16x16x32_bf16 v[44:47], v[148:151], v[180:183], v[44:47]
	v_mfma_f32_16x16x32_bf16 v[40:43], v[164:167], v[180:183], v[40:43]
	v_mfma_f32_16x16x32_bf16 v[28:31], v[148:151], v[188:191], v[28:31]
	v_mfma_f32_16x16x32_bf16 v[24:27], v[164:167], v[188:191], v[24:27]
	v_mfma_f32_16x16x32_bf16 v[12:15], v[148:151], v[200:203], v[12:15]
	v_mfma_f32_16x16x32_bf16 v[8:11], v[164:167], v[200:203], v[8:11]
	s_setprio 0
	s_barrier
	s_add_u32 s22, s44, 0x40000
	s_addc_u32 s23, s45, 0
	s_add_i32 s79, s80, s51
	v_lshl_add_u64 v[144:145], s[22:23], 0, v[128:129]
	s_mov_b32 m0, s79
	s_nop 0
	global_load_lds_dwordx4 v[144:145], off
	v_lshl_add_u64 v[144:145], s[22:23], 0, v[134:135]
	s_add_i32 m0, s79, 0x2000
	s_nop 0
	global_load_lds_dwordx4 v[144:145], off
	s_waitcnt vmcnt(6)
	s_barrier
	s_setprio 1
	v_mfma_f32_16x16x32_bf16 v[52:55], v[204:207], v[168:171], v[52:55]
	v_mfma_f32_16x16x32_bf16 v[48:51], v[212:215], v[168:171], v[48:51]
	v_mfma_f32_16x16x32_bf16 v[36:39], v[204:207], v[176:179], v[36:39]
	v_mfma_f32_16x16x32_bf16 v[32:35], v[212:215], v[176:179], v[32:35]
	v_mfma_f32_16x16x32_bf16 v[20:23], v[204:207], v[184:187], v[20:23]
	v_mfma_f32_16x16x32_bf16 v[16:19], v[212:215], v[184:187], v[16:19]
	v_mfma_f32_16x16x32_bf16 v[4:7], v[204:207], v[192:195], v[4:7]
	v_mfma_f32_16x16x32_bf16 v[0:3], v[212:215], v[192:195], v[0:3]
	v_mfma_f32_16x16x32_bf16 v[52:55], v[208:211], v[172:175], v[52:55]
	v_mfma_f32_16x16x32_bf16 v[48:51], v[216:219], v[172:175], v[48:51]
	v_mfma_f32_16x16x32_bf16 v[36:39], v[208:211], v[180:183], v[36:39]
	v_mfma_f32_16x16x32_bf16 v[32:35], v[216:219], v[180:183], v[32:35]
	v_mfma_f32_16x16x32_bf16 v[20:23], v[208:211], v[188:191], v[20:23]
	v_mfma_f32_16x16x32_bf16 v[16:19], v[216:219], v[188:191], v[16:19]
	v_mfma_f32_16x16x32_bf16 v[4:7], v[208:211], v[200:203], v[4:7]
	v_mfma_f32_16x16x32_bf16 v[0:3], v[216:219], v[200:203], v[0:3]
	s_setprio 0
	s_add_i32 s79, 0, 0x18000
	v_add_u32_e32 v164, s79, v161
	s_barrier
	ds_read_b128 v[144:147], v164
	ds_read_b128 v[148:151], v164 offset:1024
	ds_read_b128 v[152:155], v164 offset:2048
	ds_read_b128 v[164:167], v164 offset:3072
	s_add_u32 s22, s46, 0x40000
	s_addc_u32 s23, s47, 0
	s_mov_b32 m0, s70
	v_lshl_add_u64 v[204:205], s[22:23], 0, v[138:139]
	ds_read_b128 v[168:171], v163 offset:32768
	ds_read_b128 v[172:175], v163 offset:33792
	ds_read_b128 v[176:179], v163 offset:34816
	ds_read_b128 v[180:183], v163 offset:35840
	ds_read_b128 v[184:187], v163 offset:36864
	ds_read_b128 v[188:191], v163 offset:37888
	ds_read_b128 v[192:195], v163 offset:38912
	ds_read_b128 v[200:203], v163 offset:39936
	global_load_lds_dwordx4 v[204:205], off
	v_lshl_add_u64 v[204:205], s[22:23], 0, v[136:137]
	s_mov_b32 m0, s71
	s_nop 0
	global_load_lds_dwordx4 v[204:205], off
	s_waitcnt lgkmcnt(8)
	s_barrier
	s_waitcnt lgkmcnt(0)
	s_setprio 1
	s_waitcnt lgkmcnt(0)
	v_mfma_f32_16x16x32_bf16 v[124:127], v[144:147], v[168:171], v[124:127]
	v_mfma_f32_16x16x32_bf16 v[120:123], v[152:155], v[168:171], v[120:123]
	v_mfma_f32_16x16x32_bf16 v[108:111], v[144:147], v[176:179], v[108:111]
	v_mfma_f32_16x16x32_bf16 v[104:107], v[152:155], v[176:179], v[104:107]
	v_mfma_f32_16x16x32_bf16 v[92:95], v[144:147], v[184:187], v[92:95]
	v_mfma_f32_16x16x32_bf16 v[88:91], v[152:155], v[184:187], v[88:91]
	v_mfma_f32_16x16x32_bf16 v[76:79], v[144:147], v[192:195], v[76:79]
	v_mfma_f32_16x16x32_bf16 v[72:75], v[152:155], v[192:195], v[72:75]
	v_mfma_f32_16x16x32_bf16 v[124:127], v[148:151], v[172:175], v[124:127]
	v_mfma_f32_16x16x32_bf16 v[120:123], v[164:167], v[172:175], v[120:123]
	v_mfma_f32_16x16x32_bf16 v[108:111], v[148:151], v[180:183], v[108:111]
	v_mfma_f32_16x16x32_bf16 v[104:107], v[164:167], v[180:183], v[104:107]
	v_mfma_f32_16x16x32_bf16 v[92:95], v[148:151], v[188:191], v[92:95]
	v_mfma_f32_16x16x32_bf16 v[88:91], v[164:167], v[188:191], v[88:91]
	v_mfma_f32_16x16x32_bf16 v[76:79], v[148:151], v[200:203], v[76:79]
	v_mfma_f32_16x16x32_bf16 v[72:75], v[164:167], v[200:203], v[72:75]
	s_setprio 0
	s_barrier
	s_add_i32 s46, 0, 0x1c000
	s_add_i32 s22, s79, s51
	v_add_u32_e32 v216, s46, v161
	v_lshl_add_u64 v[156:157], v[156:157], 0, s[40:41]
	s_mov_b32 m0, s22
	ds_read_b128 v[204:207], v216
	ds_read_b128 v[208:211], v216 offset:1024
	ds_read_b128 v[212:215], v216 offset:2048
	ds_read_b128 v[216:219], v216 offset:3072
	global_load_lds_dwordx4 v[156:157], off
	v_lshl_add_u64 v[156:157], v[220:221], 0, s[40:41]
	s_add_i32 m0, s22, 0x2000
	s_nop 0
	global_load_lds_dwordx4 v[156:157], off
	s_barrier
	s_waitcnt lgkmcnt(0)
	s_setprio 1
	s_waitcnt lgkmcnt(0)
	v_mfma_f32_16x16x32_bf16 v[116:119], v[204:207], v[168:171], v[116:119]
	v_mfma_f32_16x16x32_bf16 v[112:115], v[212:215], v[168:171], v[112:115]
	v_mfma_f32_16x16x32_bf16 v[100:103], v[204:207], v[176:179], v[100:103]
	v_mfma_f32_16x16x32_bf16 v[96:99], v[212:215], v[176:179], v[96:99]
	v_mfma_f32_16x16x32_bf16 v[84:87], v[204:207], v[184:187], v[84:87]
	v_mfma_f32_16x16x32_bf16 v[80:83], v[212:215], v[184:187], v[80:83]
	v_mfma_f32_16x16x32_bf16 v[68:71], v[204:207], v[192:195], v[68:71]
	v_mfma_f32_16x16x32_bf16 v[64:67], v[212:215], v[192:195], v[64:67]
	v_mfma_f32_16x16x32_bf16 v[116:119], v[208:211], v[172:175], v[116:119]
	v_mfma_f32_16x16x32_bf16 v[112:115], v[216:219], v[172:175], v[112:115]
	v_mfma_f32_16x16x32_bf16 v[100:103], v[208:211], v[180:183], v[100:103]
	v_mfma_f32_16x16x32_bf16 v[96:99], v[216:219], v[180:183], v[96:99]
	v_mfma_f32_16x16x32_bf16 v[84:87], v[208:211], v[188:191], v[84:87]
	v_mfma_f32_16x16x32_bf16 v[80:83], v[216:219], v[188:191], v[80:83]
	v_mfma_f32_16x16x32_bf16 v[68:71], v[208:211], v[200:203], v[68:71]
	v_mfma_f32_16x16x32_bf16 v[64:67], v[216:219], v[200:203], v[64:67]
	s_setprio 0
	s_mov_b32 m0, s72
	v_lshl_add_u64 v[156:157], v[222:223], 0, s[40:41]
	s_barrier
	ds_read_b128 v[168:171], v163 offset:49152
	ds_read_b128 v[172:175], v163 offset:50176
	ds_read_b128 v[176:179], v163 offset:51200
	ds_read_b128 v[180:183], v163 offset:52224
	ds_read_b128 v[184:187], v163 offset:53248
	ds_read_b128 v[188:191], v163 offset:54272
	ds_read_b128 v[192:195], v163 offset:55296
	ds_read_b128 v[200:203], v163 offset:56320
	global_load_lds_dwordx4 v[156:157], off
	v_lshl_add_u64 v[156:157], v[224:225], 0, s[40:41]
	s_mov_b32 m0, s73
	s_nop 0
	global_load_lds_dwordx4 v[156:157], off
	s_barrier
	s_waitcnt lgkmcnt(0)
	s_setprio 1
	s_waitcnt lgkmcnt(0)
	v_mfma_f32_16x16x32_bf16 v[60:63], v[144:147], v[168:171], v[60:63]
	v_mfma_f32_16x16x32_bf16 v[56:59], v[152:155], v[168:171], v[56:59]
	v_mfma_f32_16x16x32_bf16 v[44:47], v[144:147], v[176:179], v[44:47]
	v_mfma_f32_16x16x32_bf16 v[40:43], v[152:155], v[176:179], v[40:43]
	v_mfma_f32_16x16x32_bf16 v[28:31], v[144:147], v[184:187], v[28:31]
	v_mfma_f32_16x16x32_bf16 v[24:27], v[152:155], v[184:187], v[24:27]
	v_mfma_f32_16x16x32_bf16 v[12:15], v[144:147], v[192:195], v[12:15]
	v_mfma_f32_16x16x32_bf16 v[8:11], v[152:155], v[192:195], v[8:11]
	v_mfma_f32_16x16x32_bf16 v[60:63], v[148:151], v[172:175], v[60:63]
	v_mfma_f32_16x16x32_bf16 v[56:59], v[164:167], v[172:175], v[56:59]
	v_mfma_f32_16x16x32_bf16 v[44:47], v[148:151], v[180:183], v[44:47]
	v_mfma_f32_16x16x32_bf16 v[40:43], v[164:167], v[180:183], v[40:43]
	v_mfma_f32_16x16x32_bf16 v[28:31], v[148:151], v[188:191], v[28:31]
	v_mfma_f32_16x16x32_bf16 v[24:27], v[164:167], v[188:191], v[24:27]
	v_mfma_f32_16x16x32_bf16 v[12:15], v[148:151], v[200:203], v[12:15]
	v_mfma_f32_16x16x32_bf16 v[8:11], v[164:167], v[200:203], v[8:11]
	s_setprio 0
	s_barrier
	s_add_u32 s22, s44, 0x40080
	s_addc_u32 s23, s45, 0
	s_add_i32 s44, s46, s51
	v_lshl_add_u64 v[144:145], s[22:23], 0, v[128:129]
	s_mov_b32 m0, s44
	s_nop 0
	global_load_lds_dwordx4 v[144:145], off
	v_lshl_add_u64 v[144:145], s[22:23], 0, v[134:135]
	s_add_i32 m0, s44, 0x2000
	s_nop 0
	global_load_lds_dwordx4 v[144:145], off
	s_waitcnt vmcnt(6)
	s_barrier
	s_setprio 1
	v_mfma_f32_16x16x32_bf16 v[52:55], v[204:207], v[168:171], v[52:55]
	v_mfma_f32_16x16x32_bf16 v[48:51], v[212:215], v[168:171], v[48:51]
	v_mfma_f32_16x16x32_bf16 v[36:39], v[204:207], v[176:179], v[36:39]
	v_mfma_f32_16x16x32_bf16 v[32:35], v[212:215], v[176:179], v[32:35]
	v_mfma_f32_16x16x32_bf16 v[20:23], v[204:207], v[184:187], v[20:23]
	v_mfma_f32_16x16x32_bf16 v[16:19], v[212:215], v[184:187], v[16:19]
	v_mfma_f32_16x16x32_bf16 v[4:7], v[204:207], v[192:195], v[4:7]
	v_mfma_f32_16x16x32_bf16 v[0:3], v[212:215], v[192:195], v[0:3]
	v_mfma_f32_16x16x32_bf16 v[52:55], v[208:211], v[172:175], v[52:55]
	v_mfma_f32_16x16x32_bf16 v[48:51], v[216:219], v[172:175], v[48:51]
	v_mfma_f32_16x16x32_bf16 v[36:39], v[208:211], v[180:183], v[36:39]
	v_mfma_f32_16x16x32_bf16 v[32:35], v[216:219], v[180:183], v[32:35]
	v_mfma_f32_16x16x32_bf16 v[20:23], v[208:211], v[188:191], v[20:23]
	v_mfma_f32_16x16x32_bf16 v[16:19], v[216:219], v[188:191], v[16:19]
	v_mfma_f32_16x16x32_bf16 v[4:7], v[208:211], v[200:203], v[4:7]
	v_mfma_f32_16x16x32_bf16 v[0:3], v[216:219], v[200:203], v[0:3]
	s_setprio 0
	s_add_i32 s60, s60, 2
	s_add_u32 s42, s42, 0x100
	s_addc_u32 s43, s43, 0
	s_add_u32 s18, s18, 0x100
	s_addc_u32 s19, s19, 0
	s_cmp_gt_u32 s60, 13
	s_barrier
	s_cbranch_scc0 .LBB0_441
	v_add_u32_e32 v152, s33, v160
	v_ashrrev_i32_e32 v153, 31, v152
	v_lshl_add_u64 v[144:145], v[152:153], 2, s[8:9]
	v_add_co_u32_e32 v146, vcc, 0x40000, v144
	s_nop 1
	v_mov_b32_e32 v156, v232
	s_nop 0
	v_addc_co_u32_e32 v147, vcc, 0, v145, vcc
	v_add_co_u32_e32 v148, vcc, 0x80000, v144
	v_mov_b32_e32 v164, v233
	s_nop 0
	v_addc_co_u32_e32 v149, vcc, 0, v145, vcc
	v_add_co_u32_e32 v150, vcc, 0xc0000, v144
	v_mov_b32_e32 v157, v234
	s_nop 0
	v_addc_co_u32_e32 v151, vcc, 0, v145, vcc
	v_mov_b32_e32 v165, v235
	global_load_dword v166, v[144:145], off offset:576
	global_load_dword v167, v[146:147], off offset:576
	global_load_dword v168, v[148:149], off offset:576
	global_load_dword v169, v[150:151], off offset:576
	global_load_dword v170, v[144:145], off offset:640
	global_load_dword v171, v[146:147], off offset:640
	global_load_dword v172, v[148:149], off offset:640
	global_load_dword v173, v[150:151], off offset:640
	global_load_dword v174, v[144:145], off offset:704
	global_load_dword v175, v[146:147], off offset:704
	global_load_dword v176, v[148:149], off offset:704
	global_load_dword v177, v[150:151], off offset:704
	v_subrev_u32_e32 v152, s74, v152
	v_add_u32_e32 v154, s78, v162
	v_ashrrev_i32_e32 v155, 31, v154
	v_lshlrev_b64 v[154:155], 1, v[154:155]
	s_mov_b32 s78, s76
	s_mov_b32 s33, s77
	s_mov_b64 s[44:45], s[6:7]
	s_mov_b64 s[42:43], s[4:5]
	s_nop 0
	v_pk_add_f32 v[156:157], v[156:157], v[164:165]
	s_nop 0
	v_add_f32_e32 v153, v156, v157
	v_fmamk_f32 v153, v153, 0x3a800000, v158
	v_cmp_gt_f32_e32 vcc, s67, v153
	v_mul_f32_e32 v156, 0x4b800000, v153
	s_nop 0
	v_cndmask_b32_e32 v153, v153, v156, vcc
	v_rsq_f32_e32 v153, v153
	s_nop 0
	v_mul_f32_e32 v156, 0x45800000, v153
	v_cndmask_b32_e32 v164, v153, v156, vcc
	v_pk_mul_f32 v[120:121], v[120:121], v[164:165] op_sel_hi:[1,0]
	v_ashrrev_i32_e32 v153, 31, v152
	v_pk_mul_f32 v[124:125], v[124:125], v[164:165] op_sel_hi:[1,0]
	v_pk_mul_f32 v[122:123], v[122:123], v[164:165] op_sel_hi:[1,0]
	v_max_f32_e32 v120, 0, v120
	v_lshlrev_b64 v[156:157], 13, v[152:153]
	v_pk_mul_f32 v[126:127], v[126:127], v[164:165] op_sel_hi:[1,0]
	v_mul_f32_e32 v153, v120, v120
	v_max_f32_e32 v120, 0, v125
	v_max_f32_e32 v121, 0, v121
	v_max_f32_e32 v122, 0, v122
	v_lshl_add_u64 v[156:157], s[92:93], 0, v[156:157]
	v_max_f32_e32 v124, 0, v124
	v_mul_f32_e32 v120, v120, v120
	v_mul_f32_e32 v125, v121, v121
	v_max_f32_e32 v121, 0, v126
	v_mul_f32_e32 v126, v122, v122
	v_max_f32_e32 v122, 0, v127
	v_max_f32_e32 v123, 0, v123
	v_pk_mul_f32 v[114:115], v[114:115], v[164:165] op_sel_hi:[1,0]
	v_pk_mul_f32 v[112:113], v[112:113], v[164:165] op_sel_hi:[1,0]
	v_lshl_add_u64 v[156:157], v[156:157], 0, v[154:155]
	v_mul_f32_e32 v124, v124, v124
	v_mul_f32_e32 v121, v121, v121
	v_mul_f32_e32 v122, v122, v122
	v_mul_f32_e32 v123, v123, v123
	v_cvt_pk_bf16_f32 v120, v124, v120
	v_pk_mul_f32 v[118:119], v[118:119], v[164:165] op_sel_hi:[1,0]
	v_pk_mul_f32 v[116:117], v[116:117], v[164:165] op_sel_hi:[1,0]
	v_max_f32_e32 v112, 0, v112
	v_max_f32_e32 v113, 0, v113
	v_max_f32_e32 v114, 0, v114
	v_cvt_pk_bf16_f32 v121, v121, v122
	v_cvt_pk_bf16_f32 v122, v153, v125
	v_cvt_pk_bf16_f32 v123, v126, v123
	global_store_dwordx4 v[156:157], v[120:123], off
	v_max_f32_e32 v115, 0, v115
	v_max_f32_e32 v116, 0, v116
	v_mul_f32_e32 v120, v112, v112
	v_max_f32_e32 v112, 0, v117
	v_mul_f32_e32 v117, v113, v113
	v_max_f32_e32 v113, 0, v118
	v_mul_f32_e32 v118, v114, v114
	v_max_f32_e32 v114, 0, v119
	v_mul_f32_e32 v112, v112, v112
	v_mul_f32_e32 v113, v113, v113
	v_mul_f32_e32 v114, v114, v114
	v_mul_f32_e32 v115, v115, v115
	v_mul_f32_e32 v116, v116, v116
	v_cvt_pk_bf16_f32 v112, v116, v112
	v_cvt_pk_bf16_f32 v113, v113, v114
	v_cvt_pk_bf16_f32 v114, v120, v117
	v_cvt_pk_bf16_f32 v115, v118, v115
	global_store_dwordx4 v[156:157], v[112:115], off offset:256
	s_nop 1
	v_mov_b32_e32 v112, v236
	s_nop 0
	v_mov_b32_e32 v114, v237
	v_mov_b32_e32 v113, v238
	v_mov_b32_e32 v115, v239
	s_nop 0
	v_pk_add_f32 v[112:113], v[112:113], v[114:115]
	s_nop 0
	v_add_f32_e32 v112, v112, v113
	v_fmamk_f32 v112, v112, 0x3a800000, v158
	v_cmp_gt_f32_e32 vcc, s67, v112
	v_mul_f32_e32 v113, 0x4b800000, v112
	s_nop 0
	v_cndmask_b32_e32 v112, v112, v113, vcc
	v_rsq_f32_e32 v112, v112
	s_nop 0
	v_mul_f32_e32 v113, 0x45800000, v112
	v_cndmask_b32_e32 v114, v112, v113, vcc
	v_add_u32_e32 v112, 16, v152
	v_pk_mul_f32 v[104:105], v[104:105], v[114:115] op_sel_hi:[1,0]
	v_ashrrev_i32_e32 v113, 31, v112
	v_pk_mul_f32 v[108:109], v[108:109], v[114:115] op_sel_hi:[1,0]
	v_pk_mul_f32 v[106:107], v[106:107], v[114:115] op_sel_hi:[1,0]
	v_max_f32_e32 v104, 0, v104
	v_lshlrev_b64 v[112:113], 13, v[112:113]
	v_pk_mul_f32 v[110:111], v[110:111], v[114:115] op_sel_hi:[1,0]
	v_mul_f32_e32 v115, v104, v104
	v_max_f32_e32 v104, 0, v109
	v_max_f32_e32 v105, 0, v105
	v_max_f32_e32 v106, 0, v106
	v_lshl_add_u64 v[112:113], s[92:93], 0, v[112:113]
	v_max_f32_e32 v108, 0, v108
	v_mul_f32_e32 v104, v104, v104
	v_mul_f32_e32 v109, v105, v105
	v_max_f32_e32 v105, 0, v110
	v_mul_f32_e32 v110, v106, v106
	v_max_f32_e32 v106, 0, v111
	v_max_f32_e32 v107, 0, v107
	v_pk_mul_f32 v[98:99], v[98:99], v[114:115] op_sel_hi:[1,0]
	v_pk_mul_f32 v[96:97], v[96:97], v[114:115] op_sel_hi:[1,0]
	v_lshl_add_u64 v[112:113], v[112:113], 0, v[154:155]
	v_mul_f32_e32 v108, v108, v108
	v_mul_f32_e32 v105, v105, v105
	v_mul_f32_e32 v106, v106, v106
	v_mul_f32_e32 v107, v107, v107
	v_cvt_pk_bf16_f32 v104, v108, v104
	v_pk_mul_f32 v[102:103], v[102:103], v[114:115] op_sel_hi:[1,0]
	v_pk_mul_f32 v[100:101], v[100:101], v[114:115] op_sel_hi:[1,0]
	v_max_f32_e32 v96, 0, v96
	v_max_f32_e32 v97, 0, v97
	v_max_f32_e32 v98, 0, v98
	v_cvt_pk_bf16_f32 v105, v105, v106
	v_cvt_pk_bf16_f32 v106, v115, v109
	v_cvt_pk_bf16_f32 v107, v110, v107
	global_store_dwordx4 v[112:113], v[104:107], off
	v_max_f32_e32 v99, 0, v99
	v_max_f32_e32 v100, 0, v100
	v_mul_f32_e32 v104, v96, v96
	v_max_f32_e32 v96, 0, v101
	v_mul_f32_e32 v101, v97, v97
	v_max_f32_e32 v97, 0, v102
	v_mul_f32_e32 v102, v98, v98
	v_max_f32_e32 v98, 0, v103
	v_mul_f32_e32 v96, v96, v96
	v_mul_f32_e32 v97, v97, v97
	v_mul_f32_e32 v98, v98, v98
	v_mul_f32_e32 v99, v99, v99
	v_mul_f32_e32 v100, v100, v100
	v_cvt_pk_bf16_f32 v96, v100, v96
	v_cvt_pk_bf16_f32 v97, v97, v98
	v_cvt_pk_bf16_f32 v98, v104, v101
	v_cvt_pk_bf16_f32 v99, v102, v99
	global_store_dwordx4 v[112:113], v[96:99], off offset:256
	s_nop 1
	v_mov_b32_e32 v96, v240
	s_nop 0
	v_mov_b32_e32 v98, v241
	v_mov_b32_e32 v97, v242
	v_mov_b32_e32 v99, v243
	s_nop 0
	v_pk_add_f32 v[96:97], v[96:97], v[98:99]
	s_nop 0
	v_add_f32_e32 v96, v96, v97
	v_fmamk_f32 v96, v96, 0x3a800000, v158
	v_cmp_gt_f32_e32 vcc, s67, v96
	v_mul_f32_e32 v97, 0x4b800000, v96
	s_nop 0
	v_cndmask_b32_e32 v96, v96, v97, vcc
	v_rsq_f32_e32 v96, v96
	s_nop 0
	v_mul_f32_e32 v97, 0x45800000, v96
	v_cndmask_b32_e32 v98, v96, v97, vcc
	v_add_u32_e32 v96, 32, v152
	v_pk_mul_f32 v[88:89], v[88:89], v[98:99] op_sel_hi:[1,0]
	v_ashrrev_i32_e32 v97, 31, v96
	v_pk_mul_f32 v[92:93], v[92:93], v[98:99] op_sel_hi:[1,0]
	v_pk_mul_f32 v[90:91], v[90:91], v[98:99] op_sel_hi:[1,0]
	v_max_f32_e32 v88, 0, v88
	v_lshlrev_b64 v[96:97], 13, v[96:97]
	v_pk_mul_f32 v[94:95], v[94:95], v[98:99] op_sel_hi:[1,0]
	v_mul_f32_e32 v99, v88, v88
	v_max_f32_e32 v88, 0, v93
	v_max_f32_e32 v89, 0, v89
	v_max_f32_e32 v90, 0, v90
	v_lshl_add_u64 v[96:97], s[92:93], 0, v[96:97]
	v_max_f32_e32 v92, 0, v92
	v_mul_f32_e32 v88, v88, v88
	v_mul_f32_e32 v93, v89, v89
	v_max_f32_e32 v89, 0, v94
	v_mul_f32_e32 v94, v90, v90
	v_max_f32_e32 v90, 0, v95
	v_max_f32_e32 v91, 0, v91
	v_pk_mul_f32 v[82:83], v[82:83], v[98:99] op_sel_hi:[1,0]
	v_pk_mul_f32 v[80:81], v[80:81], v[98:99] op_sel_hi:[1,0]
	v_lshl_add_u64 v[96:97], v[96:97], 0, v[154:155]
	v_mul_f32_e32 v92, v92, v92
	v_mul_f32_e32 v89, v89, v89
	v_mul_f32_e32 v90, v90, v90
	v_mul_f32_e32 v91, v91, v91
	v_cvt_pk_bf16_f32 v88, v92, v88
	v_pk_mul_f32 v[86:87], v[86:87], v[98:99] op_sel_hi:[1,0]
	v_pk_mul_f32 v[84:85], v[84:85], v[98:99] op_sel_hi:[1,0]
	v_max_f32_e32 v80, 0, v80
	v_max_f32_e32 v81, 0, v81
	v_max_f32_e32 v82, 0, v82
	v_cvt_pk_bf16_f32 v89, v89, v90
	v_cvt_pk_bf16_f32 v90, v99, v93
	v_cvt_pk_bf16_f32 v91, v94, v91
	global_store_dwordx4 v[96:97], v[88:91], off
	v_max_f32_e32 v83, 0, v83
	v_max_f32_e32 v84, 0, v84
	v_mul_f32_e32 v88, v80, v80
	v_max_f32_e32 v80, 0, v85
	v_mul_f32_e32 v85, v81, v81
	v_max_f32_e32 v81, 0, v86
	v_mul_f32_e32 v86, v82, v82
	v_max_f32_e32 v82, 0, v87
	v_mul_f32_e32 v80, v80, v80
	v_mul_f32_e32 v81, v81, v81
	v_mul_f32_e32 v82, v82, v82
	v_mul_f32_e32 v83, v83, v83
	v_mul_f32_e32 v84, v84, v84
	v_cvt_pk_bf16_f32 v80, v84, v80
	v_cvt_pk_bf16_f32 v81, v81, v82
	v_cvt_pk_bf16_f32 v82, v88, v85
	v_cvt_pk_bf16_f32 v83, v86, v83
	global_store_dwordx4 v[96:97], v[80:83], off offset:256
	s_nop 1
	v_mov_b32_e32 v80, v244
	s_nop 0
	v_mov_b32_e32 v82, v245
	v_mov_b32_e32 v81, v246
	v_mov_b32_e32 v83, v247
	s_nop 0
	v_pk_add_f32 v[80:81], v[80:81], v[82:83]
	s_nop 0
	v_add_f32_e32 v80, v80, v81
	v_fmamk_f32 v80, v80, 0x3a800000, v158
	v_cmp_gt_f32_e32 vcc, s67, v80
	v_mul_f32_e32 v81, 0x4b800000, v80
	s_nop 0
	v_cndmask_b32_e32 v80, v80, v81, vcc
	v_rsq_f32_e32 v80, v80
	s_nop 0
	v_mul_f32_e32 v81, 0x45800000, v80
	v_cndmask_b32_e32 v82, v80, v81, vcc
	v_add_u32_e32 v80, 48, v152
	v_pk_mul_f32 v[72:73], v[72:73], v[82:83] op_sel_hi:[1,0]
	v_ashrrev_i32_e32 v81, 31, v80
	v_pk_mul_f32 v[76:77], v[76:77], v[82:83] op_sel_hi:[1,0]
	v_pk_mul_f32 v[74:75], v[74:75], v[82:83] op_sel_hi:[1,0]
	v_max_f32_e32 v72, 0, v72
	v_lshlrev_b64 v[80:81], 13, v[80:81]
	v_pk_mul_f32 v[78:79], v[78:79], v[82:83] op_sel_hi:[1,0]
	v_mul_f32_e32 v83, v72, v72
	v_max_f32_e32 v72, 0, v77
	v_max_f32_e32 v73, 0, v73
	v_max_f32_e32 v74, 0, v74
	v_lshl_add_u64 v[80:81], s[92:93], 0, v[80:81]
	v_max_f32_e32 v76, 0, v76
	v_mul_f32_e32 v72, v72, v72
	v_mul_f32_e32 v77, v73, v73
	v_max_f32_e32 v73, 0, v78
	v_mul_f32_e32 v78, v74, v74
	v_max_f32_e32 v74, 0, v79
	v_max_f32_e32 v75, 0, v75
	v_pk_mul_f32 v[66:67], v[66:67], v[82:83] op_sel_hi:[1,0]
	v_pk_mul_f32 v[64:65], v[64:65], v[82:83] op_sel_hi:[1,0]
	v_lshl_add_u64 v[80:81], v[80:81], 0, v[154:155]
	v_mul_f32_e32 v76, v76, v76
	v_mul_f32_e32 v73, v73, v73
	v_mul_f32_e32 v74, v74, v74
	v_mul_f32_e32 v75, v75, v75
	v_cvt_pk_bf16_f32 v72, v76, v72
	v_pk_mul_f32 v[70:71], v[70:71], v[82:83] op_sel_hi:[1,0]
	v_pk_mul_f32 v[68:69], v[68:69], v[82:83] op_sel_hi:[1,0]
	v_max_f32_e32 v64, 0, v64
	v_max_f32_e32 v65, 0, v65
	v_max_f32_e32 v66, 0, v66
	v_cvt_pk_bf16_f32 v73, v73, v74
	v_cvt_pk_bf16_f32 v74, v83, v77
	v_cvt_pk_bf16_f32 v75, v78, v75
	global_store_dwordx4 v[80:81], v[72:75], off
	v_max_f32_e32 v67, 0, v67
	v_max_f32_e32 v68, 0, v68
	v_mul_f32_e32 v72, v64, v64
	v_max_f32_e32 v64, 0, v69
	v_mul_f32_e32 v69, v65, v65
	v_max_f32_e32 v65, 0, v70
	v_mul_f32_e32 v70, v66, v66
	v_max_f32_e32 v66, 0, v71
	v_mul_f32_e32 v64, v64, v64
	v_mul_f32_e32 v65, v65, v65
	v_mul_f32_e32 v66, v66, v66
	v_mul_f32_e32 v67, v67, v67
	v_mul_f32_e32 v68, v68, v68
	v_cvt_pk_bf16_f32 v64, v68, v64
	v_cvt_pk_bf16_f32 v65, v65, v66
	v_cvt_pk_bf16_f32 v66, v72, v69
	v_cvt_pk_bf16_f32 v67, v70, v67
	global_store_dwordx4 v[80:81], v[64:67], off offset:256
	s_nop 1
	v_mov_b32_e32 v64, v248
	s_nop 0
	v_mov_b32_e32 v66, v249
	v_mov_b32_e32 v65, v250
	v_mov_b32_e32 v67, v251
	s_nop 0
	v_pk_add_f32 v[64:65], v[64:65], v[66:67]
	s_nop 0
	v_add_f32_e32 v64, v64, v65
	v_fmamk_f32 v64, v64, 0x3a800000, v158
	v_cmp_gt_f32_e32 vcc, s67, v64
	v_mul_f32_e32 v65, 0x4b800000, v64
	s_nop 0
	v_cndmask_b32_e32 v64, v64, v65, vcc
	v_rsq_f32_e32 v64, v64
	s_nop 0
	v_mul_f32_e32 v65, 0x45800000, v64
	v_cndmask_b32_e32 v66, v64, v65, vcc
	v_add_u32_e32 v64, 0x80, v152
	v_pk_mul_f32 v[56:57], v[56:57], v[66:67] op_sel_hi:[1,0]
	v_ashrrev_i32_e32 v65, 31, v64
	v_pk_mul_f32 v[60:61], v[60:61], v[66:67] op_sel_hi:[1,0]
	v_pk_mul_f32 v[58:59], v[58:59], v[66:67] op_sel_hi:[1,0]
	v_max_f32_e32 v56, 0, v56
	v_lshlrev_b64 v[64:65], 13, v[64:65]
	v_pk_mul_f32 v[62:63], v[62:63], v[66:67] op_sel_hi:[1,0]
	v_mul_f32_e32 v67, v56, v56
	v_max_f32_e32 v56, 0, v61
	v_max_f32_e32 v57, 0, v57
	v_max_f32_e32 v58, 0, v58
	v_lshl_add_u64 v[64:65], s[92:93], 0, v[64:65]
	v_max_f32_e32 v60, 0, v60
	v_mul_f32_e32 v56, v56, v56
	v_mul_f32_e32 v61, v57, v57
	v_max_f32_e32 v57, 0, v62
	v_mul_f32_e32 v62, v58, v58
	v_max_f32_e32 v58, 0, v63
	v_max_f32_e32 v59, 0, v59
	v_pk_mul_f32 v[50:51], v[50:51], v[66:67] op_sel_hi:[1,0]
	v_pk_mul_f32 v[48:49], v[48:49], v[66:67] op_sel_hi:[1,0]
	v_lshl_add_u64 v[64:65], v[64:65], 0, v[154:155]
	v_mul_f32_e32 v60, v60, v60
	v_mul_f32_e32 v57, v57, v57
	v_mul_f32_e32 v58, v58, v58
	v_mul_f32_e32 v59, v59, v59
	v_cvt_pk_bf16_f32 v56, v60, v56
	v_pk_mul_f32 v[54:55], v[54:55], v[66:67] op_sel_hi:[1,0]
	v_pk_mul_f32 v[52:53], v[52:53], v[66:67] op_sel_hi:[1,0]
	v_max_f32_e32 v48, 0, v48
	v_max_f32_e32 v49, 0, v49
	v_max_f32_e32 v50, 0, v50
	v_cvt_pk_bf16_f32 v57, v57, v58
	v_cvt_pk_bf16_f32 v58, v67, v61
	v_cvt_pk_bf16_f32 v59, v62, v59
	global_store_dwordx4 v[64:65], v[56:59], off
	v_max_f32_e32 v51, 0, v51
	v_max_f32_e32 v52, 0, v52
	v_mul_f32_e32 v56, v48, v48
	v_max_f32_e32 v48, 0, v53
	v_mul_f32_e32 v53, v49, v49
	v_max_f32_e32 v49, 0, v54
	v_mul_f32_e32 v54, v50, v50
	v_max_f32_e32 v50, 0, v55
	v_mul_f32_e32 v48, v48, v48
	v_mul_f32_e32 v49, v49, v49
	v_mul_f32_e32 v50, v50, v50
	v_mul_f32_e32 v51, v51, v51
	v_mul_f32_e32 v52, v52, v52
	v_cvt_pk_bf16_f32 v48, v52, v48
	v_cvt_pk_bf16_f32 v49, v49, v50
	v_cvt_pk_bf16_f32 v50, v56, v53
	v_cvt_pk_bf16_f32 v51, v54, v51
	global_store_dwordx4 v[64:65], v[48:51], off offset:256
	s_waitcnt vmcnt(10)
	s_nop 1
	v_mov_b32_e32 v48, v166
	s_nop 0
	v_mov_b32_e32 v50, v167
	v_mov_b32_e32 v49, v168
	v_mov_b32_e32 v51, v169
	s_nop 0
	v_pk_add_f32 v[48:49], v[48:49], v[50:51]
	s_nop 0
	v_add_f32_e32 v48, v48, v49
	v_fmamk_f32 v48, v48, 0x3a800000, v158
	v_cmp_gt_f32_e32 vcc, s67, v48
	v_mul_f32_e32 v49, 0x4b800000, v48
	s_nop 0
	v_cndmask_b32_e32 v48, v48, v49, vcc
	v_rsq_f32_e32 v48, v48
	s_nop 0
	v_mul_f32_e32 v49, 0x45800000, v48
	v_cndmask_b32_e32 v50, v48, v49, vcc
	v_add_u32_e32 v48, 0x90, v152
	v_pk_mul_f32 v[40:41], v[40:41], v[50:51] op_sel_hi:[1,0]
	v_ashrrev_i32_e32 v49, 31, v48
	v_pk_mul_f32 v[44:45], v[44:45], v[50:51] op_sel_hi:[1,0]
	v_pk_mul_f32 v[42:43], v[42:43], v[50:51] op_sel_hi:[1,0]
	v_max_f32_e32 v40, 0, v40
	v_lshlrev_b64 v[48:49], 13, v[48:49]
	v_pk_mul_f32 v[46:47], v[46:47], v[50:51] op_sel_hi:[1,0]
	v_mul_f32_e32 v51, v40, v40
	v_max_f32_e32 v40, 0, v45
	v_max_f32_e32 v41, 0, v41
	v_max_f32_e32 v42, 0, v42
	v_lshl_add_u64 v[48:49], s[92:93], 0, v[48:49]
	v_max_f32_e32 v44, 0, v44
	v_mul_f32_e32 v40, v40, v40
	v_mul_f32_e32 v45, v41, v41
	v_max_f32_e32 v41, 0, v46
	v_mul_f32_e32 v46, v42, v42
	v_max_f32_e32 v42, 0, v47
	v_max_f32_e32 v43, 0, v43
	v_pk_mul_f32 v[34:35], v[34:35], v[50:51] op_sel_hi:[1,0]
	v_pk_mul_f32 v[32:33], v[32:33], v[50:51] op_sel_hi:[1,0]
	v_lshl_add_u64 v[48:49], v[48:49], 0, v[154:155]
	v_mul_f32_e32 v44, v44, v44
	v_mul_f32_e32 v41, v41, v41
	v_mul_f32_e32 v42, v42, v42
	v_mul_f32_e32 v43, v43, v43
	v_cvt_pk_bf16_f32 v40, v44, v40
	v_pk_mul_f32 v[38:39], v[38:39], v[50:51] op_sel_hi:[1,0]
	v_pk_mul_f32 v[36:37], v[36:37], v[50:51] op_sel_hi:[1,0]
	v_max_f32_e32 v32, 0, v32
	v_max_f32_e32 v33, 0, v33
	v_max_f32_e32 v34, 0, v34
	v_cvt_pk_bf16_f32 v41, v41, v42
	v_cvt_pk_bf16_f32 v42, v51, v45
	v_cvt_pk_bf16_f32 v43, v46, v43
	global_store_dwordx4 v[48:49], v[40:43], off
	v_max_f32_e32 v35, 0, v35
	v_max_f32_e32 v36, 0, v36
	v_mul_f32_e32 v40, v32, v32
	v_max_f32_e32 v32, 0, v37
	v_mul_f32_e32 v37, v33, v33
	v_max_f32_e32 v33, 0, v38
	v_mul_f32_e32 v38, v34, v34
	v_max_f32_e32 v34, 0, v39
	v_mul_f32_e32 v32, v32, v32
	v_mul_f32_e32 v33, v33, v33
	v_mul_f32_e32 v34, v34, v34
	v_mul_f32_e32 v35, v35, v35
	v_mul_f32_e32 v36, v36, v36
	v_cvt_pk_bf16_f32 v32, v36, v32
	v_cvt_pk_bf16_f32 v33, v33, v34
	v_cvt_pk_bf16_f32 v34, v40, v37
	v_cvt_pk_bf16_f32 v35, v38, v35
	global_store_dwordx4 v[48:49], v[32:35], off offset:256
	s_nop 1
	v_mov_b32_e32 v32, v170
	s_nop 0
	v_mov_b32_e32 v34, v171
	v_mov_b32_e32 v33, v172
	v_mov_b32_e32 v35, v173
	s_nop 0
	v_pk_add_f32 v[32:33], v[32:33], v[34:35]
	s_nop 0
	v_add_f32_e32 v32, v32, v33
	v_fmamk_f32 v32, v32, 0x3a800000, v158
	v_cmp_gt_f32_e32 vcc, s67, v32
	v_mul_f32_e32 v33, 0x4b800000, v32
	s_nop 0
	v_cndmask_b32_e32 v32, v32, v33, vcc
	v_rsq_f32_e32 v32, v32
	s_nop 0
	v_mul_f32_e32 v33, 0x45800000, v32
	v_cndmask_b32_e32 v34, v32, v33, vcc
	v_add_u32_e32 v32, 0xa0, v152
	v_pk_mul_f32 v[24:25], v[24:25], v[34:35] op_sel_hi:[1,0]
	v_ashrrev_i32_e32 v33, 31, v32
	v_pk_mul_f32 v[28:29], v[28:29], v[34:35] op_sel_hi:[1,0]
	v_pk_mul_f32 v[26:27], v[26:27], v[34:35] op_sel_hi:[1,0]
	v_max_f32_e32 v24, 0, v24
	v_lshlrev_b64 v[32:33], 13, v[32:33]
	v_pk_mul_f32 v[30:31], v[30:31], v[34:35] op_sel_hi:[1,0]
	v_mul_f32_e32 v35, v24, v24
	v_max_f32_e32 v24, 0, v29
	v_max_f32_e32 v25, 0, v25
	v_max_f32_e32 v26, 0, v26
	v_lshl_add_u64 v[32:33], s[92:93], 0, v[32:33]
	v_max_f32_e32 v28, 0, v28
	v_mul_f32_e32 v24, v24, v24
	v_mul_f32_e32 v29, v25, v25
	v_max_f32_e32 v25, 0, v30
	v_mul_f32_e32 v30, v26, v26
	v_max_f32_e32 v26, 0, v31
	v_max_f32_e32 v27, 0, v27
	v_pk_mul_f32 v[18:19], v[18:19], v[34:35] op_sel_hi:[1,0]
	v_pk_mul_f32 v[16:17], v[16:17], v[34:35] op_sel_hi:[1,0]
	v_lshl_add_u64 v[32:33], v[32:33], 0, v[154:155]
	v_mul_f32_e32 v28, v28, v28
	v_mul_f32_e32 v25, v25, v25
	v_mul_f32_e32 v26, v26, v26
	v_mul_f32_e32 v27, v27, v27
	v_cvt_pk_bf16_f32 v24, v28, v24
	v_pk_mul_f32 v[22:23], v[22:23], v[34:35] op_sel_hi:[1,0]
	v_pk_mul_f32 v[20:21], v[20:21], v[34:35] op_sel_hi:[1,0]
	v_max_f32_e32 v16, 0, v16
	v_max_f32_e32 v17, 0, v17
	v_max_f32_e32 v18, 0, v18
	v_cvt_pk_bf16_f32 v25, v25, v26
	v_cvt_pk_bf16_f32 v26, v35, v29
	v_cvt_pk_bf16_f32 v27, v30, v27
	global_store_dwordx4 v[32:33], v[24:27], off
	v_max_f32_e32 v19, 0, v19
	v_max_f32_e32 v20, 0, v20
	v_mul_f32_e32 v24, v16, v16
	v_max_f32_e32 v16, 0, v21
	v_mul_f32_e32 v21, v17, v17
	v_max_f32_e32 v17, 0, v22
	v_mul_f32_e32 v22, v18, v18
	v_max_f32_e32 v18, 0, v23
	v_mul_f32_e32 v16, v16, v16
	v_mul_f32_e32 v17, v17, v17
	v_mul_f32_e32 v18, v18, v18
	v_mul_f32_e32 v19, v19, v19
	v_mul_f32_e32 v20, v20, v20
	v_cvt_pk_bf16_f32 v16, v20, v16
	v_cvt_pk_bf16_f32 v17, v17, v18
	v_cvt_pk_bf16_f32 v18, v24, v21
	v_cvt_pk_bf16_f32 v19, v22, v19
	global_store_dwordx4 v[32:33], v[16:19], off offset:256
	s_nop 1
	v_mov_b32_e32 v16, v174
	s_nop 0
	v_mov_b32_e32 v18, v175
	v_mov_b32_e32 v17, v176
	v_mov_b32_e32 v19, v177
	s_nop 0
	v_pk_add_f32 v[16:17], v[16:17], v[18:19]
	s_nop 0
	v_add_f32_e32 v16, v16, v17
	v_fmamk_f32 v16, v16, 0x3a800000, v158
	v_cmp_gt_f32_e32 vcc, s67, v16
	v_mul_f32_e32 v17, 0x4b800000, v16
	v_add_u32_e32 v18, 0xb0, v152
	v_cndmask_b32_e32 v16, v16, v17, vcc
	v_rsq_f32_e32 v16, v16
	v_ashrrev_i32_e32 v19, 31, v18
	v_lshlrev_b64 v[18:19], 13, v[18:19]
	v_lshl_add_u64 v[18:19], s[92:93], 0, v[18:19]
	v_mul_f32_e32 v17, 0x45800000, v16
	v_cndmask_b32_e32 v16, v16, v17, vcc
	v_pk_mul_f32 v[8:9], v[8:9], v[16:17] op_sel_hi:[1,0]
	v_pk_mul_f32 v[12:13], v[12:13], v[16:17] op_sel_hi:[1,0]
	v_pk_mul_f32 v[10:11], v[10:11], v[16:17] op_sel_hi:[1,0]
	v_max_f32_e32 v8, 0, v8
	v_pk_mul_f32 v[14:15], v[14:15], v[16:17] op_sel_hi:[1,0]
	v_mul_f32_e32 v17, v8, v8
	v_max_f32_e32 v8, 0, v13
	v_max_f32_e32 v9, 0, v9
	v_max_f32_e32 v10, 0, v10
	v_max_f32_e32 v12, 0, v12
	v_mul_f32_e32 v8, v8, v8
	v_mul_f32_e32 v13, v9, v9
	v_max_f32_e32 v9, 0, v14
	v_mul_f32_e32 v14, v10, v10
	v_max_f32_e32 v10, 0, v15
	v_max_f32_e32 v11, 0, v11
	v_pk_mul_f32 v[2:3], v[2:3], v[16:17] op_sel_hi:[1,0]
	v_pk_mul_f32 v[0:1], v[0:1], v[16:17] op_sel_hi:[1,0]
	v_lshl_add_u64 v[18:19], v[18:19], 0, v[154:155]
	v_mul_f32_e32 v12, v12, v12
	v_mul_f32_e32 v9, v9, v9
	v_mul_f32_e32 v10, v10, v10
	v_mul_f32_e32 v11, v11, v11
	v_cvt_pk_bf16_f32 v8, v12, v8
	v_pk_mul_f32 v[6:7], v[6:7], v[16:17] op_sel_hi:[1,0]
	v_pk_mul_f32 v[4:5], v[4:5], v[16:17] op_sel_hi:[1,0]
	v_max_f32_e32 v0, 0, v0
	v_max_f32_e32 v1, 0, v1
	v_max_f32_e32 v2, 0, v2
	v_cvt_pk_bf16_f32 v9, v9, v10
	v_cvt_pk_bf16_f32 v10, v17, v13
	v_cvt_pk_bf16_f32 v11, v14, v11
	global_store_dwordx4 v[18:19], v[8:11], off
	v_max_f32_e32 v3, 0, v3
	v_max_f32_e32 v4, 0, v4
	v_mul_f32_e32 v8, v0, v0
	v_max_f32_e32 v0, 0, v5
	v_mul_f32_e32 v5, v1, v1
	v_max_f32_e32 v1, 0, v6
	v_mul_f32_e32 v6, v2, v2
	v_max_f32_e32 v2, 0, v7
	v_mul_f32_e32 v0, v0, v0
	v_mul_f32_e32 v1, v1, v1
	v_mul_f32_e32 v2, v2, v2
	v_mul_f32_e32 v3, v3, v3
	s_and_b64 vcc, exec, s[0:1]
	v_mul_f32_e32 v4, v4, v4
	v_cvt_pk_bf16_f32 v0, v4, v0
	v_cvt_pk_bf16_f32 v1, v1, v2
	v_cvt_pk_bf16_f32 v2, v8, v5
	v_cvt_pk_bf16_f32 v3, v6, v3
	global_store_dwordx4 v[18:19], v[0:3], off offset:256
	s_cbranch_vccz .LBB0_434
	s_waitcnt vmcnt(0)
	s_cmpk_gt_u32 s49, 0xff
	s_cbranch_scc1 .LBB0_445
	s_barrier

.LBB0_494:
	v_add_u32_e32 v226, s71, v154
	v_ashrrev_i32_e32 v227, 31, v226
	v_lshl_add_u64 v[228:229], v[226:227], 2, s[94:95]
	global_load_dword v232, v[228:229], off
	v_add_u32_e32 v226, s71, v154
	v_ashrrev_i32_e32 v227, 31, v226
	v_lshl_add_u64 v[228:229], v[226:227], 2, s[94:95]
	s_mov_b32 s98, 0x40000
	s_mov_b32 s99, 0
	v_lshl_add_u64 v[230:231], v[228:229], 0, s[98:99]
	global_load_dword v233, v[230:231], off
	v_add_u32_e32 v226, s71, v154
	v_ashrrev_i32_e32 v227, 31, v226
	v_lshl_add_u64 v[228:229], v[226:227], 2, s[94:95]
	s_mov_b32 s98, 0x80000
	s_mov_b32 s99, 0
	v_lshl_add_u64 v[230:231], v[228:229], 0, s[98:99]
	global_load_dword v234, v[230:231], off
	v_add_u32_e32 v226, s71, v154
	v_ashrrev_i32_e32 v227, 31, v226
	v_lshl_add_u64 v[228:229], v[226:227], 2, s[94:95]
	s_mov_b32 s98, 0xc0000
	s_mov_b32 s99, 0
	v_lshl_add_u64 v[230:231], v[228:229], 0, s[98:99]
	global_load_dword v235, v[230:231], off
	v_add_u32_e32 v226, s71, v154
	v_ashrrev_i32_e32 v227, 31, v226
	v_lshl_add_u64 v[228:229], v[226:227], 2, s[94:95]
	global_load_dword v236, v[228:229], off offset:64
	v_add_u32_e32 v226, s71, v154
	v_ashrrev_i32_e32 v227, 31, v226
	v_lshl_add_u64 v[228:229], v[226:227], 2, s[94:95]
	s_mov_b32 s98, 0x40000
	s_mov_b32 s99, 0
	v_lshl_add_u64 v[230:231], v[228:229], 0, s[98:99]
	global_load_dword v237, v[230:231], off offset:64
	v_add_u32_e32 v226, s71, v154
	v_ashrrev_i32_e32 v227, 31, v226
	v_lshl_add_u64 v[228:229], v[226:227], 2, s[94:95]
	s_mov_b32 s98, 0x80000
	s_mov_b32 s99, 0
	v_lshl_add_u64 v[230:231], v[228:229], 0, s[98:99]
	global_load_dword v238, v[230:231], off offset:64
	v_add_u32_e32 v226, s71, v154
	v_ashrrev_i32_e32 v227, 31, v226
	v_lshl_add_u64 v[228:229], v[226:227], 2, s[94:95]
	s_mov_b32 s98, 0xc0000
	s_mov_b32 s99, 0
	v_lshl_add_u64 v[230:231], v[228:229], 0, s[98:99]
	global_load_dword v239, v[230:231], off offset:64
	v_add_u32_e32 v226, s71, v154
	v_ashrrev_i32_e32 v227, 31, v226
	v_lshl_add_u64 v[228:229], v[226:227], 2, s[94:95]
	global_load_dword v240, v[228:229], off offset:128
	v_add_u32_e32 v226, s71, v154
	v_ashrrev_i32_e32 v227, 31, v226
	v_lshl_add_u64 v[228:229], v[226:227], 2, s[94:95]
	s_mov_b32 s98, 0x40000
	s_mov_b32 s99, 0
	v_lshl_add_u64 v[230:231], v[228:229], 0, s[98:99]
	global_load_dword v241, v[230:231], off offset:128
	v_add_u32_e32 v226, s71, v154
	v_ashrrev_i32_e32 v227, 31, v226
	v_lshl_add_u64 v[228:229], v[226:227], 2, s[94:95]
	s_mov_b32 s98, 0x80000
	s_mov_b32 s99, 0
	v_lshl_add_u64 v[230:231], v[228:229], 0, s[98:99]
	global_load_dword v242, v[230:231], off offset:128
	v_add_u32_e32 v226, s71, v154
	v_ashrrev_i32_e32 v227, 31, v226
	v_lshl_add_u64 v[228:229], v[226:227], 2, s[94:95]
	s_mov_b32 s98, 0xc0000
	s_mov_b32 s99, 0
	v_lshl_add_u64 v[230:231], v[228:229], 0, s[98:99]
	global_load_dword v243, v[230:231], off offset:128
	v_add_u32_e32 v226, s71, v154
	v_ashrrev_i32_e32 v227, 31, v226
	v_lshl_add_u64 v[228:229], v[226:227], 2, s[94:95]
	global_load_dword v244, v[228:229], off offset:192
	v_add_u32_e32 v226, s71, v154
	v_ashrrev_i32_e32 v227, 31, v226
	v_lshl_add_u64 v[228:229], v[226:227], 2, s[94:95]
	s_mov_b32 s98, 0x40000
	s_mov_b32 s99, 0
	v_lshl_add_u64 v[230:231], v[228:229], 0, s[98:99]
	global_load_dword v245, v[230:231], off offset:192
	v_add_u32_e32 v226, s71, v154
	v_ashrrev_i32_e32 v227, 31, v226
	v_lshl_add_u64 v[228:229], v[226:227], 2, s[94:95]
	s_mov_b32 s98, 0x80000
	s_mov_b32 s99, 0
	v_lshl_add_u64 v[230:231], v[228:229], 0, s[98:99]
	global_load_dword v246, v[230:231], off offset:192
	v_add_u32_e32 v226, s71, v154
	v_ashrrev_i32_e32 v227, 31, v226
	v_lshl_add_u64 v[228:229], v[226:227], 2, s[94:95]
	s_mov_b32 s98, 0xc0000
	s_mov_b32 s99, 0
	v_lshl_add_u64 v[230:231], v[228:229], 0, s[98:99]
	global_load_dword v247, v[230:231], off offset:192
	v_add_u32_e32 v226, s71, v154
	v_ashrrev_i32_e32 v227, 31, v226
	v_lshl_add_u64 v[228:229], v[226:227], 2, s[94:95]
	global_load_dword v248, v[228:229], off offset:512
	v_add_u32_e32 v226, s71, v154
	v_ashrrev_i32_e32 v227, 31, v226
	v_lshl_add_u64 v[228:229], v[226:227], 2, s[94:95]
	s_mov_b32 s98, 0x40000
	s_mov_b32 s99, 0
	v_lshl_add_u64 v[230:231], v[228:229], 0, s[98:99]
	global_load_dword v249, v[230:231], off offset:512
	v_add_u32_e32 v226, s71, v154
	v_ashrrev_i32_e32 v227, 31, v226
	v_lshl_add_u64 v[228:229], v[226:227], 2, s[94:95]
	s_mov_b32 s98, 0x80000
	s_mov_b32 s99, 0
	v_lshl_add_u64 v[230:231], v[228:229], 0, s[98:99]
	global_load_dword v250, v[230:231], off offset:512
	v_add_u32_e32 v226, s71, v154
	v_ashrrev_i32_e32 v227, 31, v226
	v_lshl_add_u64 v[228:229], v[226:227], 2, s[94:95]
	s_mov_b32 s98, 0xc0000
	s_mov_b32 s99, 0
	v_lshl_add_u64 v[230:231], v[228:229], 0, s[98:99]
	global_load_dword v251, v[230:231], off offset:512
	s_add_u32 s38, s42, 0x40080
	s_addc_u32 s39, s43, 0
	s_add_u32 s18, s44, 0x100
	v_mov_b32_e32 v0, 0
	s_addc_u32 s19, s45, 0
	s_mov_b32 s44, -2
	v_mov_b32_e32 v1, v0
	v_mov_b32_e32 v2, v0
	v_mov_b32_e32 v3, v0
	v_mov_b32_e32 v4, v0
	v_mov_b32_e32 v5, v0
	v_mov_b32_e32 v6, v0
	v_mov_b32_e32 v7, v0
	v_mov_b32_e32 v16, v0
	v_mov_b32_e32 v17, v0
	v_mov_b32_e32 v18, v0
	v_mov_b32_e32 v19, v0
	v_mov_b32_e32 v20, v0
	v_mov_b32_e32 v21, v0
	v_mov_b32_e32 v22, v0
	v_mov_b32_e32 v23, v0
	v_mov_b32_e32 v32, v0
	v_mov_b32_e32 v33, v0
	v_mov_b32_e32 v34, v0
	v_mov_b32_e32 v35, v0
	v_mov_b32_e32 v36, v0
	v_mov_b32_e32 v37, v0
	v_mov_b32_e32 v38, v0
	v_mov_b32_e32 v39, v0
	v_mov_b32_e32 v48, v0
	v_mov_b32_e32 v49, v0
	v_mov_b32_e32 v50, v0
	v_mov_b32_e32 v51, v0
	v_mov_b32_e32 v52, v0
	v_mov_b32_e32 v53, v0
	v_mov_b32_e32 v54, v0
	v_mov_b32_e32 v55, v0
	v_mov_b32_e32 v8, v0
	v_mov_b32_e32 v9, v0
	v_mov_b32_e32 v10, v0
	v_mov_b32_e32 v11, v0
	v_mov_b32_e32 v12, v0
	v_mov_b32_e32 v13, v0
	v_mov_b32_e32 v14, v0
	v_mov_b32_e32 v15, v0
	v_mov_b32_e32 v24, v0
	v_mov_b32_e32 v25, v0
	v_mov_b32_e32 v26, v0
	v_mov_b32_e32 v27, v0
	v_mov_b32_e32 v28, v0
	v_mov_b32_e32 v29, v0
	v_mov_b32_e32 v30, v0
	v_mov_b32_e32 v31, v0
	v_mov_b32_e32 v40, v0
	v_mov_b32_e32 v41, v0
	v_mov_b32_e32 v42, v0
	v_mov_b32_e32 v43, v0
	v_mov_b32_e32 v44, v0
	v_mov_b32_e32 v45, v0
	v_mov_b32_e32 v46, v0
	v_mov_b32_e32 v47, v0
	v_mov_b32_e32 v56, v0
	v_mov_b32_e32 v57, v0
	v_mov_b32_e32 v58, v0
	v_mov_b32_e32 v59, v0
	v_mov_b32_e32 v60, v0
	v_mov_b32_e32 v61, v0
	v_mov_b32_e32 v62, v0
	v_mov_b32_e32 v63, v0
	v_mov_b32_e32 v64, v0
	v_mov_b32_e32 v65, v0
	v_mov_b32_e32 v66, v0
	v_mov_b32_e32 v67, v0
	v_mov_b32_e32 v68, v0
	v_mov_b32_e32 v69, v0
	v_mov_b32_e32 v70, v0
	v_mov_b32_e32 v71, v0
	v_mov_b32_e32 v80, v0
	v_mov_b32_e32 v81, v0
	v_mov_b32_e32 v82, v0
	v_mov_b32_e32 v83, v0
	v_mov_b32_e32 v84, v0
	v_mov_b32_e32 v85, v0
	v_mov_b32_e32 v86, v0
	v_mov_b32_e32 v87, v0
	v_mov_b32_e32 v96, v0
	v_mov_b32_e32 v97, v0
	v_mov_b32_e32 v98, v0
	v_mov_b32_e32 v99, v0
	v_mov_b32_e32 v100, v0
	v_mov_b32_e32 v101, v0
	v_mov_b32_e32 v102, v0
	v_mov_b32_e32 v103, v0
	v_mov_b32_e32 v112, v0
	v_mov_b32_e32 v113, v0
	v_mov_b32_e32 v114, v0
	v_mov_b32_e32 v115, v0
	v_mov_b32_e32 v116, v0
	v_mov_b32_e32 v117, v0
	v_mov_b32_e32 v118, v0
	v_mov_b32_e32 v119, v0
	v_mov_b32_e32 v72, v0
	v_mov_b32_e32 v73, v0
	v_mov_b32_e32 v74, v0
	v_mov_b32_e32 v75, v0
	v_mov_b32_e32 v76, v0
	v_mov_b32_e32 v77, v0
	v_mov_b32_e32 v78, v0
	v_mov_b32_e32 v79, v0
	v_mov_b32_e32 v88, v0
	v_mov_b32_e32 v89, v0
	v_mov_b32_e32 v90, v0
	v_mov_b32_e32 v91, v0
	v_mov_b32_e32 v92, v0
	v_mov_b32_e32 v93, v0
	v_mov_b32_e32 v94, v0
	v_mov_b32_e32 v95, v0
	v_mov_b32_e32 v104, v0
	v_mov_b32_e32 v105, v0
	v_mov_b32_e32 v106, v0
	v_mov_b32_e32 v107, v0
	v_mov_b32_e32 v108, v0
	v_mov_b32_e32 v109, v0
	v_mov_b32_e32 v110, v0
	v_mov_b32_e32 v111, v0
	v_mov_b32_e32 v120, v0
	v_mov_b32_e32 v121, v0
	v_mov_b32_e32 v122, v0
	v_mov_b32_e32 v123, v0
	v_mov_b32_e32 v124, v0
	v_mov_b32_e32 v125, v0
	v_mov_b32_e32 v126, v0
	v_mov_b32_e32 v127, v0
.LBB0_495:
	ds_read_b128 v[144:147], v156
	ds_read_b128 v[148:151], v156 offset:1024
	ds_read_b128 v[160:163], v156 offset:2048
	ds_read_b128 v[164:167], v156 offset:3072
	s_add_u32 s22, s38, 0xfffc0080
	s_addc_u32 s23, s39, -1
	s_cmp_eq_u32 s44, 12
	s_cselect_b32 s43, s35, s23
	s_cselect_b32 s42, s34, s22
	s_cselect_b32 s41, s37, s19
	s_cselect_b32 s40, s36, s18
	v_lshl_add_u64 v[152:153], s[38:39], 0, v[138:139]
	s_add_i32 m0, s50, 0xc000
	ds_read_b128 v[168:171], v157
	ds_read_b128 v[172:175], v157 offset:1024
	ds_read_b128 v[176:179], v157 offset:2048
	ds_read_b128 v[180:183], v157 offset:3072
	ds_read_b128 v[184:187], v157 offset:4096
	ds_read_b128 v[188:191], v157 offset:5120
	ds_read_b128 v[192:195], v157 offset:6144
	ds_read_b128 v[200:203], v157 offset:7168
	global_load_lds_dwordx4 v[152:153], off
	v_lshl_add_u64 v[152:153], s[38:39], 0, v[140:141]
	s_add_i32 m0, s50, 0xe000
	s_nop 0
	global_load_lds_dwordx4 v[152:153], off
	s_waitcnt lgkmcnt(8)
	s_barrier
	s_waitcnt lgkmcnt(0)
	s_setprio 1
	s_waitcnt lgkmcnt(0)
	v_mfma_f32_16x16x32_bf16 v[124:127], v[144:147], v[168:171], v[124:127]
	v_mfma_f32_16x16x32_bf16 v[120:123], v[160:163], v[168:171], v[120:123]
	v_mfma_f32_16x16x32_bf16 v[108:111], v[144:147], v[176:179], v[108:111]
	v_mfma_f32_16x16x32_bf16 v[104:107], v[160:163], v[176:179], v[104:107]
	v_mfma_f32_16x16x32_bf16 v[92:95], v[144:147], v[184:187], v[92:95]
	v_mfma_f32_16x16x32_bf16 v[88:91], v[160:163], v[184:187], v[88:91]
	v_mfma_f32_16x16x32_bf16 v[76:79], v[144:147], v[192:195], v[76:79]
	v_mfma_f32_16x16x32_bf16 v[72:75], v[160:163], v[192:195], v[72:75]
	v_mfma_f32_16x16x32_bf16 v[124:127], v[148:151], v[172:175], v[124:127]
	v_mfma_f32_16x16x32_bf16 v[120:123], v[164:167], v[172:175], v[120:123]
	v_mfma_f32_16x16x32_bf16 v[108:111], v[148:151], v[180:183], v[108:111]
	v_mfma_f32_16x16x32_bf16 v[104:107], v[164:167], v[180:183], v[104:107]
	v_mfma_f32_16x16x32_bf16 v[92:95], v[148:151], v[188:191], v[92:95]
	v_mfma_f32_16x16x32_bf16 v[88:91], v[164:167], v[188:191], v[88:91]
	v_mfma_f32_16x16x32_bf16 v[76:79], v[148:151], v[200:203], v[76:79]
	v_mfma_f32_16x16x32_bf16 v[72:75], v[164:167], v[200:203], v[72:75]
	s_setprio 0
	s_barrier
	s_add_i32 s22, s64, s48
	v_lshl_add_u64 v[152:153], s[40:41], 0, v[132:133]
	s_mov_b32 m0, s22
	ds_read_b128 v[204:207], v158
	ds_read_b128 v[208:211], v158 offset:1024
	ds_read_b128 v[212:215], v158 offset:2048
	ds_read_b128 v[216:219], v158 offset:3072
	global_load_lds_dwordx4 v[152:153], off
	v_lshl_add_u64 v[220:221], s[40:41], 0, v[128:129]
	s_add_i32 m0, s22, 0x2000
	s_nop 0
	global_load_lds_dwordx4 v[220:221], off
	s_barrier
	s_waitcnt lgkmcnt(0)
	s_setprio 1
	s_waitcnt lgkmcnt(0)
	v_mfma_f32_16x16x32_bf16 v[116:119], v[204:207], v[168:171], v[116:119]
	v_mfma_f32_16x16x32_bf16 v[112:115], v[212:215], v[168:171], v[112:115]
	v_mfma_f32_16x16x32_bf16 v[100:103], v[204:207], v[176:179], v[100:103]
	v_mfma_f32_16x16x32_bf16 v[96:99], v[212:215], v[176:179], v[96:99]
	v_mfma_f32_16x16x32_bf16 v[84:87], v[204:207], v[184:187], v[84:87]
	v_mfma_f32_16x16x32_bf16 v[80:83], v[212:215], v[184:187], v[80:83]
	v_mfma_f32_16x16x32_bf16 v[68:71], v[204:207], v[192:195], v[68:71]
	v_mfma_f32_16x16x32_bf16 v[64:67], v[212:215], v[192:195], v[64:67]
	v_mfma_f32_16x16x32_bf16 v[116:119], v[208:211], v[172:175], v[116:119]
	v_mfma_f32_16x16x32_bf16 v[112:115], v[216:219], v[172:175], v[112:115]
	v_mfma_f32_16x16x32_bf16 v[100:103], v[208:211], v[180:183], v[100:103]
	v_mfma_f32_16x16x32_bf16 v[96:99], v[216:219], v[180:183], v[96:99]
	v_mfma_f32_16x16x32_bf16 v[84:87], v[208:211], v[188:191], v[84:87]
	v_mfma_f32_16x16x32_bf16 v[80:83], v[216:219], v[188:191], v[80:83]
	v_mfma_f32_16x16x32_bf16 v[68:71], v[208:211], v[200:203], v[68:71]
	v_mfma_f32_16x16x32_bf16 v[64:67], v[216:219], v[200:203], v[64:67]
	s_setprio 0
	s_mov_b32 m0, s50
	v_lshl_add_u64 v[222:223], s[42:43], 0, v[134:135]
	s_barrier
	ds_read_b128 v[168:171], v157 offset:16384
	ds_read_b128 v[172:175], v157 offset:17408
	ds_read_b128 v[176:179], v157 offset:18432
	ds_read_b128 v[180:183], v157 offset:19456
	ds_read_b128 v[184:187], v157 offset:20480
	ds_read_b128 v[188:191], v157 offset:21504
	ds_read_b128 v[192:195], v157 offset:22528
	ds_read_b128 v[200:203], v157 offset:23552
	global_load_lds_dwordx4 v[222:223], off
	v_lshl_add_u64 v[224:225], s[42:43], 0, v[130:131]
	s_mov_b32 m0, s51
	s_nop 0
	global_load_lds_dwordx4 v[224:225], off
	s_barrier
	s_waitcnt lgkmcnt(0)
	s_setprio 1
	s_waitcnt lgkmcnt(0)
	v_mfma_f32_16x16x32_bf16 v[60:63], v[144:147], v[168:171], v[60:63]
	v_mfma_f32_16x16x32_bf16 v[56:59], v[160:163], v[168:171], v[56:59]
	v_mfma_f32_16x16x32_bf16 v[44:47], v[144:147], v[176:179], v[44:47]
	v_mfma_f32_16x16x32_bf16 v[40:43], v[160:163], v[176:179], v[40:43]
	v_mfma_f32_16x16x32_bf16 v[28:31], v[144:147], v[184:187], v[28:31]
	v_mfma_f32_16x16x32_bf16 v[24:27], v[160:163], v[184:187], v[24:27]
	v_mfma_f32_16x16x32_bf16 v[12:15], v[144:147], v[192:195], v[12:15]
	v_mfma_f32_16x16x32_bf16 v[8:11], v[160:163], v[192:195], v[8:11]
	v_mfma_f32_16x16x32_bf16 v[60:63], v[148:151], v[172:175], v[60:63]
	v_mfma_f32_16x16x32_bf16 v[56:59], v[164:167], v[172:175], v[56:59]
	v_mfma_f32_16x16x32_bf16 v[44:47], v[148:151], v[180:183], v[44:47]
	v_mfma_f32_16x16x32_bf16 v[40:43], v[164:167], v[180:183], v[40:43]
	v_mfma_f32_16x16x32_bf16 v[28:31], v[148:151], v[188:191], v[28:31]
	v_mfma_f32_16x16x32_bf16 v[24:27], v[164:167], v[188:191], v[24:27]
	v_mfma_f32_16x16x32_bf16 v[12:15], v[148:151], v[200:203], v[12:15]
	v_mfma_f32_16x16x32_bf16 v[8:11], v[164:167], v[200:203], v[8:11]
	s_setprio 0
	s_barrier
	s_add_u32 s22, s40, 0x40000
	s_addc_u32 s23, s41, 0
	s_add_i32 s45, s65, s48
	v_lshl_add_u64 v[144:145], s[22:23], 0, v[132:133]
	s_mov_b32 m0, s45
	s_nop 0
	global_load_lds_dwordx4 v[144:145], off
	v_lshl_add_u64 v[144:145], s[22:23], 0, v[128:129]
	s_add_i32 m0, s45, 0x2000
	s_nop 0
	global_load_lds_dwordx4 v[144:145], off
	s_waitcnt vmcnt(6)
	s_barrier
	s_setprio 1
	v_mfma_f32_16x16x32_bf16 v[52:55], v[204:207], v[168:171], v[52:55]
	v_mfma_f32_16x16x32_bf16 v[48:51], v[212:215], v[168:171], v[48:51]
	v_mfma_f32_16x16x32_bf16 v[36:39], v[204:207], v[176:179], v[36:39]
	v_mfma_f32_16x16x32_bf16 v[32:35], v[212:215], v[176:179], v[32:35]
	v_mfma_f32_16x16x32_bf16 v[20:23], v[204:207], v[184:187], v[20:23]
	v_mfma_f32_16x16x32_bf16 v[16:19], v[212:215], v[184:187], v[16:19]
	v_mfma_f32_16x16x32_bf16 v[4:7], v[204:207], v[192:195], v[4:7]
	v_mfma_f32_16x16x32_bf16 v[0:3], v[212:215], v[192:195], v[0:3]
	v_mfma_f32_16x16x32_bf16 v[52:55], v[208:211], v[172:175], v[52:55]
	v_mfma_f32_16x16x32_bf16 v[48:51], v[216:219], v[172:175], v[48:51]
	v_mfma_f32_16x16x32_bf16 v[36:39], v[208:211], v[180:183], v[36:39]
	v_mfma_f32_16x16x32_bf16 v[32:35], v[216:219], v[180:183], v[32:35]
	v_mfma_f32_16x16x32_bf16 v[20:23], v[208:211], v[188:191], v[20:23]
	v_mfma_f32_16x16x32_bf16 v[16:19], v[216:219], v[188:191], v[16:19]
	v_mfma_f32_16x16x32_bf16 v[4:7], v[208:211], v[200:203], v[4:7]
	v_mfma_f32_16x16x32_bf16 v[0:3], v[216:219], v[200:203], v[0:3]
	s_setprio 0
	s_add_i32 s45, 0, 0x18000
	v_add_u32_e32 v164, s45, v155
	s_barrier
	ds_read_b128 v[144:147], v164
	ds_read_b128 v[148:151], v164 offset:1024
	ds_read_b128 v[160:163], v164 offset:2048
	ds_read_b128 v[164:167], v164 offset:3072
	s_add_u32 s22, s42, 0x40000
	s_addc_u32 s23, s43, 0
	s_mov_b32 m0, s52
	v_lshl_add_u64 v[204:205], s[22:23], 0, v[134:135]
	ds_read_b128 v[168:171], v157 offset:32768
	ds_read_b128 v[172:175], v157 offset:33792
	ds_read_b128 v[176:179], v157 offset:34816
	ds_read_b128 v[180:183], v157 offset:35840
	ds_read_b128 v[184:187], v157 offset:36864
	ds_read_b128 v[188:191], v157 offset:37888
	ds_read_b128 v[192:195], v157 offset:38912
	ds_read_b128 v[200:203], v157 offset:39936
	global_load_lds_dwordx4 v[204:205], off
	v_lshl_add_u64 v[204:205], s[22:23], 0, v[130:131]
	s_mov_b32 m0, s53
	s_nop 0
	global_load_lds_dwordx4 v[204:205], off
	s_waitcnt lgkmcnt(8)
	s_barrier
	s_waitcnt lgkmcnt(0)
	s_setprio 1
	s_waitcnt lgkmcnt(0)
	v_mfma_f32_16x16x32_bf16 v[124:127], v[144:147], v[168:171], v[124:127]
	v_mfma_f32_16x16x32_bf16 v[120:123], v[160:163], v[168:171], v[120:123]
	v_mfma_f32_16x16x32_bf16 v[108:111], v[144:147], v[176:179], v[108:111]
	v_mfma_f32_16x16x32_bf16 v[104:107], v[160:163], v[176:179], v[104:107]
	v_mfma_f32_16x16x32_bf16 v[92:95], v[144:147], v[184:187], v[92:95]
	v_mfma_f32_16x16x32_bf16 v[88:91], v[160:163], v[184:187], v[88:91]
	v_mfma_f32_16x16x32_bf16 v[76:79], v[144:147], v[192:195], v[76:79]
	v_mfma_f32_16x16x32_bf16 v[72:75], v[160:163], v[192:195], v[72:75]
	v_mfma_f32_16x16x32_bf16 v[124:127], v[148:151], v[172:175], v[124:127]
	v_mfma_f32_16x16x32_bf16 v[120:123], v[164:167], v[172:175], v[120:123]
	v_mfma_f32_16x16x32_bf16 v[108:111], v[148:151], v[180:183], v[108:111]
	v_mfma_f32_16x16x32_bf16 v[104:107], v[164:167], v[180:183], v[104:107]
	v_mfma_f32_16x16x32_bf16 v[92:95], v[148:151], v[188:191], v[92:95]
	v_mfma_f32_16x16x32_bf16 v[88:91], v[164:167], v[188:191], v[88:91]
	v_mfma_f32_16x16x32_bf16 v[76:79], v[148:151], v[200:203], v[76:79]
	v_mfma_f32_16x16x32_bf16 v[72:75], v[164:167], v[200:203], v[72:75]
	s_setprio 0
	s_barrier
	s_add_i32 s42, 0, 0x1c000
	s_add_i32 s22, s45, s48
	v_add_u32_e32 v216, s42, v155
	v_lshl_add_u64 v[152:153], v[152:153], 0, s[6:7]
	s_mov_b32 m0, s22
	ds_read_b128 v[204:207], v216
	ds_read_b128 v[208:211], v216 offset:1024
	ds_read_b128 v[212:215], v216 offset:2048
	ds_read_b128 v[216:219], v216 offset:3072
	global_load_lds_dwordx4 v[152:153], off
	v_lshl_add_u64 v[152:153], v[220:221], 0, s[6:7]
	s_add_i32 m0, s22, 0x2000
	s_nop 0
	global_load_lds_dwordx4 v[152:153], off
	s_barrier
	s_waitcnt lgkmcnt(0)
	s_setprio 1
	s_waitcnt lgkmcnt(0)
	v_mfma_f32_16x16x32_bf16 v[116:119], v[204:207], v[168:171], v[116:119]
	v_mfma_f32_16x16x32_bf16 v[112:115], v[212:215], v[168:171], v[112:115]
	v_mfma_f32_16x16x32_bf16 v[100:103], v[204:207], v[176:179], v[100:103]
	v_mfma_f32_16x16x32_bf16 v[96:99], v[212:215], v[176:179], v[96:99]
	v_mfma_f32_16x16x32_bf16 v[84:87], v[204:207], v[184:187], v[84:87]
	v_mfma_f32_16x16x32_bf16 v[80:83], v[212:215], v[184:187], v[80:83]
	v_mfma_f32_16x16x32_bf16 v[68:71], v[204:207], v[192:195], v[68:71]
	v_mfma_f32_16x16x32_bf16 v[64:67], v[212:215], v[192:195], v[64:67]
	v_mfma_f32_16x16x32_bf16 v[116:119], v[208:211], v[172:175], v[116:119]
	v_mfma_f32_16x16x32_bf16 v[112:115], v[216:219], v[172:175], v[112:115]
	v_mfma_f32_16x16x32_bf16 v[100:103], v[208:211], v[180:183], v[100:103]
	v_mfma_f32_16x16x32_bf16 v[96:99], v[216:219], v[180:183], v[96:99]
	v_mfma_f32_16x16x32_bf16 v[84:87], v[208:211], v[188:191], v[84:87]
	v_mfma_f32_16x16x32_bf16 v[80:83], v[216:219], v[188:191], v[80:83]
	v_mfma_f32_16x16x32_bf16 v[68:71], v[208:211], v[200:203], v[68:71]
	v_mfma_f32_16x16x32_bf16 v[64:67], v[216:219], v[200:203], v[64:67]
	s_setprio 0
	s_mov_b32 m0, s62
	v_lshl_add_u64 v[152:153], v[222:223], 0, s[6:7]
	s_barrier
	ds_read_b128 v[168:171], v157 offset:49152
	ds_read_b128 v[172:175], v157 offset:50176
	ds_read_b128 v[176:179], v157 offset:51200
	ds_read_b128 v[180:183], v157 offset:52224
	ds_read_b128 v[184:187], v157 offset:53248
	ds_read_b128 v[188:191], v157 offset:54272
	ds_read_b128 v[192:195], v157 offset:55296
	ds_read_b128 v[200:203], v157 offset:56320
	global_load_lds_dwordx4 v[152:153], off
	v_lshl_add_u64 v[152:153], v[224:225], 0, s[6:7]
	s_mov_b32 m0, s63
	s_nop 0
	global_load_lds_dwordx4 v[152:153], off
	s_barrier
	s_waitcnt lgkmcnt(0)
	s_setprio 1
	s_waitcnt lgkmcnt(0)
	v_mfma_f32_16x16x32_bf16 v[60:63], v[144:147], v[168:171], v[60:63]
	v_mfma_f32_16x16x32_bf16 v[56:59], v[160:163], v[168:171], v[56:59]
	v_mfma_f32_16x16x32_bf16 v[44:47], v[144:147], v[176:179], v[44:47]
	v_mfma_f32_16x16x32_bf16 v[40:43], v[160:163], v[176:179], v[40:43]
	v_mfma_f32_16x16x32_bf16 v[28:31], v[144:147], v[184:187], v[28:31]
	v_mfma_f32_16x16x32_bf16 v[24:27], v[160:163], v[184:187], v[24:27]
	v_mfma_f32_16x16x32_bf16 v[12:15], v[144:147], v[192:195], v[12:15]
	v_mfma_f32_16x16x32_bf16 v[8:11], v[160:163], v[192:195], v[8:11]
	v_mfma_f32_16x16x32_bf16 v[60:63], v[148:151], v[172:175], v[60:63]
	v_mfma_f32_16x16x32_bf16 v[56:59], v[164:167], v[172:175], v[56:59]
	v_mfma_f32_16x16x32_bf16 v[44:47], v[148:151], v[180:183], v[44:47]
	v_mfma_f32_16x16x32_bf16 v[40:43], v[164:167], v[180:183], v[40:43]
	v_mfma_f32_16x16x32_bf16 v[28:31], v[148:151], v[188:191], v[28:31]
	v_mfma_f32_16x16x32_bf16 v[24:27], v[164:167], v[188:191], v[24:27]
	v_mfma_f32_16x16x32_bf16 v[12:15], v[148:151], v[200:203], v[12:15]
	v_mfma_f32_16x16x32_bf16 v[8:11], v[164:167], v[200:203], v[8:11]
	s_setprio 0
	s_barrier
	s_add_u32 s22, s40, 0x40080
	s_addc_u32 s23, s41, 0
	s_add_i32 s40, s42, s48
	v_lshl_add_u64 v[144:145], s[22:23], 0, v[132:133]
	s_mov_b32 m0, s40
	s_nop 0
	global_load_lds_dwordx4 v[144:145], off
	v_lshl_add_u64 v[144:145], s[22:23], 0, v[128:129]
	s_add_i32 m0, s40, 0x2000
	s_nop 0
	global_load_lds_dwordx4 v[144:145], off
	s_waitcnt vmcnt(6)
	s_barrier
	s_setprio 1
	v_mfma_f32_16x16x32_bf16 v[52:55], v[204:207], v[168:171], v[52:55]
	v_mfma_f32_16x16x32_bf16 v[48:51], v[212:215], v[168:171], v[48:51]
	v_mfma_f32_16x16x32_bf16 v[36:39], v[204:207], v[176:179], v[36:39]
	v_mfma_f32_16x16x32_bf16 v[32:35], v[212:215], v[176:179], v[32:35]
	v_mfma_f32_16x16x32_bf16 v[20:23], v[204:207], v[184:187], v[20:23]
	v_mfma_f32_16x16x32_bf16 v[16:19], v[212:215], v[184:187], v[16:19]
	v_mfma_f32_16x16x32_bf16 v[4:7], v[204:207], v[192:195], v[4:7]
	v_mfma_f32_16x16x32_bf16 v[0:3], v[212:215], v[192:195], v[0:3]
	v_mfma_f32_16x16x32_bf16 v[52:55], v[208:211], v[172:175], v[52:55]
	v_mfma_f32_16x16x32_bf16 v[48:51], v[216:219], v[172:175], v[48:51]
	v_mfma_f32_16x16x32_bf16 v[36:39], v[208:211], v[180:183], v[36:39]
	v_mfma_f32_16x16x32_bf16 v[32:35], v[216:219], v[180:183], v[32:35]
	v_mfma_f32_16x16x32_bf16 v[20:23], v[208:211], v[188:191], v[20:23]
	v_mfma_f32_16x16x32_bf16 v[16:19], v[216:219], v[188:191], v[16:19]
	v_mfma_f32_16x16x32_bf16 v[4:7], v[208:211], v[200:203], v[4:7]
	v_mfma_f32_16x16x32_bf16 v[0:3], v[216:219], v[200:203], v[0:3]
	s_setprio 0
	s_add_i32 s44, s44, 2
	s_add_u32 s38, s38, 0x100
	s_addc_u32 s39, s39, 0
	s_add_u32 s18, s18, 0x100
	s_addc_u32 s19, s19, 0
	s_cmp_gt_u32 s44, 13
	s_barrier
	s_cbranch_scc0 .LBB0_495
	v_add_u32_e32 v144, s71, v154
	v_ashrrev_i32_e32 v145, 31, v144
	v_lshl_add_u64 v[146:147], v[144:145], 2, s[94:95]
	v_add_co_u32_e32 v148, vcc, 0x40000, v146
	s_ashr_i32 s18, s70, 7
	s_nop 0
	v_addc_co_u32_e32 v149, vcc, 0, v147, vcc
	v_add_co_u32_e32 v150, vcc, 0x80000, v146
	s_ashr_i32 s19, s18, 31
	s_nop 0
	v_addc_co_u32_e32 v151, vcc, 0, v147, vcc
	v_add_co_u32_e32 v152, vcc, 0xc0000, v146
	s_lshl_b64 s[18:19], s[18:19], 23
	s_nop 0
	v_addc_co_u32_e32 v153, vcc, 0, v147, vcc
	s_nop 1
	v_mov_b32_e32 v160, v232
	v_mov_b32_e32 v162, v233
	v_mov_b32_e32 v161, v234
	v_mov_b32_e32 v163, v235
	global_load_dword v168, v[146:147], off offset:576
	global_load_dword v169, v[148:149], off offset:576
	global_load_dword v170, v[150:151], off offset:576
	global_load_dword v171, v[152:153], off offset:576
	global_load_dword v172, v[146:147], off offset:640
	global_load_dword v173, v[148:149], off offset:640
	global_load_dword v174, v[150:151], off offset:640
	global_load_dword v175, v[152:153], off offset:640
	global_load_dword v176, v[146:147], off offset:704
	global_load_dword v177, v[148:149], off offset:704
	global_load_dword v178, v[150:151], off offset:704
	global_load_dword v179, v[152:153], off offset:704
	s_add_u32 s38, s92, s18
	s_addc_u32 s39, s93, s19
	v_lshlrev_b64 v[144:145], 8, v[144:145]
	s_add_u32 s40, s38, 0x800000
	v_lshl_add_u64 v[164:165], s[38:39], 0, v[144:145]
	s_addc_u32 s41, s39, 0
	v_lshl_add_u64 v[164:165], v[164:165], 0, s[8:9]
	v_lshl_add_u64 v[164:165], v[164:165], 0, v[136:137]
	s_mov_b64 s[18:19], 0x1000
	s_mov_b32 s70, s68
	s_mov_b32 s71, s69
	s_mov_b64 s[44:45], s[36:37]
	s_mov_b64 s[42:43], s[34:35]
	s_nop 0
	v_pk_add_f32 v[160:161], v[160:161], v[162:163]
	s_nop 0
	v_add_f32_e32 v160, v160, v161
	v_fmamk_f32 v160, v160, 0x3a800000, v159
	v_mul_f32_e32 v161, 0x4b800000, v160
	v_cmp_gt_f32_e32 vcc, s66, v160
	s_nop 1
	v_cndmask_b32_e32 v160, v160, v161, vcc
	v_rsq_f32_e32 v162, v160
	v_lshl_add_u64 v[160:161], s[40:41], 0, v[144:145]
	v_lshl_add_u64 v[160:161], v[160:161], 0, s[8:9]
	v_lshl_add_u64 v[160:161], v[160:161], 0, v[136:137]
	v_mul_f32_e32 v163, 0x45800000, v162
	v_cndmask_b32_e32 v162, v162, v163, vcc
	v_pk_mul_f32 v[126:127], v[126:127], v[162:163] op_sel_hi:[1,0]
	v_pk_mul_f32 v[124:125], v[124:125], v[162:163] op_sel_hi:[1,0]
	v_pk_mul_f32 v[122:123], v[122:123], v[162:163] op_sel_hi:[1,0]
	v_pk_mul_f32 v[120:121], v[120:121], v[162:163] op_sel_hi:[1,0]
	v_pk_mul_f32 v[118:119], v[118:119], v[162:163] op_sel_hi:[1,0]
	v_pk_mul_f32 v[116:117], v[116:117], v[162:163] op_sel_hi:[1,0]
	v_pk_mul_f32 v[166:167], v[114:115], v[162:163] op_sel_hi:[1,0]
	v_pk_mul_f32 v[162:163], v[112:113], v[162:163] op_sel_hi:[1,0]
	v_cvt_pk_bf16_f32 v112, v124, v125
	v_cvt_pk_bf16_f32 v113, v126, v127
	v_cvt_pk_bf16_f32 v114, v120, v121
	v_cvt_pk_bf16_f32 v115, v122, v123
	v_cvt_pk_bf16_f32 v116, v116, v117
	v_cvt_pk_bf16_f32 v117, v118, v119
	s_nop 0
	v_cvt_pk_bf16_f32 v118, v162, v163
	v_cvt_pk_bf16_f32 v119, v166, v167
	global_store_dwordx4 v[164:165], v[112:115], off
	global_store_dwordx4 v[160:161], v[116:119], off
	s_nop 1
	v_mov_b32_e32 v112, v236
	s_nop 0
	v_mov_b32_e32 v114, v237
	v_mov_b32_e32 v113, v238
	v_mov_b32_e32 v115, v239
	v_lshl_add_u64 v[116:117], v[144:145], 0, s[18:19]
	v_lshl_add_u64 v[118:119], s[38:39], 0, v[116:117]
	v_lshl_add_u64 v[118:119], v[118:119], 0, s[8:9]
	v_lshl_add_u64 v[118:119], v[118:119], 0, v[136:137]
	s_mov_b64 s[18:19], 0x2000
	s_nop 0
	v_pk_add_f32 v[112:113], v[112:113], v[114:115]
	s_nop 0
	v_add_f32_e32 v112, v112, v113
	v_fmamk_f32 v112, v112, 0x3a800000, v159
	v_mul_f32_e32 v113, 0x4b800000, v112
	v_cmp_gt_f32_e32 vcc, s66, v112
	s_nop 1
	v_cndmask_b32_e32 v112, v112, v113, vcc
	v_rsq_f32_e32 v114, v112
	v_lshl_add_u64 v[112:113], s[40:41], 0, v[116:117]
	v_lshl_add_u64 v[112:113], v[112:113], 0, s[8:9]
	v_lshl_add_u64 v[112:113], v[112:113], 0, v[136:137]
	v_mul_f32_e32 v115, 0x45800000, v114
	v_cndmask_b32_e32 v114, v114, v115, vcc
	v_pk_mul_f32 v[110:111], v[110:111], v[114:115] op_sel_hi:[1,0]
	v_pk_mul_f32 v[108:109], v[108:109], v[114:115] op_sel_hi:[1,0]
	v_pk_mul_f32 v[106:107], v[106:107], v[114:115] op_sel_hi:[1,0]
	v_pk_mul_f32 v[104:105], v[104:105], v[114:115] op_sel_hi:[1,0]
	v_pk_mul_f32 v[102:103], v[102:103], v[114:115] op_sel_hi:[1,0]
	v_pk_mul_f32 v[100:101], v[100:101], v[114:115] op_sel_hi:[1,0]
	v_pk_mul_f32 v[116:117], v[98:99], v[114:115] op_sel_hi:[1,0]
	v_pk_mul_f32 v[114:115], v[96:97], v[114:115] op_sel_hi:[1,0]
	v_cvt_pk_bf16_f32 v96, v108, v109
	v_cvt_pk_bf16_f32 v97, v110, v111
	v_cvt_pk_bf16_f32 v98, v104, v105
	v_cvt_pk_bf16_f32 v99, v106, v107
	v_cvt_pk_bf16_f32 v100, v100, v101
	v_cvt_pk_bf16_f32 v101, v102, v103
	s_nop 0
	v_cvt_pk_bf16_f32 v102, v114, v115
	v_cvt_pk_bf16_f32 v103, v116, v117
	global_store_dwordx4 v[118:119], v[96:99], off
	global_store_dwordx4 v[112:113], v[100:103], off
	s_nop 1
	v_mov_b32_e32 v96, v240
	s_nop 0
	v_mov_b32_e32 v98, v241
	v_mov_b32_e32 v97, v242
	v_mov_b32_e32 v99, v243
	v_lshl_add_u64 v[100:101], v[144:145], 0, s[18:19]
	v_lshl_add_u64 v[102:103], s[38:39], 0, v[100:101]
	v_lshl_add_u64 v[102:103], v[102:103], 0, s[8:9]
	v_lshl_add_u64 v[102:103], v[102:103], 0, v[136:137]
	s_nop 0
	v_pk_add_f32 v[96:97], v[96:97], v[98:99]
	s_nop 0
	v_add_f32_e32 v96, v96, v97
	v_fmamk_f32 v96, v96, 0x3a800000, v159
	v_mul_f32_e32 v97, 0x4b800000, v96
	v_cmp_gt_f32_e32 vcc, s66, v96
	s_nop 1
	v_cndmask_b32_e32 v96, v96, v97, vcc
	v_rsq_f32_e32 v98, v96
	v_lshl_add_u64 v[96:97], s[40:41], 0, v[100:101]
	v_lshl_add_u64 v[96:97], v[96:97], 0, s[8:9]
	v_lshl_add_u64 v[96:97], v[96:97], 0, v[136:137]
	v_mul_f32_e32 v99, 0x45800000, v98
	v_cndmask_b32_e32 v98, v98, v99, vcc
	v_pk_mul_f32 v[94:95], v[94:95], v[98:99] op_sel_hi:[1,0]
	v_pk_mul_f32 v[92:93], v[92:93], v[98:99] op_sel_hi:[1,0]
	v_pk_mul_f32 v[90:91], v[90:91], v[98:99] op_sel_hi:[1,0]
	v_pk_mul_f32 v[88:89], v[88:89], v[98:99] op_sel_hi:[1,0]
	v_pk_mul_f32 v[86:87], v[86:87], v[98:99] op_sel_hi:[1,0]
	v_pk_mul_f32 v[84:85], v[84:85], v[98:99] op_sel_hi:[1,0]
	v_pk_mul_f32 v[100:101], v[82:83], v[98:99] op_sel_hi:[1,0]
	v_pk_mul_f32 v[98:99], v[80:81], v[98:99] op_sel_hi:[1,0]
	v_cvt_pk_bf16_f32 v80, v92, v93
	v_cvt_pk_bf16_f32 v81, v94, v95
	v_cvt_pk_bf16_f32 v82, v88, v89
	v_cvt_pk_bf16_f32 v83, v90, v91
	v_cvt_pk_bf16_f32 v84, v84, v85
	v_cvt_pk_bf16_f32 v85, v86, v87
	s_nop 0
	v_cvt_pk_bf16_f32 v86, v98, v99
	v_cvt_pk_bf16_f32 v87, v100, v101
	global_store_dwordx4 v[102:103], v[80:83], off
	global_store_dwordx4 v[96:97], v[84:87], off
	s_nop 1
	v_mov_b32_e32 v80, v244
	s_nop 0
	v_mov_b32_e32 v82, v245
	v_mov_b32_e32 v81, v246
	v_mov_b32_e32 v83, v247
	v_lshl_add_u64 v[84:85], v[144:145], 0, s[10:11]
	v_lshl_add_u64 v[86:87], s[38:39], 0, v[84:85]
	v_lshl_add_u64 v[86:87], v[86:87], 0, s[8:9]
	v_lshl_add_u64 v[86:87], v[86:87], 0, v[136:137]
	s_nop 0
	v_pk_add_f32 v[80:81], v[80:81], v[82:83]
	s_nop 0
	v_add_f32_e32 v80, v80, v81
	v_fmamk_f32 v80, v80, 0x3a800000, v159
	v_mul_f32_e32 v81, 0x4b800000, v80
	v_cmp_gt_f32_e32 vcc, s66, v80
	s_nop 1
	v_cndmask_b32_e32 v80, v80, v81, vcc
	v_rsq_f32_e32 v82, v80
	v_lshl_add_u64 v[80:81], s[40:41], 0, v[84:85]
	v_lshl_add_u64 v[80:81], v[80:81], 0, s[8:9]
	v_lshl_add_u64 v[80:81], v[80:81], 0, v[136:137]
	v_mul_f32_e32 v83, 0x45800000, v82
	v_cndmask_b32_e32 v82, v82, v83, vcc
	v_pk_mul_f32 v[78:79], v[78:79], v[82:83] op_sel_hi:[1,0]
	v_pk_mul_f32 v[76:77], v[76:77], v[82:83] op_sel_hi:[1,0]
	v_pk_mul_f32 v[74:75], v[74:75], v[82:83] op_sel_hi:[1,0]
	v_pk_mul_f32 v[72:73], v[72:73], v[82:83] op_sel_hi:[1,0]
	v_pk_mul_f32 v[70:71], v[70:71], v[82:83] op_sel_hi:[1,0]
	v_pk_mul_f32 v[68:69], v[68:69], v[82:83] op_sel_hi:[1,0]
	v_pk_mul_f32 v[84:85], v[66:67], v[82:83] op_sel_hi:[1,0]
	v_pk_mul_f32 v[82:83], v[64:65], v[82:83] op_sel_hi:[1,0]
	v_cvt_pk_bf16_f32 v64, v76, v77
	v_cvt_pk_bf16_f32 v65, v78, v79
	v_cvt_pk_bf16_f32 v66, v72, v73
	v_cvt_pk_bf16_f32 v67, v74, v75
	v_cvt_pk_bf16_f32 v68, v68, v69
	v_cvt_pk_bf16_f32 v69, v70, v71
	s_nop 0
	v_cvt_pk_bf16_f32 v70, v82, v83
	v_cvt_pk_bf16_f32 v71, v84, v85
	global_store_dwordx4 v[86:87], v[64:67], off
	global_store_dwordx4 v[80:81], v[68:71], off
	s_nop 1
	v_mov_b32_e32 v64, v248
	s_nop 0
	v_mov_b32_e32 v66, v249
	v_mov_b32_e32 v65, v250
	v_mov_b32_e32 v67, v251
	v_lshl_add_u64 v[68:69], v[144:145], 0, s[24:25]
	v_lshl_add_u64 v[70:71], s[38:39], 0, v[68:69]
	v_lshl_add_u64 v[70:71], v[70:71], 0, s[8:9]
	v_lshl_add_u64 v[70:71], v[70:71], 0, v[136:137]
	s_nop 0
	v_pk_add_f32 v[64:65], v[64:65], v[66:67]
	s_nop 0
	v_add_f32_e32 v64, v64, v65
	v_fmamk_f32 v64, v64, 0x3a800000, v159
	v_mul_f32_e32 v65, 0x4b800000, v64
	v_cmp_gt_f32_e32 vcc, s66, v64
	s_nop 1
	v_cndmask_b32_e32 v64, v64, v65, vcc
	v_rsq_f32_e32 v66, v64
	v_lshl_add_u64 v[64:65], s[40:41], 0, v[68:69]
	v_lshl_add_u64 v[64:65], v[64:65], 0, s[8:9]
	v_lshl_add_u64 v[64:65], v[64:65], 0, v[136:137]
	v_mul_f32_e32 v67, 0x45800000, v66
	v_cndmask_b32_e32 v66, v66, v67, vcc
	v_pk_mul_f32 v[62:63], v[62:63], v[66:67] op_sel_hi:[1,0]
	v_pk_mul_f32 v[60:61], v[60:61], v[66:67] op_sel_hi:[1,0]
	v_pk_mul_f32 v[58:59], v[58:59], v[66:67] op_sel_hi:[1,0]
	v_pk_mul_f32 v[56:57], v[56:57], v[66:67] op_sel_hi:[1,0]
	v_pk_mul_f32 v[54:55], v[54:55], v[66:67] op_sel_hi:[1,0]
	v_pk_mul_f32 v[52:53], v[52:53], v[66:67] op_sel_hi:[1,0]
	v_pk_mul_f32 v[68:69], v[50:51], v[66:67] op_sel_hi:[1,0]
	v_pk_mul_f32 v[66:67], v[48:49], v[66:67] op_sel_hi:[1,0]
	v_cvt_pk_bf16_f32 v48, v60, v61
	v_cvt_pk_bf16_f32 v49, v62, v63
	v_cvt_pk_bf16_f32 v50, v56, v57
	v_cvt_pk_bf16_f32 v51, v58, v59
	v_cvt_pk_bf16_f32 v52, v52, v53
	v_cvt_pk_bf16_f32 v53, v54, v55
	s_nop 0
	v_cvt_pk_bf16_f32 v54, v66, v67
	v_cvt_pk_bf16_f32 v55, v68, v69
	global_store_dwordx4 v[70:71], v[48:51], off
	global_store_dwordx4 v[64:65], v[52:55], off
	s_waitcnt vmcnt(10)
	s_nop 1
	v_mov_b32_e32 v48, v168
	s_nop 0
	v_mov_b32_e32 v50, v169
	v_mov_b32_e32 v49, v170
	v_mov_b32_e32 v51, v171
	v_lshl_add_u64 v[52:53], v[144:145], 0, s[26:27]
	v_lshl_add_u64 v[54:55], s[38:39], 0, v[52:53]
	v_lshl_add_u64 v[54:55], v[54:55], 0, s[8:9]
	v_lshl_add_u64 v[54:55], v[54:55], 0, v[136:137]
	s_nop 0
	v_pk_add_f32 v[48:49], v[48:49], v[50:51]
	s_nop 0
	v_add_f32_e32 v48, v48, v49
	v_fmamk_f32 v48, v48, 0x3a800000, v159
	v_mul_f32_e32 v49, 0x4b800000, v48
	v_cmp_gt_f32_e32 vcc, s66, v48
	s_nop 1
	v_cndmask_b32_e32 v48, v48, v49, vcc
	v_rsq_f32_e32 v50, v48
	v_lshl_add_u64 v[48:49], s[40:41], 0, v[52:53]
	v_lshl_add_u64 v[48:49], v[48:49], 0, s[8:9]
	v_lshl_add_u64 v[48:49], v[48:49], 0, v[136:137]
	v_mul_f32_e32 v51, 0x45800000, v50
	v_cndmask_b32_e32 v50, v50, v51, vcc
	v_pk_mul_f32 v[46:47], v[46:47], v[50:51] op_sel_hi:[1,0]
	v_pk_mul_f32 v[44:45], v[44:45], v[50:51] op_sel_hi:[1,0]
	v_pk_mul_f32 v[42:43], v[42:43], v[50:51] op_sel_hi:[1,0]
	v_pk_mul_f32 v[40:41], v[40:41], v[50:51] op_sel_hi:[1,0]
	v_pk_mul_f32 v[38:39], v[38:39], v[50:51] op_sel_hi:[1,0]
	v_pk_mul_f32 v[36:37], v[36:37], v[50:51] op_sel_hi:[1,0]
	v_pk_mul_f32 v[52:53], v[34:35], v[50:51] op_sel_hi:[1,0]
	v_pk_mul_f32 v[50:51], v[32:33], v[50:51] op_sel_hi:[1,0]
	v_cvt_pk_bf16_f32 v32, v44, v45
	v_cvt_pk_bf16_f32 v33, v46, v47
	v_cvt_pk_bf16_f32 v34, v40, v41
	v_cvt_pk_bf16_f32 v35, v42, v43
	v_cvt_pk_bf16_f32 v36, v36, v37
	v_cvt_pk_bf16_f32 v37, v38, v39
	s_nop 0
	v_cvt_pk_bf16_f32 v38, v50, v51
	v_cvt_pk_bf16_f32 v39, v52, v53
	global_store_dwordx4 v[54:55], v[32:35], off
	global_store_dwordx4 v[48:49], v[36:39], off
	s_nop 1
	v_mov_b32_e32 v32, v172
	s_nop 0
	v_mov_b32_e32 v34, v173
	v_mov_b32_e32 v33, v174
	v_mov_b32_e32 v35, v175
	v_lshl_add_u64 v[36:37], v[144:145], 0, s[28:29]
	v_lshl_add_u64 v[38:39], s[38:39], 0, v[36:37]
	v_lshl_add_u64 v[38:39], v[38:39], 0, s[8:9]
	v_lshl_add_u64 v[38:39], v[38:39], 0, v[136:137]
	s_nop 0
	v_pk_add_f32 v[32:33], v[32:33], v[34:35]
	s_nop 0
	v_add_f32_e32 v32, v32, v33
	v_fmamk_f32 v32, v32, 0x3a800000, v159
	v_mul_f32_e32 v33, 0x4b800000, v32
	v_cmp_gt_f32_e32 vcc, s66, v32
	s_nop 1
	v_cndmask_b32_e32 v32, v32, v33, vcc
	v_rsq_f32_e32 v34, v32
	v_lshl_add_u64 v[32:33], s[40:41], 0, v[36:37]
	v_lshl_add_u64 v[32:33], v[32:33], 0, s[8:9]
	v_lshl_add_u64 v[32:33], v[32:33], 0, v[136:137]
	v_mul_f32_e32 v35, 0x45800000, v34
	v_cndmask_b32_e32 v34, v34, v35, vcc
	v_pk_mul_f32 v[30:31], v[30:31], v[34:35] op_sel_hi:[1,0]
	v_pk_mul_f32 v[28:29], v[28:29], v[34:35] op_sel_hi:[1,0]
	v_pk_mul_f32 v[26:27], v[26:27], v[34:35] op_sel_hi:[1,0]
	v_pk_mul_f32 v[24:25], v[24:25], v[34:35] op_sel_hi:[1,0]
	v_pk_mul_f32 v[22:23], v[22:23], v[34:35] op_sel_hi:[1,0]
	v_pk_mul_f32 v[20:21], v[20:21], v[34:35] op_sel_hi:[1,0]
	v_pk_mul_f32 v[36:37], v[18:19], v[34:35] op_sel_hi:[1,0]
	v_pk_mul_f32 v[34:35], v[16:17], v[34:35] op_sel_hi:[1,0]
	v_cvt_pk_bf16_f32 v16, v28, v29
	v_cvt_pk_bf16_f32 v17, v30, v31
	v_cvt_pk_bf16_f32 v18, v24, v25
	v_cvt_pk_bf16_f32 v19, v26, v27
	v_cvt_pk_bf16_f32 v20, v20, v21
	v_cvt_pk_bf16_f32 v21, v22, v23
	s_nop 0
	v_cvt_pk_bf16_f32 v22, v34, v35
	v_cvt_pk_bf16_f32 v23, v36, v37
	global_store_dwordx4 v[38:39], v[16:19], off
	global_store_dwordx4 v[32:33], v[20:23], off
	s_nop 1
	v_mov_b32_e32 v16, v176
	s_nop 0
	v_mov_b32_e32 v18, v177
	v_mov_b32_e32 v17, v178
	v_mov_b32_e32 v19, v179
	s_and_b64 vcc, exec, s[2:3]
	v_lshl_add_u64 v[20:21], v[144:145], 0, s[30:31]
	v_lshl_add_u64 v[22:23], s[38:39], 0, v[20:21]
	v_lshl_add_u64 v[22:23], v[22:23], 0, s[8:9]
	v_lshl_add_u64 v[22:23], v[22:23], 0, v[136:137]
	s_nop 0
	v_pk_add_f32 v[16:17], v[16:17], v[18:19]
	s_nop 0
	v_add_f32_e32 v16, v16, v17
	v_fmamk_f32 v16, v16, 0x3a800000, v159
	v_mul_f32_e32 v17, 0x4b800000, v16
	v_cmp_gt_f32_e64 s[2:3], s66, v16
	s_nop 1
	v_cndmask_b32_e64 v16, v16, v17, s[2:3]
	v_rsq_f32_e32 v18, v16
	v_lshl_add_u64 v[16:17], s[40:41], 0, v[20:21]
	v_lshl_add_u64 v[16:17], v[16:17], 0, s[8:9]
	v_lshl_add_u64 v[16:17], v[16:17], 0, v[136:137]
	v_mul_f32_e32 v19, 0x45800000, v18
	v_cndmask_b32_e64 v18, v18, v19, s[2:3]
	v_pk_mul_f32 v[14:15], v[14:15], v[18:19] op_sel_hi:[1,0]
	v_pk_mul_f32 v[12:13], v[12:13], v[18:19] op_sel_hi:[1,0]
	v_pk_mul_f32 v[10:11], v[10:11], v[18:19] op_sel_hi:[1,0]
	v_pk_mul_f32 v[8:9], v[8:9], v[18:19] op_sel_hi:[1,0]
	v_pk_mul_f32 v[6:7], v[6:7], v[18:19] op_sel_hi:[1,0]
	v_pk_mul_f32 v[4:5], v[4:5], v[18:19] op_sel_hi:[1,0]
	v_pk_mul_f32 v[20:21], v[2:3], v[18:19] op_sel_hi:[1,0]
	v_pk_mul_f32 v[18:19], v[0:1], v[18:19] op_sel_hi:[1,0]
	v_cvt_pk_bf16_f32 v0, v12, v13
	v_cvt_pk_bf16_f32 v1, v14, v15
	v_cvt_pk_bf16_f32 v2, v8, v9
	v_cvt_pk_bf16_f32 v3, v10, v11
	v_cvt_pk_bf16_f32 v4, v4, v5
	v_cvt_pk_bf16_f32 v5, v6, v7
	s_nop 0
	v_cvt_pk_bf16_f32 v6, v18, v19
	v_cvt_pk_bf16_f32 v7, v20, v21
	global_store_dwordx4 v[22:23], v[0:3], off
	global_store_dwordx4 v[16:17], v[4:7], off
	s_cbranch_vccz .LBB0_492
	s_waitcnt vmcnt(0)
	s_cmpk_gt_u32 s33, 0xff
	s_cbranch_scc1 .LBB0_499
	s_barrier

.LBB0_666:
	v_add_u32_e32 v226, s74, v154
	v_ashrrev_i32_e32 v227, 31, v226
	v_lshl_add_u64 v[228:229], v[226:227], 2, s[94:95]
	global_load_dword v232, v[228:229], off
	v_add_u32_e32 v226, s74, v154
	v_ashrrev_i32_e32 v227, 31, v226
	v_lshl_add_u64 v[228:229], v[226:227], 2, s[94:95]
	s_mov_b32 s98, 0x40000
	s_mov_b32 s99, 0
	v_lshl_add_u64 v[230:231], v[228:229], 0, s[98:99]
	global_load_dword v233, v[230:231], off
	v_add_u32_e32 v226, s74, v154
	v_ashrrev_i32_e32 v227, 31, v226
	v_lshl_add_u64 v[228:229], v[226:227], 2, s[94:95]
	s_mov_b32 s98, 0x80000
	s_mov_b32 s99, 0
	v_lshl_add_u64 v[230:231], v[228:229], 0, s[98:99]
	global_load_dword v234, v[230:231], off
	v_add_u32_e32 v226, s74, v154
	v_ashrrev_i32_e32 v227, 31, v226
	v_lshl_add_u64 v[228:229], v[226:227], 2, s[94:95]
	s_mov_b32 s98, 0xc0000
	s_mov_b32 s99, 0
	v_lshl_add_u64 v[230:231], v[228:229], 0, s[98:99]
	global_load_dword v235, v[230:231], off
	v_add_u32_e32 v226, s74, v154
	v_ashrrev_i32_e32 v227, 31, v226
	v_lshl_add_u64 v[228:229], v[226:227], 2, s[94:95]
	global_load_dword v236, v[228:229], off offset:64
	v_add_u32_e32 v226, s74, v154
	v_ashrrev_i32_e32 v227, 31, v226
	v_lshl_add_u64 v[228:229], v[226:227], 2, s[94:95]
	s_mov_b32 s98, 0x40000
	s_mov_b32 s99, 0
	v_lshl_add_u64 v[230:231], v[228:229], 0, s[98:99]
	global_load_dword v237, v[230:231], off offset:64
	v_add_u32_e32 v226, s74, v154
	v_ashrrev_i32_e32 v227, 31, v226
	v_lshl_add_u64 v[228:229], v[226:227], 2, s[94:95]
	s_mov_b32 s98, 0x80000
	s_mov_b32 s99, 0
	v_lshl_add_u64 v[230:231], v[228:229], 0, s[98:99]
	global_load_dword v238, v[230:231], off offset:64
	v_add_u32_e32 v226, s74, v154
	v_ashrrev_i32_e32 v227, 31, v226
	v_lshl_add_u64 v[228:229], v[226:227], 2, s[94:95]
	s_mov_b32 s98, 0xc0000
	s_mov_b32 s99, 0
	v_lshl_add_u64 v[230:231], v[228:229], 0, s[98:99]
	global_load_dword v239, v[230:231], off offset:64
	v_add_u32_e32 v226, s74, v154
	v_ashrrev_i32_e32 v227, 31, v226
	v_lshl_add_u64 v[228:229], v[226:227], 2, s[94:95]
	global_load_dword v240, v[228:229], off offset:128
	v_add_u32_e32 v226, s74, v154
	v_ashrrev_i32_e32 v227, 31, v226
	v_lshl_add_u64 v[228:229], v[226:227], 2, s[94:95]
	s_mov_b32 s98, 0x40000
	s_mov_b32 s99, 0
	v_lshl_add_u64 v[230:231], v[228:229], 0, s[98:99]
	global_load_dword v241, v[230:231], off offset:128
	v_add_u32_e32 v226, s74, v154
	v_ashrrev_i32_e32 v227, 31, v226
	v_lshl_add_u64 v[228:229], v[226:227], 2, s[94:95]
	s_mov_b32 s98, 0x80000
	s_mov_b32 s99, 0
	v_lshl_add_u64 v[230:231], v[228:229], 0, s[98:99]
	global_load_dword v242, v[230:231], off offset:128
	v_add_u32_e32 v226, s74, v154
	v_ashrrev_i32_e32 v227, 31, v226
	v_lshl_add_u64 v[228:229], v[226:227], 2, s[94:95]
	s_mov_b32 s98, 0xc0000
	s_mov_b32 s99, 0
	v_lshl_add_u64 v[230:231], v[228:229], 0, s[98:99]
	global_load_dword v243, v[230:231], off offset:128
	v_add_u32_e32 v226, s74, v154
	v_ashrrev_i32_e32 v227, 31, v226
	v_lshl_add_u64 v[228:229], v[226:227], 2, s[94:95]
	global_load_dword v244, v[228:229], off offset:192
	v_add_u32_e32 v226, s74, v154
	v_ashrrev_i32_e32 v227, 31, v226
	v_lshl_add_u64 v[228:229], v[226:227], 2, s[94:95]
	s_mov_b32 s98, 0x40000
	s_mov_b32 s99, 0
	v_lshl_add_u64 v[230:231], v[228:229], 0, s[98:99]
	global_load_dword v245, v[230:231], off offset:192
	v_add_u32_e32 v226, s74, v154
	v_ashrrev_i32_e32 v227, 31, v226
	v_lshl_add_u64 v[228:229], v[226:227], 2, s[94:95]
	s_mov_b32 s98, 0x80000
	s_mov_b32 s99, 0
	v_lshl_add_u64 v[230:231], v[228:229], 0, s[98:99]
	global_load_dword v246, v[230:231], off offset:192
	v_add_u32_e32 v226, s74, v154
	v_ashrrev_i32_e32 v227, 31, v226
	v_lshl_add_u64 v[228:229], v[226:227], 2, s[94:95]
	s_mov_b32 s98, 0xc0000
	s_mov_b32 s99, 0
	v_lshl_add_u64 v[230:231], v[228:229], 0, s[98:99]
	global_load_dword v247, v[230:231], off offset:192
	v_add_u32_e32 v226, s74, v154
	v_ashrrev_i32_e32 v227, 31, v226
	v_lshl_add_u64 v[228:229], v[226:227], 2, s[94:95]
	global_load_dword v248, v[228:229], off offset:512
	v_add_u32_e32 v226, s74, v154
	v_ashrrev_i32_e32 v227, 31, v226
	v_lshl_add_u64 v[228:229], v[226:227], 2, s[94:95]
	s_mov_b32 s98, 0x40000
	s_mov_b32 s99, 0
	v_lshl_add_u64 v[230:231], v[228:229], 0, s[98:99]
	global_load_dword v249, v[230:231], off offset:512
	v_add_u32_e32 v226, s74, v154
	v_ashrrev_i32_e32 v227, 31, v226
	v_lshl_add_u64 v[228:229], v[226:227], 2, s[94:95]
	s_mov_b32 s98, 0x80000
	s_mov_b32 s99, 0
	v_lshl_add_u64 v[230:231], v[228:229], 0, s[98:99]
	global_load_dword v250, v[230:231], off offset:512
	v_add_u32_e32 v226, s74, v154
	v_ashrrev_i32_e32 v227, 31, v226
	v_lshl_add_u64 v[228:229], v[226:227], 2, s[94:95]
	s_mov_b32 s98, 0xc0000
	s_mov_b32 s99, 0
	v_lshl_add_u64 v[230:231], v[228:229], 0, s[98:99]
	global_load_dword v251, v[230:231], off offset:512
	s_add_u32 s40, s44, 0x40080
	s_addc_u32 s41, s45, 0
	s_add_u32 s18, s46, 0x100
	v_mov_b32_e32 v0, 0
	s_addc_u32 s19, s47, 0
	s_mov_b32 s46, -2
	v_mov_b32_e32 v1, v0
	v_mov_b32_e32 v2, v0
	v_mov_b32_e32 v3, v0
	v_mov_b32_e32 v4, v0
	v_mov_b32_e32 v5, v0
	v_mov_b32_e32 v6, v0
	v_mov_b32_e32 v7, v0
	v_mov_b32_e32 v16, v0
	v_mov_b32_e32 v17, v0
	v_mov_b32_e32 v18, v0
	v_mov_b32_e32 v19, v0
	v_mov_b32_e32 v20, v0
	v_mov_b32_e32 v21, v0
	v_mov_b32_e32 v22, v0
	v_mov_b32_e32 v23, v0
	v_mov_b32_e32 v32, v0
	v_mov_b32_e32 v33, v0
	v_mov_b32_e32 v34, v0
	v_mov_b32_e32 v35, v0
	v_mov_b32_e32 v36, v0
	v_mov_b32_e32 v37, v0
	v_mov_b32_e32 v38, v0
	v_mov_b32_e32 v39, v0
	v_mov_b32_e32 v48, v0
	v_mov_b32_e32 v49, v0
	v_mov_b32_e32 v50, v0
	v_mov_b32_e32 v51, v0
	v_mov_b32_e32 v52, v0
	v_mov_b32_e32 v53, v0
	v_mov_b32_e32 v54, v0
	v_mov_b32_e32 v55, v0
	v_mov_b32_e32 v8, v0
	v_mov_b32_e32 v9, v0
	v_mov_b32_e32 v10, v0
	v_mov_b32_e32 v11, v0
	v_mov_b32_e32 v12, v0
	v_mov_b32_e32 v13, v0
	v_mov_b32_e32 v14, v0
	v_mov_b32_e32 v15, v0
	v_mov_b32_e32 v24, v0
	v_mov_b32_e32 v25, v0
	v_mov_b32_e32 v26, v0
	v_mov_b32_e32 v27, v0
	v_mov_b32_e32 v28, v0
	v_mov_b32_e32 v29, v0
	v_mov_b32_e32 v30, v0
	v_mov_b32_e32 v31, v0
	v_mov_b32_e32 v40, v0
	v_mov_b32_e32 v41, v0
	v_mov_b32_e32 v42, v0
	v_mov_b32_e32 v43, v0
	v_mov_b32_e32 v44, v0
	v_mov_b32_e32 v45, v0
	v_mov_b32_e32 v46, v0
	v_mov_b32_e32 v47, v0
	v_mov_b32_e32 v56, v0
	v_mov_b32_e32 v57, v0
	v_mov_b32_e32 v58, v0
	v_mov_b32_e32 v59, v0
	v_mov_b32_e32 v60, v0
	v_mov_b32_e32 v61, v0
	v_mov_b32_e32 v62, v0
	v_mov_b32_e32 v63, v0
	v_mov_b32_e32 v64, v0
	v_mov_b32_e32 v65, v0
	v_mov_b32_e32 v66, v0
	v_mov_b32_e32 v67, v0
	v_mov_b32_e32 v68, v0
	v_mov_b32_e32 v69, v0
	v_mov_b32_e32 v70, v0
	v_mov_b32_e32 v71, v0
	v_mov_b32_e32 v80, v0
	v_mov_b32_e32 v81, v0
	v_mov_b32_e32 v82, v0
	v_mov_b32_e32 v83, v0
	v_mov_b32_e32 v84, v0
	v_mov_b32_e32 v85, v0
	v_mov_b32_e32 v86, v0
	v_mov_b32_e32 v87, v0
	v_mov_b32_e32 v96, v0
	v_mov_b32_e32 v97, v0
	v_mov_b32_e32 v98, v0
	v_mov_b32_e32 v99, v0
	v_mov_b32_e32 v100, v0
	v_mov_b32_e32 v101, v0
	v_mov_b32_e32 v102, v0
	v_mov_b32_e32 v103, v0
	v_mov_b32_e32 v112, v0
	v_mov_b32_e32 v113, v0
	v_mov_b32_e32 v114, v0
	v_mov_b32_e32 v115, v0
	v_mov_b32_e32 v116, v0
	v_mov_b32_e32 v117, v0
	v_mov_b32_e32 v118, v0
	v_mov_b32_e32 v119, v0
	v_mov_b32_e32 v72, v0
	v_mov_b32_e32 v73, v0
	v_mov_b32_e32 v74, v0
	v_mov_b32_e32 v75, v0
	v_mov_b32_e32 v76, v0
	v_mov_b32_e32 v77, v0
	v_mov_b32_e32 v78, v0
	v_mov_b32_e32 v79, v0
	v_mov_b32_e32 v88, v0
	v_mov_b32_e32 v89, v0
	v_mov_b32_e32 v90, v0
	v_mov_b32_e32 v91, v0
	v_mov_b32_e32 v92, v0
	v_mov_b32_e32 v93, v0
	v_mov_b32_e32 v94, v0
	v_mov_b32_e32 v95, v0
	v_mov_b32_e32 v104, v0
	v_mov_b32_e32 v105, v0
	v_mov_b32_e32 v106, v0
	v_mov_b32_e32 v107, v0
	v_mov_b32_e32 v108, v0
	v_mov_b32_e32 v109, v0
	v_mov_b32_e32 v110, v0
	v_mov_b32_e32 v111, v0
	v_mov_b32_e32 v120, v0
	v_mov_b32_e32 v121, v0
	v_mov_b32_e32 v122, v0
	v_mov_b32_e32 v123, v0
	v_mov_b32_e32 v124, v0
	v_mov_b32_e32 v125, v0
	v_mov_b32_e32 v126, v0
	v_mov_b32_e32 v127, v0
.LBB0_667:
	ds_read_b128 v[144:147], v156
	ds_read_b128 v[148:151], v156 offset:1024
	ds_read_b128 v[160:163], v156 offset:2048
	ds_read_b128 v[164:167], v156 offset:3072
	s_add_u32 s42, s40, 0xfffc0080
	s_addc_u32 s43, s41, -1
	s_cmp_eq_u32 s46, 12
	s_cselect_b32 s45, s37, s43
	s_cselect_b32 s44, s36, s42
	s_cselect_b32 s43, s39, s19
	s_cselect_b32 s42, s38, s18
	v_lshl_add_u64 v[152:153], s[40:41], 0, v[138:139]
	s_add_i32 m0, s53, 0xc000
	ds_read_b128 v[168:171], v157
	ds_read_b128 v[172:175], v157 offset:1024
	ds_read_b128 v[176:179], v157 offset:2048
	ds_read_b128 v[180:183], v157 offset:3072
	ds_read_b128 v[184:187], v157 offset:4096
	ds_read_b128 v[188:191], v157 offset:5120
	ds_read_b128 v[192:195], v157 offset:6144
	ds_read_b128 v[200:203], v157 offset:7168
	global_load_lds_dwordx4 v[152:153], off
	v_lshl_add_u64 v[152:153], s[40:41], 0, v[140:141]
	s_add_i32 m0, s53, 0xe000
	s_nop 0
	global_load_lds_dwordx4 v[152:153], off
	s_waitcnt lgkmcnt(8)
	s_barrier
	s_waitcnt lgkmcnt(0)
	s_setprio 1
	s_waitcnt lgkmcnt(0)
	v_mfma_f32_16x16x32_bf16 v[124:127], v[144:147], v[168:171], v[124:127]
	v_mfma_f32_16x16x32_bf16 v[120:123], v[160:163], v[168:171], v[120:123]
	v_mfma_f32_16x16x32_bf16 v[108:111], v[144:147], v[176:179], v[108:111]
	v_mfma_f32_16x16x32_bf16 v[104:107], v[160:163], v[176:179], v[104:107]
	v_mfma_f32_16x16x32_bf16 v[92:95], v[144:147], v[184:187], v[92:95]
	v_mfma_f32_16x16x32_bf16 v[88:91], v[160:163], v[184:187], v[88:91]
	v_mfma_f32_16x16x32_bf16 v[76:79], v[144:147], v[192:195], v[76:79]
	v_mfma_f32_16x16x32_bf16 v[72:75], v[160:163], v[192:195], v[72:75]
	v_mfma_f32_16x16x32_bf16 v[124:127], v[148:151], v[172:175], v[124:127]
	v_mfma_f32_16x16x32_bf16 v[120:123], v[164:167], v[172:175], v[120:123]
	v_mfma_f32_16x16x32_bf16 v[108:111], v[148:151], v[180:183], v[108:111]
	v_mfma_f32_16x16x32_bf16 v[104:107], v[164:167], v[180:183], v[104:107]
	v_mfma_f32_16x16x32_bf16 v[92:95], v[148:151], v[188:191], v[92:95]
	v_mfma_f32_16x16x32_bf16 v[88:91], v[164:167], v[188:191], v[88:91]
	v_mfma_f32_16x16x32_bf16 v[76:79], v[148:151], v[200:203], v[76:79]
	v_mfma_f32_16x16x32_bf16 v[72:75], v[164:167], v[200:203], v[72:75]
	s_setprio 0
	s_barrier
	s_add_i32 s47, s67, s50
	v_lshl_add_u64 v[152:153], s[42:43], 0, v[132:133]
	s_mov_b32 m0, s47
	ds_read_b128 v[204:207], v158
	ds_read_b128 v[208:211], v158 offset:1024
	ds_read_b128 v[212:215], v158 offset:2048
	ds_read_b128 v[216:219], v158 offset:3072
	global_load_lds_dwordx4 v[152:153], off
	v_lshl_add_u64 v[220:221], s[42:43], 0, v[128:129]
	s_add_i32 m0, s47, 0x2000
	s_nop 0
	global_load_lds_dwordx4 v[220:221], off
	s_barrier
	s_waitcnt lgkmcnt(0)
	s_setprio 1
	s_waitcnt lgkmcnt(0)
	v_mfma_f32_16x16x32_bf16 v[116:119], v[204:207], v[168:171], v[116:119]
	v_mfma_f32_16x16x32_bf16 v[112:115], v[212:215], v[168:171], v[112:115]
	v_mfma_f32_16x16x32_bf16 v[100:103], v[204:207], v[176:179], v[100:103]
	v_mfma_f32_16x16x32_bf16 v[96:99], v[212:215], v[176:179], v[96:99]
	v_mfma_f32_16x16x32_bf16 v[84:87], v[204:207], v[184:187], v[84:87]
	v_mfma_f32_16x16x32_bf16 v[80:83], v[212:215], v[184:187], v[80:83]
	v_mfma_f32_16x16x32_bf16 v[68:71], v[204:207], v[192:195], v[68:71]
	v_mfma_f32_16x16x32_bf16 v[64:67], v[212:215], v[192:195], v[64:67]
	v_mfma_f32_16x16x32_bf16 v[116:119], v[208:211], v[172:175], v[116:119]
	v_mfma_f32_16x16x32_bf16 v[112:115], v[216:219], v[172:175], v[112:115]
	v_mfma_f32_16x16x32_bf16 v[100:103], v[208:211], v[180:183], v[100:103]
	v_mfma_f32_16x16x32_bf16 v[96:99], v[216:219], v[180:183], v[96:99]
	v_mfma_f32_16x16x32_bf16 v[84:87], v[208:211], v[188:191], v[84:87]
	v_mfma_f32_16x16x32_bf16 v[80:83], v[216:219], v[188:191], v[80:83]
	v_mfma_f32_16x16x32_bf16 v[68:71], v[208:211], v[200:203], v[68:71]
	v_mfma_f32_16x16x32_bf16 v[64:67], v[216:219], v[200:203], v[64:67]
	s_setprio 0
	s_mov_b32 m0, s53
	v_lshl_add_u64 v[222:223], s[44:45], 0, v[134:135]
	s_barrier
	ds_read_b128 v[168:171], v157 offset:16384
	ds_read_b128 v[172:175], v157 offset:17408
	ds_read_b128 v[176:179], v157 offset:18432
	ds_read_b128 v[180:183], v157 offset:19456
	ds_read_b128 v[184:187], v157 offset:20480
	ds_read_b128 v[188:191], v157 offset:21504
	ds_read_b128 v[192:195], v157 offset:22528
	ds_read_b128 v[200:203], v157 offset:23552
	global_load_lds_dwordx4 v[222:223], off
	v_lshl_add_u64 v[224:225], s[44:45], 0, v[130:131]
	s_mov_b32 m0, s62
	s_nop 0
	global_load_lds_dwordx4 v[224:225], off
	s_barrier
	s_waitcnt lgkmcnt(0)
	s_setprio 1
	s_waitcnt lgkmcnt(0)
	v_mfma_f32_16x16x32_bf16 v[60:63], v[144:147], v[168:171], v[60:63]
	v_mfma_f32_16x16x32_bf16 v[56:59], v[160:163], v[168:171], v[56:59]
	v_mfma_f32_16x16x32_bf16 v[44:47], v[144:147], v[176:179], v[44:47]
	v_mfma_f32_16x16x32_bf16 v[40:43], v[160:163], v[176:179], v[40:43]
	v_mfma_f32_16x16x32_bf16 v[28:31], v[144:147], v[184:187], v[28:31]
	v_mfma_f32_16x16x32_bf16 v[24:27], v[160:163], v[184:187], v[24:27]
	v_mfma_f32_16x16x32_bf16 v[12:15], v[144:147], v[192:195], v[12:15]
	v_mfma_f32_16x16x32_bf16 v[8:11], v[160:163], v[192:195], v[8:11]
	v_mfma_f32_16x16x32_bf16 v[60:63], v[148:151], v[172:175], v[60:63]
	v_mfma_f32_16x16x32_bf16 v[56:59], v[164:167], v[172:175], v[56:59]
	v_mfma_f32_16x16x32_bf16 v[44:47], v[148:151], v[180:183], v[44:47]
	v_mfma_f32_16x16x32_bf16 v[40:43], v[164:167], v[180:183], v[40:43]
	v_mfma_f32_16x16x32_bf16 v[28:31], v[148:151], v[188:191], v[28:31]
	v_mfma_f32_16x16x32_bf16 v[24:27], v[164:167], v[188:191], v[24:27]
	v_mfma_f32_16x16x32_bf16 v[12:15], v[148:151], v[200:203], v[12:15]
	v_mfma_f32_16x16x32_bf16 v[8:11], v[164:167], v[200:203], v[8:11]
	s_setprio 0
	s_barrier
	s_add_u32 s76, s42, 0x40000
	s_addc_u32 s77, s43, 0
	s_add_i32 s47, s68, s50
	v_lshl_add_u64 v[144:145], s[76:77], 0, v[132:133]
	s_mov_b32 m0, s47
	s_nop 0
	global_load_lds_dwordx4 v[144:145], off
	v_lshl_add_u64 v[144:145], s[76:77], 0, v[128:129]
	s_add_i32 m0, s47, 0x2000
	s_nop 0
	global_load_lds_dwordx4 v[144:145], off
	s_waitcnt vmcnt(6)
	s_barrier
	s_setprio 1
	v_mfma_f32_16x16x32_bf16 v[52:55], v[204:207], v[168:171], v[52:55]
	v_mfma_f32_16x16x32_bf16 v[48:51], v[212:215], v[168:171], v[48:51]
	v_mfma_f32_16x16x32_bf16 v[36:39], v[204:207], v[176:179], v[36:39]
	v_mfma_f32_16x16x32_bf16 v[32:35], v[212:215], v[176:179], v[32:35]
	v_mfma_f32_16x16x32_bf16 v[20:23], v[204:207], v[184:187], v[20:23]
	v_mfma_f32_16x16x32_bf16 v[16:19], v[212:215], v[184:187], v[16:19]
	v_mfma_f32_16x16x32_bf16 v[4:7], v[204:207], v[192:195], v[4:7]
	v_mfma_f32_16x16x32_bf16 v[0:3], v[212:215], v[192:195], v[0:3]
	v_mfma_f32_16x16x32_bf16 v[52:55], v[208:211], v[172:175], v[52:55]
	v_mfma_f32_16x16x32_bf16 v[48:51], v[216:219], v[172:175], v[48:51]
	v_mfma_f32_16x16x32_bf16 v[36:39], v[208:211], v[180:183], v[36:39]
	v_mfma_f32_16x16x32_bf16 v[32:35], v[216:219], v[180:183], v[32:35]
	v_mfma_f32_16x16x32_bf16 v[20:23], v[208:211], v[188:191], v[20:23]
	v_mfma_f32_16x16x32_bf16 v[16:19], v[216:219], v[188:191], v[16:19]
	v_mfma_f32_16x16x32_bf16 v[4:7], v[208:211], v[200:203], v[4:7]
	v_mfma_f32_16x16x32_bf16 v[0:3], v[216:219], v[200:203], v[0:3]
	s_setprio 0
	s_add_i32 s47, 0, 0x18000
	v_add_u32_e32 v164, s47, v155
	s_barrier
	ds_read_b128 v[144:147], v164
	ds_read_b128 v[148:151], v164 offset:1024
	ds_read_b128 v[160:163], v164 offset:2048
	ds_read_b128 v[164:167], v164 offset:3072
	s_add_u32 s44, s44, 0x40000
	s_addc_u32 s45, s45, 0
	s_mov_b32 m0, s63
	v_lshl_add_u64 v[204:205], s[44:45], 0, v[134:135]
	ds_read_b128 v[168:171], v157 offset:32768
	ds_read_b128 v[172:175], v157 offset:33792
	ds_read_b128 v[176:179], v157 offset:34816
	ds_read_b128 v[180:183], v157 offset:35840
	ds_read_b128 v[184:187], v157 offset:36864
	ds_read_b128 v[188:191], v157 offset:37888
	ds_read_b128 v[192:195], v157 offset:38912
	ds_read_b128 v[200:203], v157 offset:39936
	global_load_lds_dwordx4 v[204:205], off
	v_lshl_add_u64 v[204:205], s[44:45], 0, v[130:131]
	s_mov_b32 m0, s64
	s_nop 0
	global_load_lds_dwordx4 v[204:205], off
	s_waitcnt lgkmcnt(8)
	s_barrier
	s_waitcnt lgkmcnt(0)
	s_setprio 1
	s_waitcnt lgkmcnt(0)
	v_mfma_f32_16x16x32_bf16 v[124:127], v[144:147], v[168:171], v[124:127]
	v_mfma_f32_16x16x32_bf16 v[120:123], v[160:163], v[168:171], v[120:123]
	v_mfma_f32_16x16x32_bf16 v[108:111], v[144:147], v[176:179], v[108:111]
	v_mfma_f32_16x16x32_bf16 v[104:107], v[160:163], v[176:179], v[104:107]
	v_mfma_f32_16x16x32_bf16 v[92:95], v[144:147], v[184:187], v[92:95]
	v_mfma_f32_16x16x32_bf16 v[88:91], v[160:163], v[184:187], v[88:91]
	v_mfma_f32_16x16x32_bf16 v[76:79], v[144:147], v[192:195], v[76:79]
	v_mfma_f32_16x16x32_bf16 v[72:75], v[160:163], v[192:195], v[72:75]
	v_mfma_f32_16x16x32_bf16 v[124:127], v[148:151], v[172:175], v[124:127]
	v_mfma_f32_16x16x32_bf16 v[120:123], v[164:167], v[172:175], v[120:123]
	v_mfma_f32_16x16x32_bf16 v[108:111], v[148:151], v[180:183], v[108:111]
	v_mfma_f32_16x16x32_bf16 v[104:107], v[164:167], v[180:183], v[104:107]
	v_mfma_f32_16x16x32_bf16 v[92:95], v[148:151], v[188:191], v[92:95]
	v_mfma_f32_16x16x32_bf16 v[88:91], v[164:167], v[188:191], v[88:91]
	v_mfma_f32_16x16x32_bf16 v[76:79], v[148:151], v[200:203], v[76:79]
	v_mfma_f32_16x16x32_bf16 v[72:75], v[164:167], v[200:203], v[72:75]
	s_setprio 0
	s_barrier
	s_add_i32 s44, 0, 0x1c000
	s_add_i32 s45, s47, s50
	v_add_u32_e32 v216, s44, v155
	v_lshl_add_u64 v[152:153], v[152:153], 0, s[8:9]
	s_mov_b32 m0, s45
	ds_read_b128 v[204:207], v216
	ds_read_b128 v[208:211], v216 offset:1024
	ds_read_b128 v[212:215], v216 offset:2048
	ds_read_b128 v[216:219], v216 offset:3072
	global_load_lds_dwordx4 v[152:153], off
	v_lshl_add_u64 v[152:153], v[220:221], 0, s[8:9]
	s_add_i32 m0, s45, 0x2000
	s_nop 0
	global_load_lds_dwordx4 v[152:153], off
	s_barrier
	s_waitcnt lgkmcnt(0)
	s_setprio 1
	s_waitcnt lgkmcnt(0)
	v_mfma_f32_16x16x32_bf16 v[116:119], v[204:207], v[168:171], v[116:119]
	v_mfma_f32_16x16x32_bf16 v[112:115], v[212:215], v[168:171], v[112:115]
	v_mfma_f32_16x16x32_bf16 v[100:103], v[204:207], v[176:179], v[100:103]
	v_mfma_f32_16x16x32_bf16 v[96:99], v[212:215], v[176:179], v[96:99]
	v_mfma_f32_16x16x32_bf16 v[84:87], v[204:207], v[184:187], v[84:87]
	v_mfma_f32_16x16x32_bf16 v[80:83], v[212:215], v[184:187], v[80:83]
	v_mfma_f32_16x16x32_bf16 v[68:71], v[204:207], v[192:195], v[68:71]
	v_mfma_f32_16x16x32_bf16 v[64:67], v[212:215], v[192:195], v[64:67]
	v_mfma_f32_16x16x32_bf16 v[116:119], v[208:211], v[172:175], v[116:119]
	v_mfma_f32_16x16x32_bf16 v[112:115], v[216:219], v[172:175], v[112:115]
	v_mfma_f32_16x16x32_bf16 v[100:103], v[208:211], v[180:183], v[100:103]
	v_mfma_f32_16x16x32_bf16 v[96:99], v[216:219], v[180:183], v[96:99]
	v_mfma_f32_16x16x32_bf16 v[84:87], v[208:211], v[188:191], v[84:87]
	v_mfma_f32_16x16x32_bf16 v[80:83], v[216:219], v[188:191], v[80:83]
	v_mfma_f32_16x16x32_bf16 v[68:71], v[208:211], v[200:203], v[68:71]
	v_mfma_f32_16x16x32_bf16 v[64:67], v[216:219], v[200:203], v[64:67]
	s_setprio 0
	s_mov_b32 m0, s65
	v_lshl_add_u64 v[152:153], v[222:223], 0, s[8:9]
	s_barrier
	ds_read_b128 v[168:171], v157 offset:49152
	ds_read_b128 v[172:175], v157 offset:50176
	ds_read_b128 v[176:179], v157 offset:51200
	ds_read_b128 v[180:183], v157 offset:52224
	ds_read_b128 v[184:187], v157 offset:53248
	ds_read_b128 v[188:191], v157 offset:54272
	ds_read_b128 v[192:195], v157 offset:55296
	ds_read_b128 v[200:203], v157 offset:56320
	global_load_lds_dwordx4 v[152:153], off
	v_lshl_add_u64 v[152:153], v[224:225], 0, s[8:9]
	s_mov_b32 m0, s66
	s_nop 0
	global_load_lds_dwordx4 v[152:153], off
	s_barrier
	s_waitcnt lgkmcnt(0)
	s_setprio 1
	s_waitcnt lgkmcnt(0)
	v_mfma_f32_16x16x32_bf16 v[60:63], v[144:147], v[168:171], v[60:63]
	v_mfma_f32_16x16x32_bf16 v[56:59], v[160:163], v[168:171], v[56:59]
	v_mfma_f32_16x16x32_bf16 v[44:47], v[144:147], v[176:179], v[44:47]
	v_mfma_f32_16x16x32_bf16 v[40:43], v[160:163], v[176:179], v[40:43]
	v_mfma_f32_16x16x32_bf16 v[28:31], v[144:147], v[184:187], v[28:31]
	v_mfma_f32_16x16x32_bf16 v[24:27], v[160:163], v[184:187], v[24:27]
	v_mfma_f32_16x16x32_bf16 v[12:15], v[144:147], v[192:195], v[12:15]
	v_mfma_f32_16x16x32_bf16 v[8:11], v[160:163], v[192:195], v[8:11]
	v_mfma_f32_16x16x32_bf16 v[60:63], v[148:151], v[172:175], v[60:63]
	v_mfma_f32_16x16x32_bf16 v[56:59], v[164:167], v[172:175], v[56:59]
	v_mfma_f32_16x16x32_bf16 v[44:47], v[148:151], v[180:183], v[44:47]
	v_mfma_f32_16x16x32_bf16 v[40:43], v[164:167], v[180:183], v[40:43]
	v_mfma_f32_16x16x32_bf16 v[28:31], v[148:151], v[188:191], v[28:31]
	v_mfma_f32_16x16x32_bf16 v[24:27], v[164:167], v[188:191], v[24:27]
	v_mfma_f32_16x16x32_bf16 v[12:15], v[148:151], v[200:203], v[12:15]
	v_mfma_f32_16x16x32_bf16 v[8:11], v[164:167], v[200:203], v[8:11]
	s_setprio 0
	s_barrier
	s_add_u32 s42, s42, 0x40080
	s_addc_u32 s43, s43, 0
	s_add_i32 s44, s44, s50
	v_lshl_add_u64 v[144:145], s[42:43], 0, v[132:133]
	s_mov_b32 m0, s44
	s_nop 0
	global_load_lds_dwordx4 v[144:145], off
	v_lshl_add_u64 v[144:145], s[42:43], 0, v[128:129]
	s_add_i32 m0, s44, 0x2000
	s_nop 0
	global_load_lds_dwordx4 v[144:145], off
	s_waitcnt vmcnt(6)
	s_barrier
	s_setprio 1
	v_mfma_f32_16x16x32_bf16 v[52:55], v[204:207], v[168:171], v[52:55]
	v_mfma_f32_16x16x32_bf16 v[48:51], v[212:215], v[168:171], v[48:51]
	v_mfma_f32_16x16x32_bf16 v[36:39], v[204:207], v[176:179], v[36:39]
	v_mfma_f32_16x16x32_bf16 v[32:35], v[212:215], v[176:179], v[32:35]
	v_mfma_f32_16x16x32_bf16 v[20:23], v[204:207], v[184:187], v[20:23]
	v_mfma_f32_16x16x32_bf16 v[16:19], v[212:215], v[184:187], v[16:19]
	v_mfma_f32_16x16x32_bf16 v[4:7], v[204:207], v[192:195], v[4:7]
	v_mfma_f32_16x16x32_bf16 v[0:3], v[212:215], v[192:195], v[0:3]
	v_mfma_f32_16x16x32_bf16 v[52:55], v[208:211], v[172:175], v[52:55]
	v_mfma_f32_16x16x32_bf16 v[48:51], v[216:219], v[172:175], v[48:51]
	v_mfma_f32_16x16x32_bf16 v[36:39], v[208:211], v[180:183], v[36:39]
	v_mfma_f32_16x16x32_bf16 v[32:35], v[216:219], v[180:183], v[32:35]
	v_mfma_f32_16x16x32_bf16 v[20:23], v[208:211], v[188:191], v[20:23]
	v_mfma_f32_16x16x32_bf16 v[16:19], v[216:219], v[188:191], v[16:19]
	v_mfma_f32_16x16x32_bf16 v[4:7], v[208:211], v[200:203], v[4:7]
	v_mfma_f32_16x16x32_bf16 v[0:3], v[216:219], v[200:203], v[0:3]
	s_setprio 0
	s_add_i32 s46, s46, 2
	s_add_u32 s40, s40, 0x100
	s_addc_u32 s41, s41, 0
	s_add_u32 s18, s18, 0x100
	s_addc_u32 s19, s19, 0
	s_cmp_gt_u32 s46, 13
	s_barrier
	s_cbranch_scc0 .LBB0_667
	v_add_u32_e32 v144, s74, v154
	v_ashrrev_i32_e32 v145, 31, v144
	v_lshl_add_u64 v[146:147], v[144:145], 2, s[94:95]
	v_add_co_u32_e32 v148, vcc, 0x40000, v146
	s_ashr_i32 s18, s73, 7
	s_nop 0
	v_addc_co_u32_e32 v149, vcc, 0, v147, vcc
	v_add_co_u32_e32 v150, vcc, 0x80000, v146
	s_mov_b32 s40, 0xff800000
	s_nop 0
	v_addc_co_u32_e32 v151, vcc, 0, v147, vcc
	v_add_co_u32_e32 v152, vcc, 0xc0000, v146
	s_ashr_i32 s19, s18, 31
	s_nop 0
	v_addc_co_u32_e32 v153, vcc, 0, v147, vcc
	s_nop 1
	v_mov_b32_e32 v160, v232
	v_mov_b32_e32 v162, v233
	v_mov_b32_e32 v161, v234
	v_mov_b32_e32 v163, v235
	global_load_dword v168, v[146:147], off offset:576
	global_load_dword v169, v[148:149], off offset:576
	global_load_dword v170, v[150:151], off offset:576
	global_load_dword v171, v[152:153], off offset:576
	global_load_dword v172, v[146:147], off offset:640
	global_load_dword v173, v[148:149], off offset:640
	global_load_dword v174, v[150:151], off offset:640
	global_load_dword v175, v[152:153], off offset:640
	global_load_dword v176, v[146:147], off offset:704
	global_load_dword v177, v[148:149], off offset:704
	global_load_dword v178, v[150:151], off offset:704
	global_load_dword v179, v[152:153], off offset:704
	s_mov_b32 s41, -1
	v_lshlrev_b64 v[144:145], 8, v[144:145]
	s_lshl_b64 s[18:19], s[18:19], 23
	v_lshl_add_u64 v[164:165], v[144:145], 0, s[40:41]
	s_add_u32 s40, s92, s18
	s_addc_u32 s41, s93, s19
	s_add_u32 s42, s40, 0x800000
	v_lshl_add_u64 v[166:167], s[40:41], 0, v[164:165]
	s_addc_u32 s43, s41, 0
	v_lshl_add_u64 v[166:167], v[166:167], 0, s[10:11]
	v_lshl_add_u64 v[166:167], v[166:167], 0, v[136:137]
	s_mov_b32 s18, 0xff801000
	s_mov_b32 s19, -1
	s_mov_b32 s73, s71
	s_mov_b32 s74, s72
	s_mov_b64 s[46:47], s[38:39]
	s_mov_b64 s[44:45], s[36:37]
	s_nop 0
	v_pk_add_f32 v[160:161], v[160:161], v[162:163]
	s_nop 0
	v_add_f32_e32 v160, v160, v161
	v_fmamk_f32 v160, v160, 0x3a800000, v159
	v_mul_f32_e32 v161, 0x4b800000, v160
	v_cmp_gt_f32_e32 vcc, s69, v160
	s_nop 1
	v_cndmask_b32_e32 v160, v160, v161, vcc
	v_rsq_f32_e32 v162, v160
	v_lshl_add_u64 v[160:161], s[42:43], 0, v[164:165]
	v_lshl_add_u64 v[160:161], v[160:161], 0, s[10:11]
	v_lshl_add_u64 v[160:161], v[160:161], 0, v[136:137]
	v_mul_f32_e32 v163, 0x45800000, v162
	v_cndmask_b32_e32 v162, v162, v163, vcc
	v_pk_mul_f32 v[126:127], v[126:127], v[162:163] op_sel_hi:[1,0]
	v_pk_mul_f32 v[124:125], v[124:125], v[162:163] op_sel_hi:[1,0]
	v_pk_mul_f32 v[122:123], v[122:123], v[162:163] op_sel_hi:[1,0]
	v_pk_mul_f32 v[120:121], v[120:121], v[162:163] op_sel_hi:[1,0]
	v_pk_mul_f32 v[118:119], v[118:119], v[162:163] op_sel_hi:[1,0]
	v_pk_mul_f32 v[116:117], v[116:117], v[162:163] op_sel_hi:[1,0]
	v_pk_mul_f32 v[164:165], v[114:115], v[162:163] op_sel_hi:[1,0]
	v_pk_mul_f32 v[162:163], v[112:113], v[162:163] op_sel_hi:[1,0]
	v_cvt_pk_bf16_f32 v112, v124, v125
	v_cvt_pk_bf16_f32 v113, v126, v127
	v_cvt_pk_bf16_f32 v114, v120, v121
	v_cvt_pk_bf16_f32 v115, v122, v123
	v_cvt_pk_bf16_f32 v116, v116, v117
	v_cvt_pk_bf16_f32 v117, v118, v119
	s_nop 0
	v_cvt_pk_bf16_f32 v118, v162, v163
	v_cvt_pk_bf16_f32 v119, v164, v165
	global_store_dwordx4 v[166:167], v[112:115], off
	global_store_dwordx4 v[160:161], v[116:119], off
	s_nop 1
	v_mov_b32_e32 v112, v236
	s_nop 0
	v_mov_b32_e32 v114, v237
	v_mov_b32_e32 v113, v238
	v_mov_b32_e32 v115, v239
	v_lshl_add_u64 v[116:117], v[144:145], 0, s[18:19]
	v_lshl_add_u64 v[118:119], s[40:41], 0, v[116:117]
	v_lshl_add_u64 v[118:119], v[118:119], 0, s[10:11]
	v_lshl_add_u64 v[118:119], v[118:119], 0, v[136:137]
	s_nop 0
	v_pk_add_f32 v[112:113], v[112:113], v[114:115]
	s_nop 0
	v_add_f32_e32 v112, v112, v113
	v_fmamk_f32 v112, v112, 0x3a800000, v159
	v_mul_f32_e32 v113, 0x4b800000, v112
	v_cmp_gt_f32_e32 vcc, s69, v112
	s_nop 1
	v_cndmask_b32_e32 v112, v112, v113, vcc
	v_rsq_f32_e32 v114, v112
	v_lshl_add_u64 v[112:113], s[42:43], 0, v[116:117]
	v_lshl_add_u64 v[112:113], v[112:113], 0, s[10:11]
	v_lshl_add_u64 v[112:113], v[112:113], 0, v[136:137]
	v_mul_f32_e32 v115, 0x45800000, v114
	v_cndmask_b32_e32 v114, v114, v115, vcc
	v_pk_mul_f32 v[110:111], v[110:111], v[114:115] op_sel_hi:[1,0]
	v_pk_mul_f32 v[108:109], v[108:109], v[114:115] op_sel_hi:[1,0]
	v_pk_mul_f32 v[106:107], v[106:107], v[114:115] op_sel_hi:[1,0]
	v_pk_mul_f32 v[104:105], v[104:105], v[114:115] op_sel_hi:[1,0]
	v_pk_mul_f32 v[102:103], v[102:103], v[114:115] op_sel_hi:[1,0]
	v_pk_mul_f32 v[100:101], v[100:101], v[114:115] op_sel_hi:[1,0]
	v_pk_mul_f32 v[116:117], v[98:99], v[114:115] op_sel_hi:[1,0]
	v_pk_mul_f32 v[114:115], v[96:97], v[114:115] op_sel_hi:[1,0]
	v_cvt_pk_bf16_f32 v96, v108, v109
	v_cvt_pk_bf16_f32 v97, v110, v111
	v_cvt_pk_bf16_f32 v98, v104, v105
	v_cvt_pk_bf16_f32 v99, v106, v107
	v_cvt_pk_bf16_f32 v100, v100, v101
	v_cvt_pk_bf16_f32 v101, v102, v103
	s_nop 0
	v_cvt_pk_bf16_f32 v102, v114, v115
	v_cvt_pk_bf16_f32 v103, v116, v117
	global_store_dwordx4 v[118:119], v[96:99], off
	global_store_dwordx4 v[112:113], v[100:103], off
	s_nop 1
	v_mov_b32_e32 v96, v240
	s_nop 0
	v_mov_b32_e32 v98, v241
	v_mov_b32_e32 v97, v242
	v_mov_b32_e32 v99, v243
	v_lshl_add_u64 v[100:101], v[144:145], 0, s[22:23]
	v_lshl_add_u64 v[102:103], s[40:41], 0, v[100:101]
	v_lshl_add_u64 v[102:103], v[102:103], 0, s[10:11]
	v_lshl_add_u64 v[102:103], v[102:103], 0, v[136:137]
	s_nop 0
	v_pk_add_f32 v[96:97], v[96:97], v[98:99]
	s_nop 0
	v_add_f32_e32 v96, v96, v97
	v_fmamk_f32 v96, v96, 0x3a800000, v159
	v_mul_f32_e32 v97, 0x4b800000, v96
	v_cmp_gt_f32_e32 vcc, s69, v96
	s_nop 1
	v_cndmask_b32_e32 v96, v96, v97, vcc
	v_rsq_f32_e32 v98, v96
	v_lshl_add_u64 v[96:97], s[42:43], 0, v[100:101]
	v_lshl_add_u64 v[96:97], v[96:97], 0, s[10:11]
	v_lshl_add_u64 v[96:97], v[96:97], 0, v[136:137]
	v_mul_f32_e32 v99, 0x45800000, v98
	v_cndmask_b32_e32 v98, v98, v99, vcc
	v_pk_mul_f32 v[94:95], v[94:95], v[98:99] op_sel_hi:[1,0]
	v_pk_mul_f32 v[92:93], v[92:93], v[98:99] op_sel_hi:[1,0]
	v_pk_mul_f32 v[90:91], v[90:91], v[98:99] op_sel_hi:[1,0]
	v_pk_mul_f32 v[88:89], v[88:89], v[98:99] op_sel_hi:[1,0]
	v_pk_mul_f32 v[86:87], v[86:87], v[98:99] op_sel_hi:[1,0]
	v_pk_mul_f32 v[84:85], v[84:85], v[98:99] op_sel_hi:[1,0]
	v_pk_mul_f32 v[100:101], v[82:83], v[98:99] op_sel_hi:[1,0]
	v_pk_mul_f32 v[98:99], v[80:81], v[98:99] op_sel_hi:[1,0]
	v_cvt_pk_bf16_f32 v80, v92, v93
	v_cvt_pk_bf16_f32 v81, v94, v95
	v_cvt_pk_bf16_f32 v82, v88, v89
	v_cvt_pk_bf16_f32 v83, v90, v91
	v_cvt_pk_bf16_f32 v84, v84, v85
	v_cvt_pk_bf16_f32 v85, v86, v87
	s_nop 0
	v_cvt_pk_bf16_f32 v86, v98, v99
	v_cvt_pk_bf16_f32 v87, v100, v101
	global_store_dwordx4 v[102:103], v[80:83], off
	global_store_dwordx4 v[96:97], v[84:87], off
	s_nop 1
	v_mov_b32_e32 v80, v244
	s_nop 0
	v_mov_b32_e32 v82, v245
	v_mov_b32_e32 v81, v246
	v_mov_b32_e32 v83, v247
	v_lshl_add_u64 v[84:85], v[144:145], 0, s[24:25]
	v_lshl_add_u64 v[86:87], s[40:41], 0, v[84:85]
	v_lshl_add_u64 v[86:87], v[86:87], 0, s[10:11]
	v_lshl_add_u64 v[86:87], v[86:87], 0, v[136:137]
	s_nop 0
	v_pk_add_f32 v[80:81], v[80:81], v[82:83]
	s_nop 0
	v_add_f32_e32 v80, v80, v81
	v_fmamk_f32 v80, v80, 0x3a800000, v159
	v_mul_f32_e32 v81, 0x4b800000, v80
	v_cmp_gt_f32_e32 vcc, s69, v80
	s_nop 1
	v_cndmask_b32_e32 v80, v80, v81, vcc
	v_rsq_f32_e32 v82, v80
	v_lshl_add_u64 v[80:81], s[42:43], 0, v[84:85]
	v_lshl_add_u64 v[80:81], v[80:81], 0, s[10:11]
	v_lshl_add_u64 v[80:81], v[80:81], 0, v[136:137]
	v_mul_f32_e32 v83, 0x45800000, v82
	v_cndmask_b32_e32 v82, v82, v83, vcc
	v_pk_mul_f32 v[78:79], v[78:79], v[82:83] op_sel_hi:[1,0]
	v_pk_mul_f32 v[76:77], v[76:77], v[82:83] op_sel_hi:[1,0]
	v_pk_mul_f32 v[74:75], v[74:75], v[82:83] op_sel_hi:[1,0]
	v_pk_mul_f32 v[72:73], v[72:73], v[82:83] op_sel_hi:[1,0]
	v_pk_mul_f32 v[70:71], v[70:71], v[82:83] op_sel_hi:[1,0]
	v_pk_mul_f32 v[68:69], v[68:69], v[82:83] op_sel_hi:[1,0]
	v_pk_mul_f32 v[84:85], v[66:67], v[82:83] op_sel_hi:[1,0]
	v_pk_mul_f32 v[82:83], v[64:65], v[82:83] op_sel_hi:[1,0]
	v_cvt_pk_bf16_f32 v64, v76, v77
	v_cvt_pk_bf16_f32 v65, v78, v79
	v_cvt_pk_bf16_f32 v66, v72, v73
	v_cvt_pk_bf16_f32 v67, v74, v75
	v_cvt_pk_bf16_f32 v68, v68, v69
	v_cvt_pk_bf16_f32 v69, v70, v71
	s_nop 0
	v_cvt_pk_bf16_f32 v70, v82, v83
	v_cvt_pk_bf16_f32 v71, v84, v85
	global_store_dwordx4 v[86:87], v[64:67], off
	global_store_dwordx4 v[80:81], v[68:71], off
	s_nop 1
	v_mov_b32_e32 v64, v248
	s_nop 0
	v_mov_b32_e32 v66, v249
	v_mov_b32_e32 v65, v250
	v_mov_b32_e32 v67, v251
	v_lshl_add_u64 v[68:69], v[144:145], 0, s[26:27]
	v_lshl_add_u64 v[70:71], s[40:41], 0, v[68:69]
	v_lshl_add_u64 v[70:71], v[70:71], 0, s[10:11]
	v_lshl_add_u64 v[70:71], v[70:71], 0, v[136:137]
	s_nop 0
	v_pk_add_f32 v[64:65], v[64:65], v[66:67]
	s_nop 0
	v_add_f32_e32 v64, v64, v65
	v_fmamk_f32 v64, v64, 0x3a800000, v159
	v_mul_f32_e32 v65, 0x4b800000, v64
	v_cmp_gt_f32_e32 vcc, s69, v64
	s_nop 1
	v_cndmask_b32_e32 v64, v64, v65, vcc
	v_rsq_f32_e32 v66, v64
	v_lshl_add_u64 v[64:65], s[42:43], 0, v[68:69]
	v_lshl_add_u64 v[64:65], v[64:65], 0, s[10:11]
	v_lshl_add_u64 v[64:65], v[64:65], 0, v[136:137]
	v_mul_f32_e32 v67, 0x45800000, v66
	v_cndmask_b32_e32 v66, v66, v67, vcc
	v_pk_mul_f32 v[62:63], v[62:63], v[66:67] op_sel_hi:[1,0]
	v_pk_mul_f32 v[60:61], v[60:61], v[66:67] op_sel_hi:[1,0]
	v_pk_mul_f32 v[58:59], v[58:59], v[66:67] op_sel_hi:[1,0]
	v_pk_mul_f32 v[56:57], v[56:57], v[66:67] op_sel_hi:[1,0]
	v_pk_mul_f32 v[54:55], v[54:55], v[66:67] op_sel_hi:[1,0]
	v_pk_mul_f32 v[52:53], v[52:53], v[66:67] op_sel_hi:[1,0]
	v_pk_mul_f32 v[68:69], v[50:51], v[66:67] op_sel_hi:[1,0]
	v_pk_mul_f32 v[66:67], v[48:49], v[66:67] op_sel_hi:[1,0]
	v_cvt_pk_bf16_f32 v48, v60, v61
	v_cvt_pk_bf16_f32 v49, v62, v63
	v_cvt_pk_bf16_f32 v50, v56, v57
	v_cvt_pk_bf16_f32 v51, v58, v59
	v_cvt_pk_bf16_f32 v52, v52, v53
	v_cvt_pk_bf16_f32 v53, v54, v55
	s_nop 0
	v_cvt_pk_bf16_f32 v54, v66, v67
	v_cvt_pk_bf16_f32 v55, v68, v69
	global_store_dwordx4 v[70:71], v[48:51], off
	global_store_dwordx4 v[64:65], v[52:55], off
	s_waitcnt vmcnt(10)
	s_nop 1
	v_mov_b32_e32 v48, v168
	s_nop 0
	v_mov_b32_e32 v50, v169
	v_mov_b32_e32 v49, v170
	v_mov_b32_e32 v51, v171
	v_lshl_add_u64 v[52:53], v[144:145], 0, s[28:29]
	v_lshl_add_u64 v[54:55], s[40:41], 0, v[52:53]
	v_lshl_add_u64 v[54:55], v[54:55], 0, s[10:11]
	v_lshl_add_u64 v[54:55], v[54:55], 0, v[136:137]
	s_nop 0
	v_pk_add_f32 v[48:49], v[48:49], v[50:51]
	s_nop 0
	v_add_f32_e32 v48, v48, v49
	v_fmamk_f32 v48, v48, 0x3a800000, v159
	v_mul_f32_e32 v49, 0x4b800000, v48
	v_cmp_gt_f32_e32 vcc, s69, v48
	s_nop 1
	v_cndmask_b32_e32 v48, v48, v49, vcc
	v_rsq_f32_e32 v50, v48
	v_lshl_add_u64 v[48:49], s[42:43], 0, v[52:53]
	v_lshl_add_u64 v[48:49], v[48:49], 0, s[10:11]
	v_lshl_add_u64 v[48:49], v[48:49], 0, v[136:137]
	v_mul_f32_e32 v51, 0x45800000, v50
	v_cndmask_b32_e32 v50, v50, v51, vcc
	v_pk_mul_f32 v[46:47], v[46:47], v[50:51] op_sel_hi:[1,0]
	v_pk_mul_f32 v[44:45], v[44:45], v[50:51] op_sel_hi:[1,0]
	v_pk_mul_f32 v[42:43], v[42:43], v[50:51] op_sel_hi:[1,0]
	v_pk_mul_f32 v[40:41], v[40:41], v[50:51] op_sel_hi:[1,0]
	v_pk_mul_f32 v[38:39], v[38:39], v[50:51] op_sel_hi:[1,0]
	v_pk_mul_f32 v[36:37], v[36:37], v[50:51] op_sel_hi:[1,0]
	v_pk_mul_f32 v[52:53], v[34:35], v[50:51] op_sel_hi:[1,0]
	v_pk_mul_f32 v[50:51], v[32:33], v[50:51] op_sel_hi:[1,0]
	v_cvt_pk_bf16_f32 v32, v44, v45
	v_cvt_pk_bf16_f32 v33, v46, v47
	v_cvt_pk_bf16_f32 v34, v40, v41
	v_cvt_pk_bf16_f32 v35, v42, v43
	v_cvt_pk_bf16_f32 v36, v36, v37
	v_cvt_pk_bf16_f32 v37, v38, v39
	s_nop 0
	v_cvt_pk_bf16_f32 v38, v50, v51
	v_cvt_pk_bf16_f32 v39, v52, v53
	global_store_dwordx4 v[54:55], v[32:35], off
	global_store_dwordx4 v[48:49], v[36:39], off
	s_nop 1
	v_mov_b32_e32 v32, v172
	s_nop 0
	v_mov_b32_e32 v34, v173
	v_mov_b32_e32 v33, v174
	v_mov_b32_e32 v35, v175
	v_lshl_add_u64 v[36:37], v[144:145], 0, s[30:31]
	v_lshl_add_u64 v[38:39], s[40:41], 0, v[36:37]
	v_lshl_add_u64 v[38:39], v[38:39], 0, s[10:11]
	v_lshl_add_u64 v[38:39], v[38:39], 0, v[136:137]
	s_nop 0
	v_pk_add_f32 v[32:33], v[32:33], v[34:35]
	s_nop 0
	v_add_f32_e32 v32, v32, v33
	v_fmamk_f32 v32, v32, 0x3a800000, v159
	v_mul_f32_e32 v33, 0x4b800000, v32
	v_cmp_gt_f32_e32 vcc, s69, v32
	s_nop 1
	v_cndmask_b32_e32 v32, v32, v33, vcc
	v_rsq_f32_e32 v34, v32
	v_lshl_add_u64 v[32:33], s[42:43], 0, v[36:37]
	v_lshl_add_u64 v[32:33], v[32:33], 0, s[10:11]
	v_lshl_add_u64 v[32:33], v[32:33], 0, v[136:137]
	v_mul_f32_e32 v35, 0x45800000, v34
	v_cndmask_b32_e32 v34, v34, v35, vcc
	v_pk_mul_f32 v[30:31], v[30:31], v[34:35] op_sel_hi:[1,0]
	v_pk_mul_f32 v[28:29], v[28:29], v[34:35] op_sel_hi:[1,0]
	v_pk_mul_f32 v[26:27], v[26:27], v[34:35] op_sel_hi:[1,0]
	v_pk_mul_f32 v[24:25], v[24:25], v[34:35] op_sel_hi:[1,0]
	v_pk_mul_f32 v[22:23], v[22:23], v[34:35] op_sel_hi:[1,0]
	v_pk_mul_f32 v[20:21], v[20:21], v[34:35] op_sel_hi:[1,0]
	v_pk_mul_f32 v[36:37], v[18:19], v[34:35] op_sel_hi:[1,0]
	v_pk_mul_f32 v[34:35], v[16:17], v[34:35] op_sel_hi:[1,0]
	v_cvt_pk_bf16_f32 v16, v28, v29
	v_cvt_pk_bf16_f32 v17, v30, v31
	v_cvt_pk_bf16_f32 v18, v24, v25
	v_cvt_pk_bf16_f32 v19, v26, v27
	v_cvt_pk_bf16_f32 v20, v20, v21
	v_cvt_pk_bf16_f32 v21, v22, v23
	s_nop 0
	v_cvt_pk_bf16_f32 v22, v34, v35
	v_cvt_pk_bf16_f32 v23, v36, v37
	global_store_dwordx4 v[38:39], v[16:19], off
	global_store_dwordx4 v[32:33], v[20:23], off
	s_nop 1
	v_mov_b32_e32 v16, v176
	s_nop 0
	v_mov_b32_e32 v18, v177
	v_mov_b32_e32 v17, v178
	v_mov_b32_e32 v19, v179
	s_and_b64 vcc, exec, s[4:5]
	v_lshl_add_u64 v[20:21], v[144:145], 0, s[34:35]
	v_lshl_add_u64 v[22:23], s[40:41], 0, v[20:21]
	v_lshl_add_u64 v[22:23], v[22:23], 0, s[10:11]
	v_lshl_add_u64 v[22:23], v[22:23], 0, v[136:137]
	s_nop 0
	v_pk_add_f32 v[16:17], v[16:17], v[18:19]
	s_nop 0
	v_add_f32_e32 v16, v16, v17
	v_fmamk_f32 v16, v16, 0x3a800000, v159
	v_mul_f32_e32 v17, 0x4b800000, v16
	v_cmp_gt_f32_e64 s[4:5], s69, v16
	s_nop 1
	v_cndmask_b32_e64 v16, v16, v17, s[4:5]
	v_rsq_f32_e32 v18, v16
	v_lshl_add_u64 v[16:17], s[42:43], 0, v[20:21]
	v_lshl_add_u64 v[16:17], v[16:17], 0, s[10:11]
	v_lshl_add_u64 v[16:17], v[16:17], 0, v[136:137]
	v_mul_f32_e32 v19, 0x45800000, v18
	v_cndmask_b32_e64 v18, v18, v19, s[4:5]
	v_pk_mul_f32 v[14:15], v[14:15], v[18:19] op_sel_hi:[1,0]
	v_pk_mul_f32 v[12:13], v[12:13], v[18:19] op_sel_hi:[1,0]
	v_pk_mul_f32 v[10:11], v[10:11], v[18:19] op_sel_hi:[1,0]
	v_pk_mul_f32 v[8:9], v[8:9], v[18:19] op_sel_hi:[1,0]
	v_pk_mul_f32 v[6:7], v[6:7], v[18:19] op_sel_hi:[1,0]
	v_pk_mul_f32 v[4:5], v[4:5], v[18:19] op_sel_hi:[1,0]
	v_pk_mul_f32 v[20:21], v[2:3], v[18:19] op_sel_hi:[1,0]
	v_pk_mul_f32 v[18:19], v[0:1], v[18:19] op_sel_hi:[1,0]
	v_cvt_pk_bf16_f32 v0, v12, v13
	v_cvt_pk_bf16_f32 v1, v14, v15
	v_cvt_pk_bf16_f32 v2, v8, v9
	v_cvt_pk_bf16_f32 v3, v10, v11
	v_cvt_pk_bf16_f32 v4, v4, v5
	v_cvt_pk_bf16_f32 v5, v6, v7
	s_nop 0
	v_cvt_pk_bf16_f32 v6, v18, v19
	v_cvt_pk_bf16_f32 v7, v20, v21
	global_store_dwordx4 v[22:23], v[0:3], off
	global_store_dwordx4 v[16:17], v[4:7], off
	s_cbranch_vccz .LBB0_664
	s_waitcnt vmcnt(0)
	s_cmpk_gt_u32 s33, 0xff
	s_cbranch_scc1 .LBB0_671
	s_barrier

.LBB0_925:
	v_add_u32_e32 v226, s74, v158
	v_ashrrev_i32_e32 v227, 31, v226
	v_lshl_add_u64 v[228:229], v[226:227], 2, s[10:11]
	global_load_dword v232, v[228:229], off
	v_add_u32_e32 v226, s74, v158
	v_ashrrev_i32_e32 v227, 31, v226
	v_lshl_add_u64 v[228:229], v[226:227], 2, s[10:11]
	s_mov_b32 s98, 0x40000
	s_mov_b32 s99, 0
	v_lshl_add_u64 v[230:231], v[228:229], 0, s[98:99]
	global_load_dword v233, v[230:231], off
	v_add_u32_e32 v226, s74, v158
	v_ashrrev_i32_e32 v227, 31, v226
	v_lshl_add_u64 v[228:229], v[226:227], 2, s[10:11]
	s_mov_b32 s98, 0x80000
	s_mov_b32 s99, 0
	v_lshl_add_u64 v[230:231], v[228:229], 0, s[98:99]
	global_load_dword v234, v[230:231], off
	v_add_u32_e32 v226, s74, v158
	v_ashrrev_i32_e32 v227, 31, v226
	v_lshl_add_u64 v[228:229], v[226:227], 2, s[10:11]
	s_mov_b32 s98, 0xc0000
	s_mov_b32 s99, 0
	v_lshl_add_u64 v[230:231], v[228:229], 0, s[98:99]
	global_load_dword v235, v[230:231], off
	v_add_u32_e32 v226, s74, v158
	v_ashrrev_i32_e32 v227, 31, v226
	v_lshl_add_u64 v[228:229], v[226:227], 2, s[10:11]
	global_load_dword v236, v[228:229], off offset:64
	v_add_u32_e32 v226, s74, v158
	v_ashrrev_i32_e32 v227, 31, v226
	v_lshl_add_u64 v[228:229], v[226:227], 2, s[10:11]
	s_mov_b32 s98, 0x40000
	s_mov_b32 s99, 0
	v_lshl_add_u64 v[230:231], v[228:229], 0, s[98:99]
	global_load_dword v237, v[230:231], off offset:64
	v_add_u32_e32 v226, s74, v158
	v_ashrrev_i32_e32 v227, 31, v226
	v_lshl_add_u64 v[228:229], v[226:227], 2, s[10:11]
	s_mov_b32 s98, 0x80000
	s_mov_b32 s99, 0
	v_lshl_add_u64 v[230:231], v[228:229], 0, s[98:99]
	global_load_dword v238, v[230:231], off offset:64
	v_add_u32_e32 v226, s74, v158
	v_ashrrev_i32_e32 v227, 31, v226
	v_lshl_add_u64 v[228:229], v[226:227], 2, s[10:11]
	s_mov_b32 s98, 0xc0000
	s_mov_b32 s99, 0
	v_lshl_add_u64 v[230:231], v[228:229], 0, s[98:99]
	global_load_dword v239, v[230:231], off offset:64
	v_add_u32_e32 v226, s74, v158
	v_ashrrev_i32_e32 v227, 31, v226
	v_lshl_add_u64 v[228:229], v[226:227], 2, s[10:11]
	global_load_dword v240, v[228:229], off offset:128
	v_add_u32_e32 v226, s74, v158
	v_ashrrev_i32_e32 v227, 31, v226
	v_lshl_add_u64 v[228:229], v[226:227], 2, s[10:11]
	s_mov_b32 s98, 0x40000
	s_mov_b32 s99, 0
	v_lshl_add_u64 v[230:231], v[228:229], 0, s[98:99]
	global_load_dword v241, v[230:231], off offset:128
	v_add_u32_e32 v226, s74, v158
	v_ashrrev_i32_e32 v227, 31, v226
	v_lshl_add_u64 v[228:229], v[226:227], 2, s[10:11]
	s_mov_b32 s98, 0x80000
	s_mov_b32 s99, 0
	v_lshl_add_u64 v[230:231], v[228:229], 0, s[98:99]
	global_load_dword v242, v[230:231], off offset:128
	v_add_u32_e32 v226, s74, v158
	v_ashrrev_i32_e32 v227, 31, v226
	v_lshl_add_u64 v[228:229], v[226:227], 2, s[10:11]
	s_mov_b32 s98, 0xc0000
	s_mov_b32 s99, 0
	v_lshl_add_u64 v[230:231], v[228:229], 0, s[98:99]
	global_load_dword v243, v[230:231], off offset:128
	v_add_u32_e32 v226, s74, v158
	v_ashrrev_i32_e32 v227, 31, v226
	v_lshl_add_u64 v[228:229], v[226:227], 2, s[10:11]
	global_load_dword v244, v[228:229], off offset:192
	v_add_u32_e32 v226, s74, v158
	v_ashrrev_i32_e32 v227, 31, v226
	v_lshl_add_u64 v[228:229], v[226:227], 2, s[10:11]
	s_mov_b32 s98, 0x40000
	s_mov_b32 s99, 0
	v_lshl_add_u64 v[230:231], v[228:229], 0, s[98:99]
	global_load_dword v245, v[230:231], off offset:192
	v_add_u32_e32 v226, s74, v158
	v_ashrrev_i32_e32 v227, 31, v226
	v_lshl_add_u64 v[228:229], v[226:227], 2, s[10:11]
	s_mov_b32 s98, 0x80000
	s_mov_b32 s99, 0
	v_lshl_add_u64 v[230:231], v[228:229], 0, s[98:99]
	global_load_dword v246, v[230:231], off offset:192
	v_add_u32_e32 v226, s74, v158
	v_ashrrev_i32_e32 v227, 31, v226
	v_lshl_add_u64 v[228:229], v[226:227], 2, s[10:11]
	s_mov_b32 s98, 0xc0000
	s_mov_b32 s99, 0
	v_lshl_add_u64 v[230:231], v[228:229], 0, s[98:99]
	global_load_dword v247, v[230:231], off offset:192
	v_add_u32_e32 v226, s74, v158
	v_ashrrev_i32_e32 v227, 31, v226
	v_lshl_add_u64 v[228:229], v[226:227], 2, s[10:11]
	global_load_dword v248, v[228:229], off offset:512
	v_add_u32_e32 v226, s74, v158
	v_ashrrev_i32_e32 v227, 31, v226
	v_lshl_add_u64 v[228:229], v[226:227], 2, s[10:11]
	s_mov_b32 s98, 0x40000
	s_mov_b32 s99, 0
	v_lshl_add_u64 v[230:231], v[228:229], 0, s[98:99]
	global_load_dword v249, v[230:231], off offset:512
	v_add_u32_e32 v226, s74, v158
	v_ashrrev_i32_e32 v227, 31, v226
	v_lshl_add_u64 v[228:229], v[226:227], 2, s[10:11]
	s_mov_b32 s98, 0x80000
	s_mov_b32 s99, 0
	v_lshl_add_u64 v[230:231], v[228:229], 0, s[98:99]
	global_load_dword v250, v[230:231], off offset:512
	v_add_u32_e32 v226, s74, v158
	v_ashrrev_i32_e32 v227, 31, v226
	v_lshl_add_u64 v[228:229], v[226:227], 2, s[10:11]
	s_mov_b32 s98, 0xc0000
	s_mov_b32 s99, 0
	v_lshl_add_u64 v[230:231], v[228:229], 0, s[98:99]
	global_load_dword v251, v[230:231], off offset:512
	s_add_u32 s36, s36, 0x40080
	s_addc_u32 s37, s37, 0
	s_add_u32 s75, s38, 0x100
	v_mov_b32_e32 v0, 0
	s_addc_u32 s76, s39, 0
	s_mov_b32 s77, -2
	v_mov_b32_e32 v1, v0
	v_mov_b32_e32 v2, v0
	v_mov_b32_e32 v3, v0
	v_mov_b32_e32 v4, v0
	v_mov_b32_e32 v5, v0
	v_mov_b32_e32 v6, v0
	v_mov_b32_e32 v7, v0
	v_mov_b32_e32 v16, v0
	v_mov_b32_e32 v17, v0
	v_mov_b32_e32 v18, v0
	v_mov_b32_e32 v19, v0
	v_mov_b32_e32 v20, v0
	v_mov_b32_e32 v21, v0
	v_mov_b32_e32 v22, v0
	v_mov_b32_e32 v23, v0
	v_mov_b32_e32 v32, v0
	v_mov_b32_e32 v33, v0
	v_mov_b32_e32 v34, v0
	v_mov_b32_e32 v35, v0
	v_mov_b32_e32 v36, v0
	v_mov_b32_e32 v37, v0
	v_mov_b32_e32 v38, v0
	v_mov_b32_e32 v39, v0
	v_mov_b32_e32 v48, v0
	v_mov_b32_e32 v49, v0
	v_mov_b32_e32 v50, v0
	v_mov_b32_e32 v51, v0
	v_mov_b32_e32 v52, v0
	v_mov_b32_e32 v53, v0
	v_mov_b32_e32 v54, v0
	v_mov_b32_e32 v55, v0
	v_mov_b32_e32 v8, v0
	v_mov_b32_e32 v9, v0
	v_mov_b32_e32 v10, v0
	v_mov_b32_e32 v11, v0
	v_mov_b32_e32 v12, v0
	v_mov_b32_e32 v13, v0
	v_mov_b32_e32 v14, v0
	v_mov_b32_e32 v15, v0
	v_mov_b32_e32 v24, v0
	v_mov_b32_e32 v25, v0
	v_mov_b32_e32 v26, v0
	v_mov_b32_e32 v27, v0
	v_mov_b32_e32 v28, v0
	v_mov_b32_e32 v29, v0
	v_mov_b32_e32 v30, v0
	v_mov_b32_e32 v31, v0
	v_mov_b32_e32 v40, v0
	v_mov_b32_e32 v41, v0
	v_mov_b32_e32 v42, v0
	v_mov_b32_e32 v43, v0
	v_mov_b32_e32 v44, v0
	v_mov_b32_e32 v45, v0
	v_mov_b32_e32 v46, v0
	v_mov_b32_e32 v47, v0
	v_mov_b32_e32 v56, v0
	v_mov_b32_e32 v57, v0
	v_mov_b32_e32 v58, v0
	v_mov_b32_e32 v59, v0
	v_mov_b32_e32 v60, v0
	v_mov_b32_e32 v61, v0
	v_mov_b32_e32 v62, v0
	v_mov_b32_e32 v63, v0
	v_mov_b32_e32 v64, v0
	v_mov_b32_e32 v65, v0
	v_mov_b32_e32 v66, v0
	v_mov_b32_e32 v67, v0
	v_mov_b32_e32 v68, v0
	v_mov_b32_e32 v69, v0
	v_mov_b32_e32 v70, v0
	v_mov_b32_e32 v71, v0
	v_mov_b32_e32 v80, v0
	v_mov_b32_e32 v81, v0
	v_mov_b32_e32 v82, v0
	v_mov_b32_e32 v83, v0
	v_mov_b32_e32 v84, v0
	v_mov_b32_e32 v85, v0
	v_mov_b32_e32 v86, v0
	v_mov_b32_e32 v87, v0
	v_mov_b32_e32 v96, v0
	v_mov_b32_e32 v97, v0
	v_mov_b32_e32 v98, v0
	v_mov_b32_e32 v99, v0
	v_mov_b32_e32 v100, v0
	v_mov_b32_e32 v101, v0
	v_mov_b32_e32 v102, v0
	v_mov_b32_e32 v103, v0
	v_mov_b32_e32 v112, v0
	v_mov_b32_e32 v113, v0
	v_mov_b32_e32 v114, v0
	v_mov_b32_e32 v115, v0
	v_mov_b32_e32 v116, v0
	v_mov_b32_e32 v117, v0
	v_mov_b32_e32 v118, v0
	v_mov_b32_e32 v119, v0
	v_mov_b32_e32 v72, v0
	v_mov_b32_e32 v73, v0
	v_mov_b32_e32 v74, v0
	v_mov_b32_e32 v75, v0
	v_mov_b32_e32 v76, v0
	v_mov_b32_e32 v77, v0
	v_mov_b32_e32 v78, v0
	v_mov_b32_e32 v79, v0
	v_mov_b32_e32 v88, v0
	v_mov_b32_e32 v89, v0
	v_mov_b32_e32 v90, v0
	v_mov_b32_e32 v91, v0
	v_mov_b32_e32 v92, v0
	v_mov_b32_e32 v93, v0
	v_mov_b32_e32 v94, v0
	v_mov_b32_e32 v95, v0
	v_mov_b32_e32 v104, v0
	v_mov_b32_e32 v105, v0
	v_mov_b32_e32 v106, v0
	v_mov_b32_e32 v107, v0
	v_mov_b32_e32 v108, v0
	v_mov_b32_e32 v109, v0
	v_mov_b32_e32 v110, v0
	v_mov_b32_e32 v111, v0
	v_mov_b32_e32 v120, v0
	v_mov_b32_e32 v121, v0
	v_mov_b32_e32 v122, v0
	v_mov_b32_e32 v123, v0
	v_mov_b32_e32 v124, v0
	v_mov_b32_e32 v125, v0
	v_mov_b32_e32 v126, v0
	v_mov_b32_e32 v127, v0
.LBB0_926:
	s_add_u32 s38, s36, 0xfffc0080
	s_addc_u32 s39, s37, -1
	s_add_i32 s78, 0, 0x10000
	v_add_u32_e32 v146, s78, v159
	ds_read_b128 v[138:141], v146
	ds_read_b128 v[142:145], v146 offset:1024
	ds_read_b128 v[154:157], v146 offset:2048
	ds_read_b128 v[162:165], v146 offset:3072
	s_cmp_eq_u32 s77, 12
	s_cselect_b32 s41, s9, s39
	s_cselect_b32 s40, s8, s38
	s_cselect_b32 s39, s35, s76
	s_cselect_b32 s38, s34, s75
	v_lshl_add_u64 v[146:147], s[36:37], 0, v[134:135]
	s_add_i32 m0, s64, 0xc000
	ds_read_b128 v[166:169], v161
	ds_read_b128 v[170:173], v161 offset:1024
	ds_read_b128 v[178:181], v161 offset:2048
	ds_read_b128 v[182:185], v161 offset:3072
	ds_read_b128 v[186:189], v161 offset:4096
	ds_read_b128 v[190:193], v161 offset:5120
	ds_read_b128 v[200:203], v161 offset:6144
	ds_read_b128 v[204:207], v161 offset:7168
	global_load_lds_dwordx4 v[146:147], off
	v_lshl_add_u64 v[146:147], s[36:37], 0, v[136:137]
	s_add_i32 m0, s64, 0xe000
	s_nop 0
	global_load_lds_dwordx4 v[146:147], off
	s_waitcnt lgkmcnt(8)
	s_barrier
	s_waitcnt lgkmcnt(0)
	s_setprio 1
	s_waitcnt lgkmcnt(0)
	v_mfma_f32_16x16x32_bf16 v[124:127], v[138:141], v[166:169], v[124:127]
	v_mfma_f32_16x16x32_bf16 v[120:123], v[154:157], v[166:169], v[120:123]
	v_mfma_f32_16x16x32_bf16 v[108:111], v[138:141], v[178:181], v[108:111]
	v_mfma_f32_16x16x32_bf16 v[104:107], v[154:157], v[178:181], v[104:107]
	v_mfma_f32_16x16x32_bf16 v[92:95], v[138:141], v[186:189], v[92:95]
	v_mfma_f32_16x16x32_bf16 v[88:91], v[154:157], v[186:189], v[88:91]
	v_mfma_f32_16x16x32_bf16 v[76:79], v[138:141], v[200:203], v[76:79]
	v_mfma_f32_16x16x32_bf16 v[72:75], v[154:157], v[200:203], v[72:75]
	v_mfma_f32_16x16x32_bf16 v[124:127], v[142:145], v[170:173], v[124:127]
	v_mfma_f32_16x16x32_bf16 v[120:123], v[162:165], v[170:173], v[120:123]
	v_mfma_f32_16x16x32_bf16 v[108:111], v[142:145], v[182:185], v[108:111]
	v_mfma_f32_16x16x32_bf16 v[104:107], v[162:165], v[182:185], v[104:107]
	v_mfma_f32_16x16x32_bf16 v[92:95], v[142:145], v[190:193], v[92:95]
	v_mfma_f32_16x16x32_bf16 v[88:91], v[162:165], v[190:193], v[88:91]
	v_mfma_f32_16x16x32_bf16 v[76:79], v[142:145], v[204:207], v[76:79]
	v_mfma_f32_16x16x32_bf16 v[72:75], v[162:165], v[204:207], v[72:75]
	s_setprio 0
	s_barrier
	s_add_i32 s80, 0, 0x14000
	v_add_u32_e32 v146, s80, v159
	s_add_i32 s78, s78, s45
	ds_read_b128 v[208:211], v146
	ds_read_b128 v[212:215], v146 offset:1024
	ds_read_b128 v[216:219], v146 offset:2048
	ds_read_b128 v[220:223], v146 offset:3072
	v_lshl_add_u64 v[146:147], s[38:39], 0, v[148:149]
	s_mov_b32 m0, s78
	v_lshl_add_u64 v[174:175], s[38:39], 0, v[128:129]
	global_load_lds_dwordx4 v[146:147], off
	s_add_i32 m0, s78, 0x2000
	s_nop 0
	global_load_lds_dwordx4 v[174:175], off
	s_barrier
	s_waitcnt lgkmcnt(0)
	s_setprio 1
	s_waitcnt lgkmcnt(0)
	v_mfma_f32_16x16x32_bf16 v[116:119], v[208:211], v[166:169], v[116:119]
	v_mfma_f32_16x16x32_bf16 v[112:115], v[216:219], v[166:169], v[112:115]
	v_mfma_f32_16x16x32_bf16 v[100:103], v[208:211], v[178:181], v[100:103]
	v_mfma_f32_16x16x32_bf16 v[96:99], v[216:219], v[178:181], v[96:99]
	v_mfma_f32_16x16x32_bf16 v[84:87], v[208:211], v[186:189], v[84:87]
	v_mfma_f32_16x16x32_bf16 v[80:83], v[216:219], v[186:189], v[80:83]
	v_mfma_f32_16x16x32_bf16 v[68:71], v[208:211], v[200:203], v[68:71]
	v_mfma_f32_16x16x32_bf16 v[64:67], v[216:219], v[200:203], v[64:67]
	v_mfma_f32_16x16x32_bf16 v[116:119], v[212:215], v[170:173], v[116:119]
	v_mfma_f32_16x16x32_bf16 v[112:115], v[220:223], v[170:173], v[112:115]
	v_mfma_f32_16x16x32_bf16 v[100:103], v[212:215], v[182:185], v[100:103]
	v_mfma_f32_16x16x32_bf16 v[96:99], v[220:223], v[182:185], v[96:99]
	v_mfma_f32_16x16x32_bf16 v[84:87], v[212:215], v[190:193], v[84:87]
	v_mfma_f32_16x16x32_bf16 v[80:83], v[220:223], v[190:193], v[80:83]
	v_mfma_f32_16x16x32_bf16 v[68:71], v[212:215], v[204:207], v[68:71]
	v_mfma_f32_16x16x32_bf16 v[64:67], v[220:223], v[204:207], v[64:67]
	s_setprio 0
	s_mov_b32 m0, s64
	v_lshl_add_u64 v[194:195], s[40:41], 0, v[132:133]
	s_barrier
	ds_read_b128 v[166:169], v161 offset:16384
	ds_read_b128 v[170:173], v161 offset:17408
	ds_read_b128 v[178:181], v161 offset:18432
	ds_read_b128 v[182:185], v161 offset:19456
	ds_read_b128 v[186:189], v161 offset:20480
	ds_read_b128 v[190:193], v161 offset:21504
	ds_read_b128 v[200:203], v161 offset:22528
	ds_read_b128 v[204:207], v161 offset:23552
	global_load_lds_dwordx4 v[194:195], off
	v_lshl_add_u64 v[224:225], s[40:41], 0, v[130:131]
	s_mov_b32 m0, s65
	s_nop 0
	global_load_lds_dwordx4 v[224:225], off
	s_barrier
	s_waitcnt lgkmcnt(0)
	s_setprio 1
	s_waitcnt lgkmcnt(0)
	v_mfma_f32_16x16x32_bf16 v[60:63], v[138:141], v[166:169], v[60:63]
	v_mfma_f32_16x16x32_bf16 v[56:59], v[154:157], v[166:169], v[56:59]
	v_mfma_f32_16x16x32_bf16 v[44:47], v[138:141], v[178:181], v[44:47]
	v_mfma_f32_16x16x32_bf16 v[40:43], v[154:157], v[178:181], v[40:43]
	v_mfma_f32_16x16x32_bf16 v[28:31], v[138:141], v[186:189], v[28:31]
	v_mfma_f32_16x16x32_bf16 v[24:27], v[154:157], v[186:189], v[24:27]
	v_mfma_f32_16x16x32_bf16 v[12:15], v[138:141], v[200:203], v[12:15]
	v_mfma_f32_16x16x32_bf16 v[8:11], v[154:157], v[200:203], v[8:11]
	v_mfma_f32_16x16x32_bf16 v[60:63], v[142:145], v[170:173], v[60:63]
	v_mfma_f32_16x16x32_bf16 v[56:59], v[162:165], v[170:173], v[56:59]
	v_mfma_f32_16x16x32_bf16 v[44:47], v[142:145], v[182:185], v[44:47]
	v_mfma_f32_16x16x32_bf16 v[40:43], v[162:165], v[182:185], v[40:43]
	v_mfma_f32_16x16x32_bf16 v[28:31], v[142:145], v[190:193], v[28:31]
	v_mfma_f32_16x16x32_bf16 v[24:27], v[162:165], v[190:193], v[24:27]
	v_mfma_f32_16x16x32_bf16 v[12:15], v[142:145], v[204:207], v[12:15]
	v_mfma_f32_16x16x32_bf16 v[8:11], v[162:165], v[204:207], v[8:11]
	s_setprio 0
	s_barrier
	s_add_u32 s78, s38, 0x40000
	s_addc_u32 s79, s39, 0
	s_add_i32 s80, s80, s45
	v_lshl_add_u64 v[138:139], s[78:79], 0, v[148:149]
	s_mov_b32 m0, s80
	s_nop 0
	global_load_lds_dwordx4 v[138:139], off
	v_lshl_add_u64 v[138:139], s[78:79], 0, v[128:129]
	s_add_i32 m0, s80, 0x2000
	s_nop 0
	global_load_lds_dwordx4 v[138:139], off
	s_waitcnt vmcnt(6)
	s_barrier
	s_setprio 1
	v_mfma_f32_16x16x32_bf16 v[52:55], v[208:211], v[166:169], v[52:55]
	v_mfma_f32_16x16x32_bf16 v[48:51], v[216:219], v[166:169], v[48:51]
	v_mfma_f32_16x16x32_bf16 v[36:39], v[208:211], v[178:181], v[36:39]
	v_mfma_f32_16x16x32_bf16 v[32:35], v[216:219], v[178:181], v[32:35]
	v_mfma_f32_16x16x32_bf16 v[20:23], v[208:211], v[186:189], v[20:23]
	v_mfma_f32_16x16x32_bf16 v[16:19], v[216:219], v[186:189], v[16:19]
	v_mfma_f32_16x16x32_bf16 v[4:7], v[208:211], v[200:203], v[4:7]
	v_mfma_f32_16x16x32_bf16 v[0:3], v[216:219], v[200:203], v[0:3]
	v_mfma_f32_16x16x32_bf16 v[52:55], v[212:215], v[170:173], v[52:55]
	v_mfma_f32_16x16x32_bf16 v[48:51], v[220:223], v[170:173], v[48:51]
	v_mfma_f32_16x16x32_bf16 v[36:39], v[212:215], v[182:185], v[36:39]
	v_mfma_f32_16x16x32_bf16 v[32:35], v[220:223], v[182:185], v[32:35]
	v_mfma_f32_16x16x32_bf16 v[20:23], v[212:215], v[190:193], v[20:23]
	v_mfma_f32_16x16x32_bf16 v[16:19], v[220:223], v[190:193], v[16:19]
	v_mfma_f32_16x16x32_bf16 v[4:7], v[212:215], v[204:207], v[4:7]
	v_mfma_f32_16x16x32_bf16 v[0:3], v[220:223], v[204:207], v[0:3]
	s_setprio 0
	s_add_i32 s78, 0, 0x18000
	v_add_u32_e32 v162, s78, v159
	s_barrier
	ds_read_b128 v[138:141], v162
	ds_read_b128 v[142:145], v162 offset:1024
	ds_read_b128 v[154:157], v162 offset:2048
	ds_read_b128 v[162:165], v162 offset:3072
	s_add_u32 s40, s40, 0x40000
	s_addc_u32 s41, s41, 0
	s_mov_b32 m0, s66
	v_lshl_add_u64 v[208:209], s[40:41], 0, v[132:133]
	ds_read_b128 v[166:169], v161 offset:32768
	ds_read_b128 v[170:173], v161 offset:33792
	ds_read_b128 v[178:181], v161 offset:34816
	ds_read_b128 v[182:185], v161 offset:35840
	ds_read_b128 v[186:189], v161 offset:36864
	ds_read_b128 v[190:193], v161 offset:37888
	ds_read_b128 v[200:203], v161 offset:38912
	ds_read_b128 v[204:207], v161 offset:39936
	global_load_lds_dwordx4 v[208:209], off
	v_lshl_add_u64 v[208:209], s[40:41], 0, v[130:131]
	s_mov_b32 m0, s67
	s_nop 0
	global_load_lds_dwordx4 v[208:209], off
	s_waitcnt lgkmcnt(8)
	s_barrier
	s_waitcnt lgkmcnt(0)
	s_setprio 1
	s_waitcnt lgkmcnt(0)
	v_mfma_f32_16x16x32_bf16 v[124:127], v[138:141], v[166:169], v[124:127]
	v_mfma_f32_16x16x32_bf16 v[120:123], v[154:157], v[166:169], v[120:123]
	v_mfma_f32_16x16x32_bf16 v[108:111], v[138:141], v[178:181], v[108:111]
	v_mfma_f32_16x16x32_bf16 v[104:107], v[154:157], v[178:181], v[104:107]
	v_mfma_f32_16x16x32_bf16 v[92:95], v[138:141], v[186:189], v[92:95]
	v_mfma_f32_16x16x32_bf16 v[88:91], v[154:157], v[186:189], v[88:91]
	v_mfma_f32_16x16x32_bf16 v[76:79], v[138:141], v[200:203], v[76:79]
	v_mfma_f32_16x16x32_bf16 v[72:75], v[154:157], v[200:203], v[72:75]
	v_mfma_f32_16x16x32_bf16 v[124:127], v[142:145], v[170:173], v[124:127]
	v_mfma_f32_16x16x32_bf16 v[120:123], v[162:165], v[170:173], v[120:123]
	v_mfma_f32_16x16x32_bf16 v[108:111], v[142:145], v[182:185], v[108:111]
	v_mfma_f32_16x16x32_bf16 v[104:107], v[162:165], v[182:185], v[104:107]
	v_mfma_f32_16x16x32_bf16 v[92:95], v[142:145], v[190:193], v[92:95]
	v_mfma_f32_16x16x32_bf16 v[88:91], v[162:165], v[190:193], v[88:91]
	v_mfma_f32_16x16x32_bf16 v[76:79], v[142:145], v[204:207], v[76:79]
	v_mfma_f32_16x16x32_bf16 v[72:75], v[162:165], v[204:207], v[72:75]
	s_setprio 0
	s_barrier
	s_add_i32 s40, 0, 0x1c000
	s_add_i32 s41, s78, s45
	v_add_u32_e32 v199, s40, v159
	v_lshl_add_u64 v[146:147], v[146:147], 0, s[26:27]
	s_mov_b32 m0, s41
	ds_read_b128 v[208:211], v199
	ds_read_b128 v[212:215], v199 offset:1024
	ds_read_b128 v[216:219], v199 offset:2048
	ds_read_b128 v[220:223], v199 offset:3072
	global_load_lds_dwordx4 v[146:147], off
	v_lshl_add_u64 v[146:147], v[174:175], 0, s[26:27]
	s_add_i32 m0, s41, 0x2000
	s_nop 0
	global_load_lds_dwordx4 v[146:147], off
	s_barrier
	s_waitcnt lgkmcnt(0)
	s_setprio 1
	s_waitcnt lgkmcnt(0)
	v_mfma_f32_16x16x32_bf16 v[116:119], v[208:211], v[166:169], v[116:119]
	v_mfma_f32_16x16x32_bf16 v[112:115], v[216:219], v[166:169], v[112:115]
	v_mfma_f32_16x16x32_bf16 v[100:103], v[208:211], v[178:181], v[100:103]
	v_mfma_f32_16x16x32_bf16 v[96:99], v[216:219], v[178:181], v[96:99]
	v_mfma_f32_16x16x32_bf16 v[84:87], v[208:211], v[186:189], v[84:87]
	v_mfma_f32_16x16x32_bf16 v[80:83], v[216:219], v[186:189], v[80:83]
	v_mfma_f32_16x16x32_bf16 v[68:71], v[208:211], v[200:203], v[68:71]
	v_mfma_f32_16x16x32_bf16 v[64:67], v[216:219], v[200:203], v[64:67]
	v_mfma_f32_16x16x32_bf16 v[116:119], v[212:215], v[170:173], v[116:119]
	v_mfma_f32_16x16x32_bf16 v[112:115], v[220:223], v[170:173], v[112:115]
	v_mfma_f32_16x16x32_bf16 v[100:103], v[212:215], v[182:185], v[100:103]
	v_mfma_f32_16x16x32_bf16 v[96:99], v[220:223], v[182:185], v[96:99]
	v_mfma_f32_16x16x32_bf16 v[84:87], v[212:215], v[190:193], v[84:87]
	v_mfma_f32_16x16x32_bf16 v[80:83], v[220:223], v[190:193], v[80:83]
	v_mfma_f32_16x16x32_bf16 v[68:71], v[212:215], v[204:207], v[68:71]
	v_mfma_f32_16x16x32_bf16 v[64:67], v[220:223], v[204:207], v[64:67]
	s_setprio 0
	s_mov_b32 m0, s68
	v_lshl_add_u64 v[146:147], v[194:195], 0, s[26:27]
	s_barrier
	ds_read_b128 v[166:169], v161 offset:49152
	ds_read_b128 v[170:173], v161 offset:50176
	ds_read_b128 v[178:181], v161 offset:51200
	ds_read_b128 v[182:185], v161 offset:52224
	ds_read_b128 v[186:189], v161 offset:53248
	ds_read_b128 v[190:193], v161 offset:54272
	ds_read_b128 v[200:203], v161 offset:55296
	ds_read_b128 v[204:207], v161 offset:56320
	global_load_lds_dwordx4 v[146:147], off
	v_lshl_add_u64 v[146:147], v[224:225], 0, s[26:27]
	s_mov_b32 m0, s69
	s_nop 0
	global_load_lds_dwordx4 v[146:147], off
	s_barrier
	s_waitcnt lgkmcnt(0)
	s_setprio 1
	s_waitcnt lgkmcnt(0)
	v_mfma_f32_16x16x32_bf16 v[60:63], v[138:141], v[166:169], v[60:63]
	v_mfma_f32_16x16x32_bf16 v[56:59], v[154:157], v[166:169], v[56:59]
	v_mfma_f32_16x16x32_bf16 v[44:47], v[138:141], v[178:181], v[44:47]
	v_mfma_f32_16x16x32_bf16 v[40:43], v[154:157], v[178:181], v[40:43]
	v_mfma_f32_16x16x32_bf16 v[28:31], v[138:141], v[186:189], v[28:31]
	v_mfma_f32_16x16x32_bf16 v[24:27], v[154:157], v[186:189], v[24:27]
	v_mfma_f32_16x16x32_bf16 v[12:15], v[138:141], v[200:203], v[12:15]
	v_mfma_f32_16x16x32_bf16 v[8:11], v[154:157], v[200:203], v[8:11]
	v_mfma_f32_16x16x32_bf16 v[60:63], v[142:145], v[170:173], v[60:63]
	v_mfma_f32_16x16x32_bf16 v[56:59], v[162:165], v[170:173], v[56:59]
	v_mfma_f32_16x16x32_bf16 v[44:47], v[142:145], v[182:185], v[44:47]
	v_mfma_f32_16x16x32_bf16 v[40:43], v[162:165], v[182:185], v[40:43]
	v_mfma_f32_16x16x32_bf16 v[28:31], v[142:145], v[190:193], v[28:31]
	v_mfma_f32_16x16x32_bf16 v[24:27], v[162:165], v[190:193], v[24:27]
	v_mfma_f32_16x16x32_bf16 v[12:15], v[142:145], v[204:207], v[12:15]
	v_mfma_f32_16x16x32_bf16 v[8:11], v[162:165], v[204:207], v[8:11]
	s_setprio 0
	s_barrier
	s_add_u32 s38, s38, 0x40080
	s_addc_u32 s39, s39, 0
	s_add_i32 s40, s40, s45
	v_lshl_add_u64 v[138:139], s[38:39], 0, v[148:149]
	s_mov_b32 m0, s40
	s_nop 0
	global_load_lds_dwordx4 v[138:139], off
	v_lshl_add_u64 v[138:139], s[38:39], 0, v[128:129]
	s_add_i32 m0, s40, 0x2000
	s_nop 0
	global_load_lds_dwordx4 v[138:139], off
	s_waitcnt vmcnt(6)
	s_barrier
	s_setprio 1
	v_mfma_f32_16x16x32_bf16 v[52:55], v[208:211], v[166:169], v[52:55]
	v_mfma_f32_16x16x32_bf16 v[48:51], v[216:219], v[166:169], v[48:51]
	v_mfma_f32_16x16x32_bf16 v[36:39], v[208:211], v[178:181], v[36:39]
	v_mfma_f32_16x16x32_bf16 v[32:35], v[216:219], v[178:181], v[32:35]
	v_mfma_f32_16x16x32_bf16 v[20:23], v[208:211], v[186:189], v[20:23]
	v_mfma_f32_16x16x32_bf16 v[16:19], v[216:219], v[186:189], v[16:19]
	v_mfma_f32_16x16x32_bf16 v[4:7], v[208:211], v[200:203], v[4:7]
	v_mfma_f32_16x16x32_bf16 v[0:3], v[216:219], v[200:203], v[0:3]
	v_mfma_f32_16x16x32_bf16 v[52:55], v[212:215], v[170:173], v[52:55]
	v_mfma_f32_16x16x32_bf16 v[48:51], v[220:223], v[170:173], v[48:51]
	v_mfma_f32_16x16x32_bf16 v[36:39], v[212:215], v[182:185], v[36:39]
	v_mfma_f32_16x16x32_bf16 v[32:35], v[220:223], v[182:185], v[32:35]
	v_mfma_f32_16x16x32_bf16 v[20:23], v[212:215], v[190:193], v[20:23]
	v_mfma_f32_16x16x32_bf16 v[16:19], v[220:223], v[190:193], v[16:19]
	v_mfma_f32_16x16x32_bf16 v[4:7], v[212:215], v[204:207], v[4:7]
	v_mfma_f32_16x16x32_bf16 v[0:3], v[220:223], v[204:207], v[0:3]
	s_setprio 0
	s_add_i32 s77, s77, 2
	s_add_u32 s36, s36, 0x100
	s_addc_u32 s37, s37, 0
	s_add_u32 s75, s75, 0x100
	s_addc_u32 s76, s76, 0
	s_cmp_gt_u32 s77, 13
	s_barrier
	s_cbranch_scc0 .LBB0_926
	v_add_u32_e32 v138, s74, v158
	v_ashrrev_i32_e32 v139, 31, v138
	v_lshl_add_u64 v[142:143], v[138:139], 2, s[10:11]
	v_add_co_u32_e32 v144, vcc, 0x40000, v142
	v_subrev_u32_e32 v138, s70, v138
	s_nop 0
	v_addc_co_u32_e32 v145, vcc, 0, v143, vcc
	v_add_co_u32_e32 v146, vcc, 0x80000, v142
	v_ashrrev_i32_e32 v139, 31, v138
	s_nop 0
	v_addc_co_u32_e32 v147, vcc, 0, v143, vcc
	v_add_co_u32_e32 v154, vcc, 0xc0000, v142
	v_add_u32_e32 v140, s33, v160
	s_nop 0
	v_addc_co_u32_e32 v155, vcc, 0, v143, vcc
	s_nop 1
	v_mov_b32_e32 v156, v232
	v_mov_b32_e32 v162, v233
	v_mov_b32_e32 v157, v234
	v_mov_b32_e32 v163, v235
	global_load_dword v165, v[142:143], off offset:576
	global_load_dword v166, v[144:145], off offset:576
	global_load_dword v167, v[146:147], off offset:576
	global_load_dword v168, v[154:155], off offset:576
	global_load_dword v169, v[142:143], off offset:640
	global_load_dword v170, v[144:145], off offset:640
	global_load_dword v171, v[146:147], off offset:640
	global_load_dword v172, v[154:155], off offset:640
	global_load_dword v173, v[142:143], off offset:704
	global_load_dword v174, v[144:145], off offset:704
	global_load_dword v175, v[146:147], off offset:704
	global_load_dword v178, v[154:155], off offset:704
	v_ashrrev_i32_e32 v141, 31, v140
	v_lshlrev_b64 v[140:141], 1, v[140:141]
	s_mov_b32 s33, s72
	s_mov_b32 s74, s73
	s_mov_b64 s[38:39], s[34:35]
	s_mov_b64 s[36:37], s[8:9]
	s_nop 0
	v_pk_add_f32 v[156:157], v[156:157], v[162:163]
	s_nop 0
	v_add_f32_e32 v156, v156, v157
	v_fmamk_f32 v156, v156, 0x3a800000, v176
	v_mul_f32_e32 v157, 0x4b800000, v156
	v_cmp_gt_f32_e32 vcc, s53, v156
	s_nop 1
	v_cndmask_b32_e32 v156, v156, v157, vcc
	v_rsq_f32_e32 v162, v156
	v_lshlrev_b64 v[156:157], 13, v[138:139]
	v_lshl_add_u64 v[156:157], s[92:93], 0, v[156:157]
	v_lshl_add_u64 v[156:157], v[156:157], 0, v[140:141]
	v_mul_f32_e32 v139, 0x45800000, v162
	v_cndmask_b32_e32 v162, v162, v139, vcc
	v_pk_mul_f32 v[126:127], v[126:127], v[162:163] op_sel_hi:[1,0]
	v_pk_mul_f32 v[124:125], v[124:125], v[162:163] op_sel_hi:[1,0]
	v_pk_mul_f32 v[122:123], v[122:123], v[162:163] op_sel_hi:[1,0]
	v_pk_mul_f32 v[120:121], v[120:121], v[162:163] op_sel_hi:[1,0]
	v_pk_mul_f32 v[118:119], v[118:119], v[162:163] op_sel_hi:[1,0]
	v_pk_mul_f32 v[116:117], v[116:117], v[162:163] op_sel_hi:[1,0]
	v_pk_mul_f32 v[114:115], v[114:115], v[162:163] op_sel_hi:[1,0]
	v_pk_mul_f32 v[112:113], v[112:113], v[162:163] op_sel_hi:[1,0]
	v_max_f32_e32 v124, 0, v124
	v_max_f32_e32 v120, 0, v120
	v_max_f32_e32 v125, 0, v125
	v_max_f32_e32 v121, 0, v121
	v_max_f32_e32 v126, 0, v126
	v_max_f32_e32 v122, 0, v122
	v_max_f32_e32 v127, 0, v127
	v_max_f32_e32 v123, 0, v123
	v_max_f32_e32 v116, 0, v116
	v_max_f32_e32 v112, 0, v112
	v_max_f32_e32 v117, 0, v117
	v_max_f32_e32 v113, 0, v113
	v_max_f32_e32 v118, 0, v118
	v_max_f32_e32 v114, 0, v114
	v_max_f32_e32 v119, 0, v119
	v_max_f32_e32 v115, 0, v115
	v_mul_f32_e32 v124, v124, v124
	v_mul_f32_e32 v120, v120, v120
	v_mul_f32_e32 v125, v125, v125
	v_mul_f32_e32 v121, v121, v121
	v_mul_f32_e32 v126, v126, v126
	v_mul_f32_e32 v122, v122, v122
	v_mul_f32_e32 v127, v127, v127
	v_mul_f32_e32 v123, v123, v123
	v_mul_f32_e32 v116, v116, v116
	v_mul_f32_e32 v139, v112, v112
	v_mul_f32_e32 v117, v117, v117
	v_mul_f32_e32 v162, v113, v113
	v_mul_f32_e32 v118, v118, v118
	v_mul_f32_e32 v163, v114, v114
	v_mul_f32_e32 v119, v119, v119
	v_mul_f32_e32 v164, v115, v115
	v_cvt_pk_bf16_f32 v112, v124, v125
	v_cvt_pk_bf16_f32 v113, v126, v127
	v_cvt_pk_bf16_f32 v114, v120, v121
	v_cvt_pk_bf16_f32 v115, v122, v123
	v_cvt_pk_bf16_f32 v116, v116, v117
	v_cvt_pk_bf16_f32 v117, v118, v119
	v_cvt_pk_bf16_f32 v118, v139, v162
	v_cvt_pk_bf16_f32 v119, v163, v164
	global_store_dwordx4 v[156:157], v[112:115], off
	global_store_dwordx4 v[156:157], v[116:119], off offset:256
	s_nop 1
	v_mov_b32_e32 v112, v236
	s_nop 0
	v_mov_b32_e32 v114, v237
	v_mov_b32_e32 v113, v238
	v_mov_b32_e32 v115, v239
	v_add_u32_e32 v116, 16, v138
	v_ashrrev_i32_e32 v117, 31, v116
	s_nop 0
	v_pk_add_f32 v[112:113], v[112:113], v[114:115]
	s_nop 0
	v_add_f32_e32 v112, v112, v113
	v_fmamk_f32 v112, v112, 0x3a800000, v176
	v_mul_f32_e32 v113, 0x4b800000, v112
	v_cmp_gt_f32_e32 vcc, s53, v112
	s_nop 1
	v_cndmask_b32_e32 v112, v112, v113, vcc
	v_rsq_f32_e32 v114, v112
	v_lshlrev_b64 v[112:113], 13, v[116:117]
	v_lshl_add_u64 v[112:113], s[92:93], 0, v[112:113]
	v_lshl_add_u64 v[112:113], v[112:113], 0, v[140:141]
	v_mul_f32_e32 v115, 0x45800000, v114
	v_cndmask_b32_e32 v114, v114, v115, vcc
	v_pk_mul_f32 v[110:111], v[110:111], v[114:115] op_sel_hi:[1,0]
	v_pk_mul_f32 v[108:109], v[108:109], v[114:115] op_sel_hi:[1,0]
	v_pk_mul_f32 v[106:107], v[106:107], v[114:115] op_sel_hi:[1,0]
	v_pk_mul_f32 v[104:105], v[104:105], v[114:115] op_sel_hi:[1,0]
	v_pk_mul_f32 v[102:103], v[102:103], v[114:115] op_sel_hi:[1,0]
	v_pk_mul_f32 v[100:101], v[100:101], v[114:115] op_sel_hi:[1,0]
	v_pk_mul_f32 v[98:99], v[98:99], v[114:115] op_sel_hi:[1,0]
	v_pk_mul_f32 v[96:97], v[96:97], v[114:115] op_sel_hi:[1,0]
	v_max_f32_e32 v108, 0, v108
	v_max_f32_e32 v104, 0, v104
	v_max_f32_e32 v109, 0, v109
	v_max_f32_e32 v105, 0, v105
	v_max_f32_e32 v110, 0, v110
	v_max_f32_e32 v106, 0, v106
	v_max_f32_e32 v111, 0, v111
	v_max_f32_e32 v107, 0, v107
	v_max_f32_e32 v100, 0, v100
	v_max_f32_e32 v96, 0, v96
	v_max_f32_e32 v101, 0, v101
	v_max_f32_e32 v97, 0, v97
	v_max_f32_e32 v102, 0, v102
	v_max_f32_e32 v98, 0, v98
	v_max_f32_e32 v103, 0, v103
	v_max_f32_e32 v99, 0, v99
	v_mul_f32_e32 v108, v108, v108
	v_mul_f32_e32 v104, v104, v104
	v_mul_f32_e32 v109, v109, v109
	v_mul_f32_e32 v105, v105, v105
	v_mul_f32_e32 v110, v110, v110
	v_mul_f32_e32 v106, v106, v106
	v_mul_f32_e32 v111, v111, v111
	v_mul_f32_e32 v107, v107, v107
	v_mul_f32_e32 v100, v100, v100
	v_mul_f32_e32 v114, v96, v96
	v_mul_f32_e32 v101, v101, v101
	v_mul_f32_e32 v115, v97, v97
	v_mul_f32_e32 v102, v102, v102
	v_mul_f32_e32 v116, v98, v98
	v_mul_f32_e32 v103, v103, v103
	v_mul_f32_e32 v117, v99, v99
	v_cvt_pk_bf16_f32 v96, v108, v109
	v_cvt_pk_bf16_f32 v97, v110, v111
	v_cvt_pk_bf16_f32 v98, v104, v105
	v_cvt_pk_bf16_f32 v99, v106, v107
	v_cvt_pk_bf16_f32 v100, v100, v101
	v_cvt_pk_bf16_f32 v101, v102, v103
	v_cvt_pk_bf16_f32 v102, v114, v115
	v_cvt_pk_bf16_f32 v103, v116, v117
	global_store_dwordx4 v[112:113], v[96:99], off
	global_store_dwordx4 v[112:113], v[100:103], off offset:256
	s_nop 1
	v_mov_b32_e32 v96, v240
	s_nop 0
	v_mov_b32_e32 v98, v241
	v_mov_b32_e32 v97, v242
	v_mov_b32_e32 v99, v243
	v_add_u32_e32 v100, 32, v138
	v_ashrrev_i32_e32 v101, 31, v100
	s_nop 0
	v_pk_add_f32 v[96:97], v[96:97], v[98:99]
	s_nop 0
	v_add_f32_e32 v96, v96, v97
	v_fmamk_f32 v96, v96, 0x3a800000, v176
	v_mul_f32_e32 v97, 0x4b800000, v96
	v_cmp_gt_f32_e32 vcc, s53, v96
	s_nop 1
	v_cndmask_b32_e32 v96, v96, v97, vcc
	v_rsq_f32_e32 v98, v96
	v_lshlrev_b64 v[96:97], 13, v[100:101]
	v_lshl_add_u64 v[96:97], s[92:93], 0, v[96:97]
	v_lshl_add_u64 v[96:97], v[96:97], 0, v[140:141]
	v_mul_f32_e32 v99, 0x45800000, v98
	v_cndmask_b32_e32 v98, v98, v99, vcc
	v_pk_mul_f32 v[94:95], v[94:95], v[98:99] op_sel_hi:[1,0]
	v_pk_mul_f32 v[92:93], v[92:93], v[98:99] op_sel_hi:[1,0]
	v_pk_mul_f32 v[90:91], v[90:91], v[98:99] op_sel_hi:[1,0]
	v_pk_mul_f32 v[88:89], v[88:89], v[98:99] op_sel_hi:[1,0]
	v_pk_mul_f32 v[86:87], v[86:87], v[98:99] op_sel_hi:[1,0]
	v_pk_mul_f32 v[84:85], v[84:85], v[98:99] op_sel_hi:[1,0]
	v_pk_mul_f32 v[82:83], v[82:83], v[98:99] op_sel_hi:[1,0]
	v_pk_mul_f32 v[80:81], v[80:81], v[98:99] op_sel_hi:[1,0]
	v_max_f32_e32 v92, 0, v92
	v_max_f32_e32 v88, 0, v88
	v_max_f32_e32 v93, 0, v93
	v_max_f32_e32 v89, 0, v89
	v_max_f32_e32 v94, 0, v94
	v_max_f32_e32 v90, 0, v90
	v_max_f32_e32 v95, 0, v95
	v_max_f32_e32 v91, 0, v91
	v_max_f32_e32 v84, 0, v84
	v_max_f32_e32 v80, 0, v80
	v_max_f32_e32 v85, 0, v85
	v_max_f32_e32 v81, 0, v81
	v_max_f32_e32 v86, 0, v86
	v_max_f32_e32 v82, 0, v82
	v_max_f32_e32 v87, 0, v87
	v_max_f32_e32 v83, 0, v83
	v_mul_f32_e32 v92, v92, v92
	v_mul_f32_e32 v88, v88, v88
	v_mul_f32_e32 v93, v93, v93
	v_mul_f32_e32 v89, v89, v89
	v_mul_f32_e32 v94, v94, v94
	v_mul_f32_e32 v90, v90, v90
	v_mul_f32_e32 v95, v95, v95
	v_mul_f32_e32 v91, v91, v91
	v_mul_f32_e32 v84, v84, v84
	v_mul_f32_e32 v98, v80, v80
	v_mul_f32_e32 v85, v85, v85
	v_mul_f32_e32 v99, v81, v81
	v_mul_f32_e32 v86, v86, v86
	v_mul_f32_e32 v100, v82, v82
	v_mul_f32_e32 v87, v87, v87
	v_mul_f32_e32 v101, v83, v83
	v_cvt_pk_bf16_f32 v80, v92, v93
	v_cvt_pk_bf16_f32 v81, v94, v95
	v_cvt_pk_bf16_f32 v82, v88, v89
	v_cvt_pk_bf16_f32 v83, v90, v91
	v_cvt_pk_bf16_f32 v84, v84, v85
	v_cvt_pk_bf16_f32 v85, v86, v87
	v_cvt_pk_bf16_f32 v86, v98, v99
	v_cvt_pk_bf16_f32 v87, v100, v101
	global_store_dwordx4 v[96:97], v[80:83], off
	global_store_dwordx4 v[96:97], v[84:87], off offset:256
	s_nop 1
	v_mov_b32_e32 v80, v244
	s_nop 0
	v_mov_b32_e32 v82, v245
	v_mov_b32_e32 v81, v246
	v_mov_b32_e32 v83, v247
	v_add_u32_e32 v84, 48, v138
	v_ashrrev_i32_e32 v85, 31, v84
	s_nop 0
	v_pk_add_f32 v[80:81], v[80:81], v[82:83]
	s_nop 0
	v_add_f32_e32 v80, v80, v81
	v_fmamk_f32 v80, v80, 0x3a800000, v176
	v_mul_f32_e32 v81, 0x4b800000, v80
	v_cmp_gt_f32_e32 vcc, s53, v80
	s_nop 1
	v_cndmask_b32_e32 v80, v80, v81, vcc
	v_rsq_f32_e32 v82, v80
	v_lshlrev_b64 v[80:81], 13, v[84:85]
	v_lshl_add_u64 v[80:81], s[92:93], 0, v[80:81]
	v_lshl_add_u64 v[80:81], v[80:81], 0, v[140:141]
	v_mul_f32_e32 v83, 0x45800000, v82
	v_cndmask_b32_e32 v82, v82, v83, vcc
	v_pk_mul_f32 v[78:79], v[78:79], v[82:83] op_sel_hi:[1,0]
	v_pk_mul_f32 v[76:77], v[76:77], v[82:83] op_sel_hi:[1,0]
	v_pk_mul_f32 v[74:75], v[74:75], v[82:83] op_sel_hi:[1,0]
	v_pk_mul_f32 v[72:73], v[72:73], v[82:83] op_sel_hi:[1,0]
	v_pk_mul_f32 v[70:71], v[70:71], v[82:83] op_sel_hi:[1,0]
	v_pk_mul_f32 v[68:69], v[68:69], v[82:83] op_sel_hi:[1,0]
	v_pk_mul_f32 v[66:67], v[66:67], v[82:83] op_sel_hi:[1,0]
	v_pk_mul_f32 v[64:65], v[64:65], v[82:83] op_sel_hi:[1,0]
	v_max_f32_e32 v76, 0, v76
	v_max_f32_e32 v72, 0, v72
	v_max_f32_e32 v77, 0, v77
	v_max_f32_e32 v73, 0, v73
	v_max_f32_e32 v78, 0, v78
	v_max_f32_e32 v74, 0, v74
	v_max_f32_e32 v79, 0, v79
	v_max_f32_e32 v75, 0, v75
	v_max_f32_e32 v68, 0, v68
	v_max_f32_e32 v64, 0, v64
	v_max_f32_e32 v69, 0, v69
	v_max_f32_e32 v65, 0, v65
	v_max_f32_e32 v70, 0, v70
	v_max_f32_e32 v66, 0, v66
	v_max_f32_e32 v71, 0, v71
	v_max_f32_e32 v67, 0, v67
	v_mul_f32_e32 v76, v76, v76
	v_mul_f32_e32 v72, v72, v72
	v_mul_f32_e32 v77, v77, v77
	v_mul_f32_e32 v73, v73, v73
	v_mul_f32_e32 v78, v78, v78
	v_mul_f32_e32 v74, v74, v74
	v_mul_f32_e32 v79, v79, v79
	v_mul_f32_e32 v75, v75, v75
	v_mul_f32_e32 v68, v68, v68
	v_mul_f32_e32 v82, v64, v64
	v_mul_f32_e32 v69, v69, v69
	v_mul_f32_e32 v83, v65, v65
	v_mul_f32_e32 v70, v70, v70
	v_mul_f32_e32 v84, v66, v66
	v_mul_f32_e32 v71, v71, v71
	v_mul_f32_e32 v85, v67, v67
	v_cvt_pk_bf16_f32 v64, v76, v77
	v_cvt_pk_bf16_f32 v65, v78, v79
	v_cvt_pk_bf16_f32 v66, v72, v73
	v_cvt_pk_bf16_f32 v67, v74, v75
	v_cvt_pk_bf16_f32 v68, v68, v69
	v_cvt_pk_bf16_f32 v69, v70, v71
	v_cvt_pk_bf16_f32 v70, v82, v83
	v_cvt_pk_bf16_f32 v71, v84, v85
	global_store_dwordx4 v[80:81], v[64:67], off
	global_store_dwordx4 v[80:81], v[68:71], off offset:256
	s_nop 1
	v_mov_b32_e32 v64, v248
	s_nop 0
	v_mov_b32_e32 v66, v249
	v_mov_b32_e32 v65, v250
	v_mov_b32_e32 v67, v251
	v_add_u32_e32 v68, 0x80, v138
	v_ashrrev_i32_e32 v69, 31, v68
	s_nop 0
	v_pk_add_f32 v[64:65], v[64:65], v[66:67]
	s_nop 0
	v_add_f32_e32 v64, v64, v65
	v_fmamk_f32 v64, v64, 0x3a800000, v176
	v_mul_f32_e32 v65, 0x4b800000, v64
	v_cmp_gt_f32_e32 vcc, s53, v64
	s_nop 1
	v_cndmask_b32_e32 v64, v64, v65, vcc
	v_rsq_f32_e32 v66, v64
	v_lshlrev_b64 v[64:65], 13, v[68:69]
	v_lshl_add_u64 v[64:65], s[92:93], 0, v[64:65]
	v_lshl_add_u64 v[64:65], v[64:65], 0, v[140:141]
	v_mul_f32_e32 v67, 0x45800000, v66
	v_cndmask_b32_e32 v66, v66, v67, vcc
	v_pk_mul_f32 v[62:63], v[62:63], v[66:67] op_sel_hi:[1,0]
	v_pk_mul_f32 v[60:61], v[60:61], v[66:67] op_sel_hi:[1,0]
	v_pk_mul_f32 v[58:59], v[58:59], v[66:67] op_sel_hi:[1,0]
	v_pk_mul_f32 v[56:57], v[56:57], v[66:67] op_sel_hi:[1,0]
	v_pk_mul_f32 v[54:55], v[54:55], v[66:67] op_sel_hi:[1,0]
	v_pk_mul_f32 v[52:53], v[52:53], v[66:67] op_sel_hi:[1,0]
	v_pk_mul_f32 v[50:51], v[50:51], v[66:67] op_sel_hi:[1,0]
	v_pk_mul_f32 v[48:49], v[48:49], v[66:67] op_sel_hi:[1,0]
	v_max_f32_e32 v60, 0, v60
	v_max_f32_e32 v56, 0, v56
	v_max_f32_e32 v61, 0, v61
	v_max_f32_e32 v57, 0, v57
	v_max_f32_e32 v62, 0, v62
	v_max_f32_e32 v58, 0, v58
	v_max_f32_e32 v63, 0, v63
	v_max_f32_e32 v59, 0, v59
	v_max_f32_e32 v52, 0, v52
	v_max_f32_e32 v48, 0, v48
	v_max_f32_e32 v53, 0, v53
	v_max_f32_e32 v49, 0, v49
	v_max_f32_e32 v54, 0, v54
	v_max_f32_e32 v50, 0, v50
	v_max_f32_e32 v55, 0, v55
	v_max_f32_e32 v51, 0, v51
	v_mul_f32_e32 v60, v60, v60
	v_mul_f32_e32 v56, v56, v56
	v_mul_f32_e32 v61, v61, v61
	v_mul_f32_e32 v57, v57, v57
	v_mul_f32_e32 v62, v62, v62
	v_mul_f32_e32 v58, v58, v58
	v_mul_f32_e32 v63, v63, v63
	v_mul_f32_e32 v59, v59, v59
	v_mul_f32_e32 v52, v52, v52
	v_mul_f32_e32 v66, v48, v48
	v_mul_f32_e32 v53, v53, v53
	v_mul_f32_e32 v67, v49, v49
	v_mul_f32_e32 v54, v54, v54
	v_mul_f32_e32 v68, v50, v50
	v_mul_f32_e32 v55, v55, v55
	v_mul_f32_e32 v69, v51, v51
	v_cvt_pk_bf16_f32 v48, v60, v61
	v_cvt_pk_bf16_f32 v49, v62, v63
	v_cvt_pk_bf16_f32 v50, v56, v57
	v_cvt_pk_bf16_f32 v51, v58, v59
	v_cvt_pk_bf16_f32 v52, v52, v53
	v_cvt_pk_bf16_f32 v53, v54, v55
	v_cvt_pk_bf16_f32 v54, v66, v67
	v_cvt_pk_bf16_f32 v55, v68, v69
	global_store_dwordx4 v[64:65], v[48:51], off
	global_store_dwordx4 v[64:65], v[52:55], off offset:256
	s_waitcnt vmcnt(10)
	s_nop 1
	v_mov_b32_e32 v48, v165
	s_nop 0
	v_mov_b32_e32 v50, v166
	v_mov_b32_e32 v49, v167
	v_mov_b32_e32 v51, v168
	v_add_u32_e32 v52, 0x90, v138
	v_ashrrev_i32_e32 v53, 31, v52
	s_nop 0
	v_pk_add_f32 v[48:49], v[48:49], v[50:51]
	s_nop 0
	v_add_f32_e32 v48, v48, v49
	v_fmamk_f32 v48, v48, 0x3a800000, v176
	v_mul_f32_e32 v49, 0x4b800000, v48
	v_cmp_gt_f32_e32 vcc, s53, v48
	s_nop 1
	v_cndmask_b32_e32 v48, v48, v49, vcc
	v_rsq_f32_e32 v50, v48
	v_lshlrev_b64 v[48:49], 13, v[52:53]
	v_lshl_add_u64 v[48:49], s[92:93], 0, v[48:49]
	v_lshl_add_u64 v[48:49], v[48:49], 0, v[140:141]
	v_mul_f32_e32 v51, 0x45800000, v50
	v_cndmask_b32_e32 v50, v50, v51, vcc
	v_pk_mul_f32 v[46:47], v[46:47], v[50:51] op_sel_hi:[1,0]
	v_pk_mul_f32 v[44:45], v[44:45], v[50:51] op_sel_hi:[1,0]
	v_pk_mul_f32 v[42:43], v[42:43], v[50:51] op_sel_hi:[1,0]
	v_pk_mul_f32 v[40:41], v[40:41], v[50:51] op_sel_hi:[1,0]
	v_pk_mul_f32 v[38:39], v[38:39], v[50:51] op_sel_hi:[1,0]
	v_pk_mul_f32 v[36:37], v[36:37], v[50:51] op_sel_hi:[1,0]
	v_pk_mul_f32 v[34:35], v[34:35], v[50:51] op_sel_hi:[1,0]
	v_pk_mul_f32 v[32:33], v[32:33], v[50:51] op_sel_hi:[1,0]
	v_max_f32_e32 v44, 0, v44
	v_max_f32_e32 v40, 0, v40
	v_max_f32_e32 v45, 0, v45
	v_max_f32_e32 v41, 0, v41
	v_max_f32_e32 v46, 0, v46
	v_max_f32_e32 v42, 0, v42
	v_max_f32_e32 v47, 0, v47
	v_max_f32_e32 v43, 0, v43
	v_max_f32_e32 v36, 0, v36
	v_max_f32_e32 v32, 0, v32
	v_max_f32_e32 v37, 0, v37
	v_max_f32_e32 v33, 0, v33
	v_max_f32_e32 v38, 0, v38
	v_max_f32_e32 v34, 0, v34
	v_max_f32_e32 v39, 0, v39
	v_max_f32_e32 v35, 0, v35
	v_mul_f32_e32 v44, v44, v44
	v_mul_f32_e32 v40, v40, v40
	v_mul_f32_e32 v45, v45, v45
	v_mul_f32_e32 v41, v41, v41
	v_mul_f32_e32 v46, v46, v46
	v_mul_f32_e32 v42, v42, v42
	v_mul_f32_e32 v47, v47, v47
	v_mul_f32_e32 v43, v43, v43
	v_mul_f32_e32 v36, v36, v36
	v_mul_f32_e32 v50, v32, v32
	v_mul_f32_e32 v37, v37, v37
	v_mul_f32_e32 v51, v33, v33
	v_mul_f32_e32 v38, v38, v38
	v_mul_f32_e32 v52, v34, v34
	v_mul_f32_e32 v39, v39, v39
	v_mul_f32_e32 v53, v35, v35
	v_cvt_pk_bf16_f32 v32, v44, v45
	v_cvt_pk_bf16_f32 v33, v46, v47
	v_cvt_pk_bf16_f32 v34, v40, v41
	v_cvt_pk_bf16_f32 v35, v42, v43
	v_cvt_pk_bf16_f32 v36, v36, v37
	v_cvt_pk_bf16_f32 v37, v38, v39
	v_cvt_pk_bf16_f32 v38, v50, v51
	v_cvt_pk_bf16_f32 v39, v52, v53
	global_store_dwordx4 v[48:49], v[32:35], off
	global_store_dwordx4 v[48:49], v[36:39], off offset:256
	s_nop 1
	v_mov_b32_e32 v32, v169
	s_nop 0
	v_mov_b32_e32 v34, v170
	v_mov_b32_e32 v33, v171
	v_mov_b32_e32 v35, v172
	v_add_u32_e32 v36, 0xa0, v138
	v_ashrrev_i32_e32 v37, 31, v36
	s_nop 0
	v_pk_add_f32 v[32:33], v[32:33], v[34:35]
	s_nop 0
	v_add_f32_e32 v32, v32, v33
	v_fmamk_f32 v32, v32, 0x3a800000, v176
	v_mul_f32_e32 v33, 0x4b800000, v32
	v_cmp_gt_f32_e32 vcc, s53, v32
	s_nop 1
	v_cndmask_b32_e32 v32, v32, v33, vcc
	v_rsq_f32_e32 v34, v32
	v_lshlrev_b64 v[32:33], 13, v[36:37]
	v_lshl_add_u64 v[32:33], s[92:93], 0, v[32:33]
	v_lshl_add_u64 v[32:33], v[32:33], 0, v[140:141]
	v_mul_f32_e32 v35, 0x45800000, v34
	v_cndmask_b32_e32 v34, v34, v35, vcc
	v_pk_mul_f32 v[30:31], v[30:31], v[34:35] op_sel_hi:[1,0]
	v_pk_mul_f32 v[28:29], v[28:29], v[34:35] op_sel_hi:[1,0]
	v_pk_mul_f32 v[26:27], v[26:27], v[34:35] op_sel_hi:[1,0]
	v_pk_mul_f32 v[24:25], v[24:25], v[34:35] op_sel_hi:[1,0]
	v_pk_mul_f32 v[22:23], v[22:23], v[34:35] op_sel_hi:[1,0]
	v_pk_mul_f32 v[20:21], v[20:21], v[34:35] op_sel_hi:[1,0]
	v_pk_mul_f32 v[18:19], v[18:19], v[34:35] op_sel_hi:[1,0]
	v_pk_mul_f32 v[16:17], v[16:17], v[34:35] op_sel_hi:[1,0]
	v_max_f32_e32 v28, 0, v28
	v_max_f32_e32 v24, 0, v24
	v_max_f32_e32 v29, 0, v29
	v_max_f32_e32 v25, 0, v25
	v_max_f32_e32 v30, 0, v30
	v_max_f32_e32 v26, 0, v26
	v_max_f32_e32 v31, 0, v31
	v_max_f32_e32 v27, 0, v27
	v_max_f32_e32 v20, 0, v20
	v_max_f32_e32 v16, 0, v16
	v_max_f32_e32 v21, 0, v21
	v_max_f32_e32 v17, 0, v17
	v_max_f32_e32 v22, 0, v22
	v_max_f32_e32 v18, 0, v18
	v_max_f32_e32 v23, 0, v23
	v_max_f32_e32 v19, 0, v19
	v_mul_f32_e32 v28, v28, v28
	v_mul_f32_e32 v24, v24, v24
	v_mul_f32_e32 v29, v29, v29
	v_mul_f32_e32 v25, v25, v25
	v_mul_f32_e32 v30, v30, v30
	v_mul_f32_e32 v26, v26, v26
	v_mul_f32_e32 v31, v31, v31
	v_mul_f32_e32 v27, v27, v27
	v_mul_f32_e32 v20, v20, v20
	v_mul_f32_e32 v34, v16, v16
	v_mul_f32_e32 v21, v21, v21
	v_mul_f32_e32 v35, v17, v17
	v_mul_f32_e32 v22, v22, v22
	v_mul_f32_e32 v36, v18, v18
	v_mul_f32_e32 v23, v23, v23
	v_mul_f32_e32 v37, v19, v19
	v_cvt_pk_bf16_f32 v16, v28, v29
	v_cvt_pk_bf16_f32 v17, v30, v31
	v_cvt_pk_bf16_f32 v18, v24, v25
	v_cvt_pk_bf16_f32 v19, v26, v27
	v_cvt_pk_bf16_f32 v20, v20, v21
	v_cvt_pk_bf16_f32 v21, v22, v23
	v_cvt_pk_bf16_f32 v22, v34, v35
	v_cvt_pk_bf16_f32 v23, v36, v37
	global_store_dwordx4 v[32:33], v[16:19], off
	global_store_dwordx4 v[32:33], v[20:23], off offset:256
	s_nop 1
	v_mov_b32_e32 v16, v173
	s_nop 0
	v_mov_b32_e32 v18, v174
	v_mov_b32_e32 v17, v175
	v_mov_b32_e32 v19, v178
	s_and_b64 vcc, exec, s[4:5]
	v_add_u32_e32 v20, 0xb0, v138
	v_ashrrev_i32_e32 v21, 31, v20
	s_nop 0
	v_pk_add_f32 v[16:17], v[16:17], v[18:19]
	s_nop 0
	v_add_f32_e32 v16, v16, v17
	v_fmamk_f32 v16, v16, 0x3a800000, v176
	v_mul_f32_e32 v17, 0x4b800000, v16
	v_cmp_gt_f32_e64 s[4:5], s53, v16
	s_nop 1
	v_cndmask_b32_e64 v16, v16, v17, s[4:5]
	v_rsq_f32_e32 v18, v16
	v_lshlrev_b64 v[16:17], 13, v[20:21]
	v_lshl_add_u64 v[16:17], s[92:93], 0, v[16:17]
	v_lshl_add_u64 v[16:17], v[16:17], 0, v[140:141]
	v_mul_f32_e32 v19, 0x45800000, v18
	v_cndmask_b32_e64 v18, v18, v19, s[4:5]
	v_pk_mul_f32 v[14:15], v[14:15], v[18:19] op_sel_hi:[1,0]
	v_pk_mul_f32 v[12:13], v[12:13], v[18:19] op_sel_hi:[1,0]
	v_pk_mul_f32 v[10:11], v[10:11], v[18:19] op_sel_hi:[1,0]
	v_pk_mul_f32 v[8:9], v[8:9], v[18:19] op_sel_hi:[1,0]
	v_pk_mul_f32 v[6:7], v[6:7], v[18:19] op_sel_hi:[1,0]
	v_pk_mul_f32 v[4:5], v[4:5], v[18:19] op_sel_hi:[1,0]
	v_pk_mul_f32 v[2:3], v[2:3], v[18:19] op_sel_hi:[1,0]
	v_pk_mul_f32 v[0:1], v[0:1], v[18:19] op_sel_hi:[1,0]
	v_max_f32_e32 v12, 0, v12
	v_max_f32_e32 v8, 0, v8
	v_max_f32_e32 v13, 0, v13
	v_max_f32_e32 v9, 0, v9
	v_max_f32_e32 v14, 0, v14
	v_max_f32_e32 v10, 0, v10
	v_max_f32_e32 v15, 0, v15
	v_max_f32_e32 v11, 0, v11
	v_max_f32_e32 v4, 0, v4
	v_max_f32_e32 v0, 0, v0
	v_max_f32_e32 v5, 0, v5
	v_max_f32_e32 v1, 0, v1
	v_max_f32_e32 v6, 0, v6
	v_max_f32_e32 v2, 0, v2
	v_max_f32_e32 v7, 0, v7
	v_max_f32_e32 v3, 0, v3
	v_mul_f32_e32 v12, v12, v12
	v_mul_f32_e32 v8, v8, v8
	v_mul_f32_e32 v13, v13, v13
	v_mul_f32_e32 v9, v9, v9
	v_mul_f32_e32 v14, v14, v14
	v_mul_f32_e32 v10, v10, v10
	v_mul_f32_e32 v15, v15, v15
	v_mul_f32_e32 v11, v11, v11
	v_mul_f32_e32 v4, v4, v4
	v_mul_f32_e32 v18, v0, v0
	v_mul_f32_e32 v5, v5, v5
	v_mul_f32_e32 v19, v1, v1
	v_mul_f32_e32 v6, v6, v6
	v_mul_f32_e32 v20, v2, v2
	v_mul_f32_e32 v7, v7, v7
	v_mul_f32_e32 v21, v3, v3
	v_cvt_pk_bf16_f32 v0, v12, v13
	v_cvt_pk_bf16_f32 v1, v14, v15
	v_cvt_pk_bf16_f32 v2, v8, v9
	v_cvt_pk_bf16_f32 v3, v10, v11
	v_cvt_pk_bf16_f32 v4, v4, v5
	v_cvt_pk_bf16_f32 v5, v6, v7
	v_cvt_pk_bf16_f32 v6, v18, v19
	v_cvt_pk_bf16_f32 v7, v20, v21
	global_store_dwordx4 v[16:17], v[0:3], off
	global_store_dwordx4 v[16:17], v[4:7], off offset:256
	s_cbranch_vccz .LBB0_919
	s_waitcnt vmcnt(0)
	s_cmpk_gt_u32 s43, 0xff
	s_cbranch_scc1 .LBB0_930
	s_barrier
